# GEMM K-loop DMA-issue window priority 3 (was 2)
# speedup vs baseline: 1.0227x; 1.0098x over previous
; template <int MI, bool SWAP, bool F8 = false>
; __device__ __forceinline__ void gemm_core(const bf16_t* __restrict__ A, int lda, const bf16_t* __restrict__ B, int ldb,
;                                           int K, char* smem, f32x4 (&acc)[MI][4]) {
;     ...
;   for (int kt = 0; kt < nk; ++kt) {
;     __syncthreads();
; #pragma unroll
;     for (int i = 0; i < MI; ++i) *(u32x4*)(smem + woff + i * 4096) = ra[i];
; #pragma unroll
;     for (int i = 0; i < 4; ++i) *(u32x4*)(smem + 32768 + woff + i * 4096) = rb[i];
;     __syncthreads();
;     if (kt + 1 < nk) {
; #pragma unroll
;       for (int i = 0; i < MI; ++i) ra[i] = *(const u32x4*)(ap + (size_t)(32 * i) * lda + (kt + 1) * 64);
; #pragma unroll
;       for (int i = 0; i < 4; ++i) rb[i] = *(const u32x4*)(bp + (size_t)(32 * i) * ldb + (kt + 1) * 64);
;     }
;     if (F8) {
;       const int c0 = (g ^ (li & 7)) << 4, c1 = ((4 + g) ^ (li & 7)) << 4;
;       i32x8 wf8[4];
; #pragma unroll
;       for (int j = 0; j < 4; ++j) {
;         const char* rp = smem + wrow + ((j & 1) * 16 + (j >> 1) * 64) * 128;
;         const u32x4 lo = *(const u32x4*)(rp + c0), hi = *(const u32x4*)(rp + c1);
;         wf8[j] = (i32x8){(int)lo.x, (int)lo.y, (int)lo.z, (int)lo.w, (int)hi.x, (int)hi.y, (int)hi.z, (int)hi.w};
;       }
; #pragma unroll
;       for (int i = 0; i < MI; ++i) {
;         const char* rp = smem + xrow + i * 2048;
;         const u32x4 lo = *(const u32x4*)(rp + c0), hi = *(const u32x4*)(rp + c1);
;         const i32x8 xf8 = {(int)lo.x, (int)lo.y, (int)lo.z, (int)lo.w, (int)hi.x, (int)hi.y, (int)hi.z, (int)hi.w};
; #pragma unroll
;         for (int j = 0; j < 4; ++j)
;           acc[i][j] = __builtin_amdgcn_mfma_scale_f32_16x16x128_f8f6f4(wf8[j], xf8, acc[i][j], 0, 0, 0, 0x77777777, 0, 0x7f7f7f7f);
;       }
;     } else {
; #pragma unroll
;     for (int kk = 0; kk < 2; ++kk) {
;       const int ch = ((kk * 4 + g) ^ (li & 7)) << 4;
;       bf16x8 xf[MI], wf[4];
; #pragma unroll
;       for (int j = 0; j < 4; ++j) wf[j] = *(const bf16x8*)(smem + wrow + ((j & 1) * 16 + (j >> 1) * 64) * 128 + ch);
; #pragma unroll
;       for (int i = 0; i < MI; ++i) xf[i] = *(const bf16x8*)(smem + xrow + i * 2048 + ch);
; #pragma unroll
;       for (int i = 0; i < MI; ++i)
; #pragma unroll
;         for (int j = 0; j < 4; ++j) {
.LBB0_120:
	s_barrier
	s_setprio 3
	s_mov_b32 m0, s62
	s_nop 0
	global_load_lds_dwordx4 v252, s[56:57]
	s_add_u32 m0, s62, 0x1000
	s_nop 0
	global_load_lds_dwordx4 v253, s[56:57]
	s_add_u32 s56, s56, 0x20000
	s_addc_u32 s57, s57, 0
	s_add_u32 m0, s62, 0x2000
	s_nop 0
	global_load_lds_dwordx4 v252, s[56:57]
	s_add_u32 m0, s62, 0x3000
	s_nop 0
	global_load_lds_dwordx4 v253, s[56:57]
	s_add_u32 s56, s56, 0x20000
	s_addc_u32 s57, s57, 0
	s_add_u32 m0, s62, 0x4000
	s_nop 0
	global_load_lds_dwordx4 v252, s[56:57]
	s_add_u32 m0, s62, 0x5000
	s_nop 0
	global_load_lds_dwordx4 v253, s[56:57]
	s_add_u32 s56, s56, 0x20000
	s_addc_u32 s57, s57, 0
	s_add_u32 m0, s62, 0x6000
	s_nop 0
	global_load_lds_dwordx4 v252, s[56:57]
	s_add_u32 m0, s62, 0x7000
	s_nop 0
	global_load_lds_dwordx4 v253, s[56:57]
	s_sub_u32 s56, s56, 0x60000
	s_subb_u32 s57, s57, 0
	s_add_u32 m0, s62, 0x8000
	s_nop 0
	global_load_lds_dwordx4 v252, s[58:59]
	s_add_u32 m0, s62, 0x9000
	s_nop 0
	global_load_lds_dwordx4 v253, s[58:59]
	s_add_u32 s58, s58, 0x20000
	s_addc_u32 s59, s59, 0
	s_add_u32 m0, s62, 0xa000
	s_nop 0
	global_load_lds_dwordx4 v252, s[58:59]
	s_add_u32 m0, s62, 0xb000
	s_nop 0
	global_load_lds_dwordx4 v253, s[58:59]
	s_sub_u32 s58, s58, 0x20000
	s_subb_u32 s59, s59, 0
	s_setprio 0
	v_add_u32_e32 v252, 0x80, v252
	v_add_u32_e32 v253, 0x80, v253
	s_waitcnt vmcnt(0)
	s_barrier
	ds_read_b128 v[148:151], v215 offset:32768
	ds_read_b128 v[152:155], v215 offset:34816
	ds_read_b128 v[156:159], v213
	ds_read_b128 v[160:163], v213 offset:2048
	ds_read_b128 v[164:167], v215 offset:40960
	ds_read_b128 v[168:171], v215 offset:43008
	s_waitcnt lgkmcnt(3)
	v_mfma_f32_16x16x32_bf16 v[140:143], v[148:151], v[156:159], v[140:143]
	v_mfma_f32_16x16x32_bf16 v[136:139], v[152:155], v[156:159], v[136:139]
	s_waitcnt lgkmcnt(1)
	v_mfma_f32_16x16x32_bf16 v[132:135], v[164:167], v[156:159], v[132:135]
	s_waitcnt lgkmcnt(0)
	v_mfma_f32_16x16x32_bf16 v[128:131], v[168:171], v[156:159], v[128:131]
	v_mfma_f32_16x16x32_bf16 v[124:127], v[148:151], v[160:163], v[124:127]
	v_mfma_f32_16x16x32_bf16 v[120:123], v[152:155], v[160:163], v[120:123]
	v_mfma_f32_16x16x32_bf16 v[116:119], v[164:167], v[160:163], v[116:119]
	v_mfma_f32_16x16x32_bf16 v[104:107], v[168:171], v[160:163], v[104:107]
	ds_read_b128 v[156:159], v213 offset:4096
	ds_read_b128 v[160:163], v213 offset:6144
	s_waitcnt lgkmcnt(1)
	v_mfma_f32_16x16x32_bf16 v[88:91], v[148:151], v[156:159], v[88:91]
	v_mfma_f32_16x16x32_bf16 v[84:87], v[152:155], v[156:159], v[84:87]
	v_mfma_f32_16x16x32_bf16 v[80:83], v[164:167], v[156:159], v[80:83]
	v_mfma_f32_16x16x32_bf16 v[76:79], v[168:171], v[156:159], v[76:79]
	s_waitcnt lgkmcnt(0)
	v_mfma_f32_16x16x32_bf16 v[72:75], v[148:151], v[160:163], v[72:75]
	v_mfma_f32_16x16x32_bf16 v[68:71], v[152:155], v[160:163], v[68:71]
	v_mfma_f32_16x16x32_bf16 v[64:67], v[164:167], v[160:163], v[64:67]
	v_mfma_f32_16x16x32_bf16 v[60:63], v[168:171], v[160:163], v[60:63]
	ds_read_b128 v[156:159], v213 offset:8192
	ds_read_b128 v[160:163], v213 offset:10240
	s_waitcnt lgkmcnt(1)
	v_mfma_f32_16x16x32_bf16 v[44:47], v[148:151], v[156:159], v[44:47]
	v_mfma_f32_16x16x32_bf16 v[40:43], v[152:155], v[156:159], v[40:43]
	v_mfma_f32_16x16x32_bf16 v[36:39], v[164:167], v[156:159], v[36:39]
	v_mfma_f32_16x16x32_bf16 v[32:35], v[168:171], v[156:159], v[32:35]
	s_waitcnt lgkmcnt(0)
	v_mfma_f32_16x16x32_bf16 v[28:31], v[148:151], v[160:163], v[28:31]
	v_mfma_f32_16x16x32_bf16 v[24:27], v[152:155], v[160:163], v[24:27]
	v_mfma_f32_16x16x32_bf16 v[20:23], v[164:167], v[160:163], v[20:23]
	v_mfma_f32_16x16x32_bf16 v[52:55], v[168:171], v[160:163], v[52:55]
	ds_read_b128 v[156:159], v213 offset:12288
	ds_read_b128 v[160:163], v213 offset:14336
	ds_read_b128 v[172:175], v206 offset:32768
	ds_read_b128 v[180:183], v206 offset:34816
	s_waitcnt lgkmcnt(3)
	v_mfma_f32_16x16x32_bf16 v[48:51], v[148:151], v[156:159], v[48:51]
	v_mfma_f32_16x16x32_bf16 v[56:59], v[152:155], v[156:159], v[56:59]
	s_waitcnt lgkmcnt(2)
	v_mfma_f32_16x16x32_bf16 v[100:103], v[148:151], v[160:163], v[100:103]
	v_mfma_f32_16x16x32_bf16 v[96:99], v[152:155], v[160:163], v[96:99]
	ds_read_b128 v[148:151], v0
	ds_read_b128 v[152:155], v0 offset:2048
	ds_read_b128 v[192:195], v206 offset:40960
	ds_read_b128 v[196:199], v206 offset:43008
	s_waitcnt lgkmcnt(3)
	v_mfma_f32_16x16x32_bf16 v[140:143], v[172:175], v[148:151], v[140:143]
	v_mfma_f32_16x16x32_bf16 v[136:139], v[180:183], v[148:151], v[136:139]
	s_waitcnt lgkmcnt(1)
	v_mfma_f32_16x16x32_bf16 v[132:135], v[192:195], v[148:151], v[132:135]
	s_waitcnt lgkmcnt(0)
	v_mfma_f32_16x16x32_bf16 v[128:131], v[196:199], v[148:151], v[128:131]
	v_mfma_f32_16x16x32_bf16 v[124:127], v[172:175], v[152:155], v[124:127]
	v_mfma_f32_16x16x32_bf16 v[120:123], v[180:183], v[152:155], v[120:123]
	v_mfma_f32_16x16x32_bf16 v[116:119], v[192:195], v[152:155], v[116:119]
	v_mfma_f32_16x16x32_bf16 v[104:107], v[196:199], v[152:155], v[104:107]
	ds_read_b128 v[148:151], v0 offset:4096
	ds_read_b128 v[152:155], v0 offset:6144
	v_mfma_f32_16x16x32_bf16 v[112:115], v[164:167], v[156:159], v[112:115]
	v_mfma_f32_16x16x32_bf16 v[92:95], v[164:167], v[160:163], v[92:95]
	v_mfma_f32_16x16x32_bf16 v[108:111], v[168:171], v[156:159], v[108:111]
	v_mfma_f32_16x16x32_bf16 v[144:147], v[168:171], v[160:163], v[144:147]
	s_waitcnt lgkmcnt(0)
; template <int MI, bool SWAP, bool F8 = false>
; __device__ __forceinline__ void gemm_core(const bf16_t* __restrict__ A, int lda, const bf16_t* __restrict__ B, int ldb,
;                                           int K, char* smem, f32x4 (&acc)[MI][4]) {
;     ...
;   for (int kt = 0; kt < nk; ++kt) {
;     __syncthreads();
; #pragma unroll
;     for (int i = 0; i < MI; ++i) *(u32x4*)(smem + woff + i * 4096) = ra[i];
; #pragma unroll
;     for (int i = 0; i < 4; ++i) *(u32x4*)(smem + 32768 + woff + i * 4096) = rb[i];
;     __syncthreads();
;     if (kt + 1 < nk) {
; #pragma unroll
;       for (int i = 0; i < MI; ++i) ra[i] = *(const u32x4*)(ap + (size_t)(32 * i) * lda + (kt + 1) * 64);
; #pragma unroll
;       for (int i = 0; i < 4; ++i) rb[i] = *(const u32x4*)(bp + (size_t)(32 * i) * ldb + (kt + 1) * 64);
;     }
;     if (F8) {
;       const int c0 = (g ^ (li & 7)) << 4, c1 = ((4 + g) ^ (li & 7)) << 4;
;       i32x8 wf8[4];
; #pragma unroll
;       for (int j = 0; j < 4; ++j) {
;         const char* rp = smem + wrow + ((j & 1) * 16 + (j >> 1) * 64) * 128;
;         const u32x4 lo = *(const u32x4*)(rp + c0), hi = *(const u32x4*)(rp + c1);
;         wf8[j] = (i32x8){(int)lo.x, (int)lo.y, (int)lo.z, (int)lo.w, (int)hi.x, (int)hi.y, (int)hi.z, (int)hi.w};
;       }
; #pragma unroll
;       for (int i = 0; i < MI; ++i) {
;         const char* rp = smem + xrow + i * 2048;
;         const u32x4 lo = *(const u32x4*)(rp + c0), hi = *(const u32x4*)(rp + c1);
;         const i32x8 xf8 = {(int)lo.x, (int)lo.y, (int)lo.z, (int)lo.w, (int)hi.x, (int)hi.y, (int)hi.z, (int)hi.w};
; #pragma unroll
;         for (int j = 0; j < 4; ++j)
;           acc[i][j] = __builtin_amdgcn_mfma_scale_f32_16x16x128_f8f6f4(wf8[j], xf8, acc[i][j], 0, 0, 0, 0x77777777, 0, 0x7f7f7f7f);
;       }
;     } else {
; #pragma unroll
;     for (int kk = 0; kk < 2; ++kk) {
;       const int ch = ((kk * 4 + g) ^ (li & 7)) << 4;
;       bf16x8 xf[MI], wf[4];
; #pragma unroll
;       for (int j = 0; j < 4; ++j) wf[j] = *(const bf16x8*)(smem + wrow + ((j & 1) * 16 + (j >> 1) * 64) * 128 + ch);
; #pragma unroll
;       for (int i = 0; i < MI; ++i) xf[i] = *(const bf16x8*)(smem + xrow + i * 2048 + ch);
; #pragma unroll
;       for (int i = 0; i < MI; ++i)
; #pragma unroll
;         for (int j = 0; j < 4; ++j) {
	v_mfma_f32_16x16x32_bf16 v[72:75], v[172:175], v[152:155], v[72:75]
	v_mfma_f32_16x16x32_bf16 v[68:71], v[180:183], v[152:155], v[68:71]
	v_mfma_f32_16x16x32_bf16 v[64:67], v[192:195], v[152:155], v[64:67]
	v_mfma_f32_16x16x32_bf16 v[60:63], v[196:199], v[152:155], v[60:63]
	v_mfma_f32_16x16x32_bf16 v[88:91], v[172:175], v[148:151], v[88:91]
	v_mfma_f32_16x16x32_bf16 v[84:87], v[180:183], v[148:151], v[84:87]
	v_mfma_f32_16x16x32_bf16 v[80:83], v[192:195], v[148:151], v[80:83]
	v_mfma_f32_16x16x32_bf16 v[76:79], v[196:199], v[148:151], v[76:79]
	ds_read_b128 v[148:151], v0 offset:8192
	ds_read_b128 v[156:159], v0 offset:10240
	ds_read_b128 v[160:163], v0 offset:12288
	ds_read_b128 v[200:203], v0 offset:14336
	s_waitcnt lgkmcnt(3)
	v_mfma_f32_16x16x32_bf16 v[44:47], v[172:175], v[148:151], v[44:47]
	v_mfma_f32_16x16x32_bf16 v[40:43], v[180:183], v[148:151], v[40:43]
	v_mfma_f32_16x16x32_bf16 v[36:39], v[192:195], v[148:151], v[36:39]
	v_mfma_f32_16x16x32_bf16 v[32:35], v[196:199], v[148:151], v[32:35]
	s_waitcnt lgkmcnt(2)
	v_mfma_f32_16x16x32_bf16 v[28:31], v[172:175], v[156:159], v[28:31]
	v_mfma_f32_16x16x32_bf16 v[24:27], v[180:183], v[156:159], v[24:27]
	v_mfma_f32_16x16x32_bf16 v[20:23], v[192:195], v[156:159], v[20:23]
	v_mfma_f32_16x16x32_bf16 v[52:55], v[196:199], v[156:159], v[52:55]
	s_waitcnt lgkmcnt(1)
	v_mfma_f32_16x16x32_bf16 v[48:51], v[172:175], v[160:163], v[48:51]
	v_mfma_f32_16x16x32_bf16 v[56:59], v[180:183], v[160:163], v[56:59]
	v_mfma_f32_16x16x32_bf16 v[112:115], v[192:195], v[160:163], v[112:115]
	v_mfma_f32_16x16x32_bf16 v[108:111], v[196:199], v[160:163], v[108:111]
	s_waitcnt lgkmcnt(0)
	v_mfma_f32_16x16x32_bf16 v[100:103], v[172:175], v[200:203], v[100:103]
	v_mfma_f32_16x16x32_bf16 v[96:99], v[180:183], v[200:203], v[96:99]
	v_mfma_f32_16x16x32_bf16 v[92:95], v[192:195], v[200:203], v[92:95]
	v_mfma_f32_16x16x32_bf16 v[144:147], v[196:199], v[200:203], v[144:147]
	s_add_u32 s22, s22, 0x80
	s_addc_u32 s23, s23, 0
	s_cmpk_lg_i32 s22, 0x780
	s_cbranch_scc1 .LBB0_120
	s_barrier
	s_setprio 3
	s_mov_b32 m0, s62
	s_nop 0
	global_load_lds_dwordx4 v252, s[56:57]
	s_add_u32 m0, s62, 0x1000
	s_nop 0
	global_load_lds_dwordx4 v253, s[56:57]
	s_add_u32 s56, s56, 0x20000
	s_addc_u32 s57, s57, 0
	s_add_u32 m0, s62, 0x2000
	s_nop 0
	global_load_lds_dwordx4 v252, s[56:57]
	s_add_u32 m0, s62, 0x3000
	s_nop 0
	global_load_lds_dwordx4 v253, s[56:57]
	s_add_u32 s56, s56, 0x20000
	s_addc_u32 s57, s57, 0
	s_add_u32 m0, s62, 0x4000
	s_nop 0
	global_load_lds_dwordx4 v252, s[56:57]
	s_add_u32 m0, s62, 0x5000
	s_nop 0
	global_load_lds_dwordx4 v253, s[56:57]
	s_add_u32 s56, s56, 0x20000
	s_addc_u32 s57, s57, 0
	s_add_u32 m0, s62, 0x6000
	s_nop 0
	global_load_lds_dwordx4 v252, s[56:57]
	s_add_u32 m0, s62, 0x7000
	s_nop 0
	global_load_lds_dwordx4 v253, s[56:57]
	s_sub_u32 s56, s56, 0x60000
	s_subb_u32 s57, s57, 0
	s_add_u32 m0, s62, 0x8000
	s_nop 0
	global_load_lds_dwordx4 v252, s[58:59]
	s_add_u32 m0, s62, 0x9000
	s_nop 0
	global_load_lds_dwordx4 v253, s[58:59]
	s_add_u32 s58, s58, 0x20000
	s_addc_u32 s59, s59, 0
	s_add_u32 m0, s62, 0xa000
	s_nop 0
	global_load_lds_dwordx4 v252, s[58:59]
	s_add_u32 m0, s62, 0xb000
	s_nop 0
	global_load_lds_dwordx4 v253, s[58:59]
	s_sub_u32 s58, s58, 0x20000
	s_subb_u32 s59, s59, 0
	s_setprio 0
	s_waitcnt vmcnt(0)
	s_barrier
	v_bfe_u32 v12, v208, 4, 1
	v_mul_u32_u24_e32 v12, 24, v12
	v_mov_b32_e32 v13, 0
	ds_read_b128 v[148:151], v215 offset:32768
	ds_read_b128 v[152:155], v215 offset:34816
	ds_read_b128 v[156:159], v215 offset:40960
	ds_read_b128 v[160:163], v215 offset:43008
	ds_read_b128 v[164:167], v213
	ds_read_b128 v[168:171], v213 offset:2048
	ds_read_b128 v[172:175], v213 offset:4096
	ds_read_b128 v[176:179], v213 offset:6144
	ds_read_b128 v[180:183], v213 offset:8192
	ds_read_b128 v[184:187], v213 offset:10240
	ds_read_b128 v[188:191], v213 offset:12288
	ds_read_b128 v[192:195], v213 offset:14336
	s_waitcnt lgkmcnt(7)
	v_mfma_f32_16x16x32_bf16 v[140:143], v[148:151], v[164:167], v[140:143]
	s_mul_hi_i32 s11, s10, 0x180000
	s_mul_i32 s10, s10, 0x180000
	s_add_u32 s22, s8, s10
	v_mfma_f32_16x16x32_bf16 v[136:139], v[152:155], v[164:167], v[136:139]
	s_addc_u32 s23, s9, s11
	s_lshl_b64 s[10:11], s[20:21], 1
	s_add_u32 s10, s22, s10
	v_mfma_f32_16x16x32_bf16 v[132:135], v[156:159], v[164:167], v[132:135]
	s_addc_u32 s11, s23, s11
	s_movk_i32 s20, 0x1800
	s_add_i32 s28, s28, s78
	v_mfma_f32_16x16x32_bf16 v[128:131], v[160:163], v[164:167], v[128:131]
	s_add_i32 s27, s27, s71
	s_cmpk_gt_i32 s28, 0x5ff
	s_waitcnt lgkmcnt(6)
	v_mfma_f32_16x16x32_bf16 v[124:127], v[148:151], v[168:171], v[124:127]
	v_mfma_f32_16x16x32_bf16 v[120:123], v[152:155], v[168:171], v[120:123]
	v_mfma_f32_16x16x32_bf16 v[116:119], v[156:159], v[168:171], v[116:119]
	v_mfma_f32_16x16x32_bf16 v[104:107], v[160:163], v[168:171], v[104:107]
	s_waitcnt lgkmcnt(5)
	v_mfma_f32_16x16x32_bf16 v[88:91], v[148:151], v[172:175], v[88:91]
	v_mfma_f32_16x16x32_bf16 v[84:87], v[152:155], v[172:175], v[84:87]
	v_mfma_f32_16x16x32_bf16 v[80:83], v[156:159], v[172:175], v[80:83]
	v_mfma_f32_16x16x32_bf16 v[76:79], v[160:163], v[172:175], v[76:79]
	s_waitcnt lgkmcnt(4)
	v_mfma_f32_16x16x32_bf16 v[72:75], v[148:151], v[176:179], v[72:75]
	v_mfma_f32_16x16x32_bf16 v[68:71], v[152:155], v[176:179], v[68:71]
	v_mfma_f32_16x16x32_bf16 v[64:67], v[156:159], v[176:179], v[64:67]
	v_mfma_f32_16x16x32_bf16 v[60:63], v[160:163], v[176:179], v[60:63]
	s_waitcnt lgkmcnt(3)
	v_mfma_f32_16x16x32_bf16 v[44:47], v[148:151], v[180:183], v[44:47]
	v_mfma_f32_16x16x32_bf16 v[40:43], v[152:155], v[180:183], v[40:43]
	v_mfma_f32_16x16x32_bf16 v[36:39], v[156:159], v[180:183], v[36:39]
	v_mfma_f32_16x16x32_bf16 v[32:35], v[160:163], v[180:183], v[32:35]
	s_waitcnt lgkmcnt(2)
; template <int MI, bool SWAP, bool F8 = false>
; __device__ __forceinline__ void gemm_core(const bf16_t* __restrict__ A, int lda, const bf16_t* __restrict__ B, int ldb,
;                                           int K, char* smem, f32x4 (&acc)[MI][4]) {
;     ...
;     for (int kk = 0; kk < 2; ++kk) {
;       const int ch = ((kk * 4 + g) ^ (li & 7)) << 4;
;       bf16x8 xf[MI], wf[4];
; #pragma unroll
;       for (int j = 0; j < 4; ++j) wf[j] = *(const bf16x8*)(smem + wrow + ((j & 1) * 16 + (j >> 1) * 64) * 128 + ch);
; #pragma unroll
;       for (int i = 0; i < MI; ++i) xf[i] = *(const bf16x8*)(smem + xrow + i * 2048 + ch);
; #pragma unroll
;       for (int i = 0; i < MI; ++i)
; #pragma unroll
;         for (int j = 0; j < 4; ++j) {
;           if (SWAP) acc[i][j] = __builtin_amdgcn_mfma_f32_16x16x32_bf16(xf[i], wf[j], acc[i][j], 0, 0, 0);
;           else acc[i][j] = __builtin_amdgcn_mfma_f32_16x16x32_bf16(wf[j], xf[i], acc[i][j], 0, 0, 0);
;         }
; template <int MI, bool F8 = false>
; __device__ void gemm_tile_bf16(const bf16_t* A, int lda, const bf16_t* B, int ldb, int K, bf16_t* C, int ldc, char* smem) {
;     ...
; #pragma unroll
;   for (int i = 0; i < MI; ++i)
; #pragma unroll
;     for (int j = 0; j < 4; ++j) {
;       u32x2 v;
;       v.x = pk_bf16(acc[i][j][0], acc[i][j][1]);
;       v.y = pk_bf16(acc[i][j][2], acc[i][j][3]);
;       *(u32x2*)(C + (size_t)MROW(i) * ldc + NCOL(j)) = v;
;     }
	v_mfma_f32_16x16x32_bf16 v[28:31], v[148:151], v[184:187], v[28:31]
	v_mfma_f32_16x16x32_bf16 v[24:27], v[152:155], v[184:187], v[24:27]
	v_mfma_f32_16x16x32_bf16 v[20:23], v[156:159], v[184:187], v[20:23]
	v_mfma_f32_16x16x32_bf16 v[52:55], v[160:163], v[184:187], v[52:55]
	s_waitcnt lgkmcnt(1)
	v_mfma_f32_16x16x32_bf16 v[48:51], v[148:151], v[188:191], v[48:51]
	v_mfma_f32_16x16x32_bf16 v[164:167], v[152:155], v[188:191], v[56:59]
	v_mfma_f32_16x16x32_bf16 v[168:171], v[156:159], v[188:191], v[112:115]
	v_mfma_f32_16x16x32_bf16 v[172:175], v[160:163], v[188:191], v[108:111]
	s_waitcnt lgkmcnt(0)
	v_mfma_f32_16x16x32_bf16 v[148:151], v[148:151], v[192:195], v[100:103]
	v_mfma_f32_16x16x32_bf16 v[152:155], v[152:155], v[192:195], v[96:99]
	v_mfma_f32_16x16x32_bf16 v[156:159], v[156:159], v[192:195], v[92:95]
	v_mfma_f32_16x16x32_bf16 v[144:147], v[160:163], v[192:195], v[144:147]
	ds_read_b128 v[160:163], v206 offset:32768
	ds_read_b128 v[176:179], v206 offset:34816
	ds_read_b128 v[180:183], v206 offset:40960
	ds_read_b128 v[184:187], v206 offset:43008
	ds_read_b128 v[56:59], v0
	ds_read_b128 v[92:95], v0 offset:2048
	ds_read_b128 v[96:99], v0 offset:4096
	ds_read_b128 v[188:191], v0 offset:6144
	ds_read_b128 v[192:195], v0 offset:8192
	ds_read_b128 v[196:199], v0 offset:10240
	ds_read_b128 v[200:203], v0 offset:12288
	ds_read_b128 v[204:207], v0 offset:14336
	s_waitcnt lgkmcnt(7)
	v_mfma_f32_16x16x32_bf16 v[140:143], v[160:163], v[56:59], v[140:143]
	v_mfma_f32_16x16x32_bf16 v[136:139], v[176:179], v[56:59], v[136:139]
	v_mfma_f32_16x16x32_bf16 v[132:135], v[180:183], v[56:59], v[132:135]
	s_nop 5
	v_cvt_pk_bf16_f32 v140, v140, v141
	v_cvt_pk_bf16_f32 v141, v142, v143
	v_cvt_pk_bf16_f32 v136, v136, v137
	v_mfma_f32_16x16x32_bf16 v[128:131], v[184:187], v[56:59], v[128:131]
	v_cvt_pk_bf16_f32 v137, v138, v139
	v_cvt_pk_bf16_f32 v132, v132, v133
	v_cvt_pk_bf16_f32 v133, v134, v135
	s_waitcnt lgkmcnt(2)
	v_mfma_f32_16x16x32_bf16 v[56:59], v[180:183], v[196:199], v[20:23]
	s_waitcnt lgkmcnt(0)
	v_mfma_f32_16x16x32_bf16 v[20:23], v[184:187], v[204:207], v[144:147]
	s_nop 0
	v_cvt_pk_bf16_f32 v128, v128, v129
	v_cvt_pk_bf16_f32 v129, v130, v131
	s_nop 2
	v_cvt_pk_bf16_f32 v56, v56, v57
	v_mov_b32_e32 v146, v208
	v_mfma_f32_16x16x32_bf16 v[124:127], v[160:163], v[92:95], v[124:127]
	v_lshrrev_b32_e32 v0, 1, v146
	v_and_b32_e32 v0, 32, v0
	v_lshrrev_b32_e32 v2, 2, v146
	v_and_b32_e32 v147, 0xffffff8f, v146
	v_and_or_b32 v0, v2, 12, v0
	v_mov_b64_e32 v[2:3], s[10:11]
	v_mfma_f32_16x16x32_bf16 v[216:219], v[180:183], v[92:95], v[116:119]
	v_mad_i64_i32 v[144:145], s[10:11], v147, s20, v[2:3]
	v_lshlrev_b32_e32 v0, 1, v0
	v_mfma_f32_16x16x32_bf16 v[116:119], v[184:187], v[92:95], v[104:107]
	v_lshl_add_u64 v[142:143], v[144:145], 0, v[0:1]
	global_store_dwordx2 v[142:143], v[128:129], off offset:160
	v_or_b32_e32 v128, 16, v147
	v_mfma_f32_16x16x32_bf16 v[112:115], v[160:163], v[96:99], v[88:91]
	v_mad_i64_i32 v[128:129], s[10:11], v128, s20, v[2:3]
	v_cvt_pk_bf16_f32 v124, v124, v125
	v_mfma_f32_16x16x32_bf16 v[100:103], v[184:187], v[96:99], v[76:79]
	v_cvt_pk_bf16_f32 v125, v126, v127
	v_lshl_add_u64 v[126:127], v[128:129], 0, v[0:1]
	v_cvt_pk_bf16_f32 v116, v116, v117
	v_cvt_pk_bf16_f32 v117, v118, v119
	global_store_dwordx2 v[126:127], v[116:117], off offset:160
	v_or_b32_e32 v116, 32, v147
	v_mfma_f32_16x16x32_bf16 v[108:111], v[176:179], v[96:99], v[84:87]
	v_mad_i64_i32 v[116:117], s[10:11], v116, s20, v[2:3]
	v_cvt_pk_bf16_f32 v112, v112, v113
	v_mfma_f32_16x16x32_bf16 v[104:107], v[180:183], v[96:99], v[80:83]
	v_cvt_pk_bf16_f32 v113, v114, v115
	v_lshl_add_u64 v[114:115], v[116:117], 0, v[0:1]
	v_cvt_pk_bf16_f32 v100, v100, v101
	v_mfma_f32_16x16x32_bf16 v[96:99], v[160:163], v[188:191], v[72:75]
	v_cvt_pk_bf16_f32 v101, v102, v103
	global_store_dwordx2 v[114:115], v[100:101], off offset:160
	v_or_b32_e32 v100, 48, v147
	v_mfma_f32_16x16x32_bf16 v[84:87], v[184:187], v[188:191], v[60:63]
	v_mad_i64_i32 v[100:101], s[10:11], v100, s20, v[2:3]
	s_nop 2
	v_cvt_pk_bf16_f32 v96, v96, v97
	v_mfma_f32_16x16x32_bf16 v[120:123], v[176:179], v[92:95], v[120:123]
	v_cvt_pk_bf16_f32 v97, v98, v99
	v_lshl_add_u64 v[98:99], v[100:101], 0, v[0:1]
	v_cvt_pk_bf16_f32 v84, v84, v85
	v_mfma_f32_16x16x32_bf16 v[92:95], v[176:179], v[188:191], v[68:71]
	v_cvt_pk_bf16_f32 v85, v86, v87
	global_store_dwordx2 v[98:99], v[84:85], off offset:160
	v_or_b32_e32 v84, 64, v147
	v_mfma_f32_16x16x32_bf16 v[80:83], v[160:163], v[192:195], v[44:47]
	v_mad_i64_i32 v[84:85], s[10:11], v84, s20, v[2:3]
	v_cvt_pk_bf16_f32 v120, v120, v121
	v_mfma_f32_16x16x32_bf16 v[68:71], v[184:187], v[192:195], v[32:35]
	v_cvt_pk_bf16_f32 v121, v122, v123
	s_nop 3
	v_cvt_pk_bf16_f32 v80, v80, v81
	v_cvt_pk_bf16_f32 v81, v82, v83
	v_mfma_f32_16x16x32_bf16 v[88:91], v[180:183], v[188:191], v[64:67]
	v_lshl_add_u64 v[82:83], v[84:85], 0, v[0:1]
	v_cvt_pk_bf16_f32 v68, v68, v69
	v_cvt_pk_bf16_f32 v69, v70, v71
	v_mfma_f32_16x16x32_bf16 v[64:67], v[160:163], v[196:199], v[28:31]
; template <int MI, bool F8 = false>
; __device__ void gemm_tile_bf16(const bf16_t* A, int lda, const bf16_t* B, int ldb, int K, bf16_t* C, int ldc, char* smem) {
;     ...
; #pragma unroll
;   for (int i = 0; i < MI; ++i)
; #pragma unroll
;     for (int j = 0; j < 4; ++j) {
;       u32x2 v;
;       v.x = pk_bf16(acc[i][j][0], acc[i][j][1]);
;       v.y = pk_bf16(acc[i][j][2], acc[i][j][3]);
;       *(u32x2*)(C + (size_t)MROW(i) * ldc + NCOL(j)) = v;
;     }
	global_store_dwordx2 v[82:83], v[68:69], off offset:160
	v_or_b32_e32 v68, 0x50, v147
	v_mad_i64_i32 v[68:69], s[10:11], v68, s20, v[2:3]
	v_mfma_f32_16x16x32_bf16 v[52:55], v[184:187], v[196:199], v[52:55]
	s_nop 3
	v_cvt_pk_bf16_f32 v64, v64, v65
	v_cvt_pk_bf16_f32 v65, v66, v67
	v_lshl_add_u64 v[66:67], v[68:69], 0, v[0:1]
	v_mfma_f32_16x16x32_bf16 v[72:75], v[180:183], v[192:195], v[36:39]
	global_store_dwordx2 v[126:127], v[120:121], off offset:32
	v_cvt_pk_bf16_f32 v52, v52, v53
	v_cvt_pk_bf16_f32 v53, v54, v55
	v_mfma_f32_16x16x32_bf16 v[48:51], v[160:163], v[200:203], v[48:51]
	global_store_dwordx2 v[66:67], v[52:53], off offset:160
	v_or_b32_e32 v52, 0x60, v147
	v_mad_i64_i32 v[52:53], s[10:11], v52, s20, v[2:3]
	v_mfma_f32_16x16x32_bf16 v[36:39], v[184:187], v[200:203], v[172:175]
	s_nop 3
	v_cvt_pk_bf16_f32 v48, v48, v49
	v_cvt_pk_bf16_f32 v49, v50, v51
	v_lshl_add_u64 v[50:51], v[52:53], 0, v[0:1]
	v_mfma_f32_16x16x32_bf16 v[76:79], v[176:179], v[192:195], v[40:43]
	v_cvt_pk_bf16_f32 v120, v216, v217
	v_cvt_pk_bf16_f32 v36, v36, v37
	v_cvt_pk_bf16_f32 v37, v38, v39
	v_mfma_f32_16x16x32_bf16 v[60:63], v[176:179], v[196:199], v[24:27]
	global_store_dwordx2 v[50:51], v[36:37], off offset:160
	v_or_b32_e32 v36, 0x70, v146
	v_mad_i64_i32 v[2:3], s[10:11], v36, s20, v[2:3]
	v_mfma_f32_16x16x32_bf16 v[44:47], v[176:179], v[200:203], v[164:167]
	v_cvt_pk_bf16_f32 v121, v218, v219
	v_cvt_pk_bf16_f32 v108, v108, v109
	v_cvt_pk_bf16_f32 v109, v110, v111
	v_mfma_f32_16x16x32_bf16 v[40:43], v[180:183], v[200:203], v[168:171]
	v_cvt_pk_bf16_f32 v104, v104, v105
	v_cvt_pk_bf16_f32 v105, v106, v107
	v_cvt_pk_bf16_f32 v92, v92, v93
	v_mfma_f32_16x16x32_bf16 v[32:35], v[160:163], v[204:207], v[148:151]
	v_cvt_pk_bf16_f32 v93, v94, v95
	v_cvt_pk_bf16_f32 v88, v88, v89
	v_cvt_pk_bf16_f32 v89, v90, v91
	v_mfma_f32_16x16x32_bf16 v[28:31], v[176:179], v[204:207], v[152:155]
	v_cvt_pk_bf16_f32 v76, v76, v77
	v_cvt_pk_bf16_f32 v77, v78, v79
	v_cvt_pk_bf16_f32 v72, v72, v73
	v_mfma_f32_16x16x32_bf16 v[24:27], v[180:183], v[204:207], v[156:159]
	v_cvt_pk_bf16_f32 v73, v74, v75
	v_cvt_pk_bf16_f32 v60, v60, v61
	v_cvt_pk_bf16_f32 v61, v62, v63
	v_cvt_pk_bf16_f32 v57, v58, v59
	v_cvt_pk_bf16_f32 v44, v44, v45
	v_cvt_pk_bf16_f32 v45, v46, v47
	v_cvt_pk_bf16_f32 v40, v40, v41
	v_cvt_pk_bf16_f32 v41, v42, v43
	v_cvt_pk_bf16_f32 v32, v32, v33
	v_cvt_pk_bf16_f32 v33, v34, v35
	v_lshl_add_u64 v[2:3], v[2:3], 0, v[0:1]
	v_cvt_pk_bf16_f32 v28, v28, v29
	v_cvt_pk_bf16_f32 v29, v30, v31
	v_cvt_pk_bf16_f32 v24, v24, v25
	v_cvt_pk_bf16_f32 v25, v26, v27
	v_cvt_pk_bf16_f32 v20, v20, v21
	v_cvt_pk_bf16_f32 v21, v22, v23
	v_mov_b64_e32 v[4:5], v[140:141]
	v_mov_b64_e32 v[6:7], v[136:137]
	s_nop 1
	v_permlane16_swap_b32_e32 v4, v6
	v_permlane16_swap_b32_e32 v5, v7
	v_lshl_add_u64 v[14:15], v[142:143], 0, v[12:13]
	global_store_dwordx4 v[14:15], v[4:7], off
	global_store_dwordx2 v[142:143], v[132:133], off offset:128
	global_store_dwordx2 v[126:127], v[124:125], off
	global_store_dwordx2 v[126:127], v[120:121], off offset:128
	v_mov_b64_e32 v[8:9], v[112:113]
	v_mov_b64_e32 v[10:11], v[108:109]
	s_nop 1
	v_permlane16_swap_b32_e32 v8, v10
	v_permlane16_swap_b32_e32 v9, v11
	v_lshl_add_u64 v[14:15], v[114:115], 0, v[12:13]
	global_store_dwordx4 v[14:15], v[8:11], off
	global_store_dwordx2 v[114:115], v[104:105], off offset:128
	v_mov_b64_e32 v[4:5], v[96:97]
	v_mov_b64_e32 v[6:7], v[92:93]
	s_nop 1
	v_permlane16_swap_b32_e32 v4, v6
	v_permlane16_swap_b32_e32 v5, v7
	v_lshl_add_u64 v[14:15], v[98:99], 0, v[12:13]
	global_store_dwordx4 v[14:15], v[4:7], off
	global_store_dwordx2 v[98:99], v[88:89], off offset:128
	v_mov_b64_e32 v[8:9], v[80:81]
	v_mov_b64_e32 v[10:11], v[76:77]
	s_nop 1
	v_permlane16_swap_b32_e32 v8, v10
	v_permlane16_swap_b32_e32 v9, v11
	v_lshl_add_u64 v[14:15], v[82:83], 0, v[12:13]
	global_store_dwordx4 v[14:15], v[8:11], off
	global_store_dwordx2 v[82:83], v[72:73], off offset:128
	v_mov_b64_e32 v[4:5], v[64:65]
	v_mov_b64_e32 v[6:7], v[60:61]
	s_nop 1
	v_permlane16_swap_b32_e32 v4, v6
	v_permlane16_swap_b32_e32 v5, v7
	v_lshl_add_u64 v[14:15], v[66:67], 0, v[12:13]
	global_store_dwordx4 v[14:15], v[4:7], off
	global_store_dwordx2 v[66:67], v[56:57], off offset:128
	v_mov_b64_e32 v[8:9], v[48:49]
	v_mov_b64_e32 v[10:11], v[44:45]
	s_nop 1
	v_permlane16_swap_b32_e32 v8, v10
	v_permlane16_swap_b32_e32 v9, v11
	v_lshl_add_u64 v[14:15], v[50:51], 0, v[12:13]
	global_store_dwordx4 v[14:15], v[8:11], off
	global_store_dwordx2 v[50:51], v[40:41], off offset:128
	v_mov_b64_e32 v[4:5], v[32:33]
	v_mov_b64_e32 v[6:7], v[28:29]
	s_nop 1
	v_permlane16_swap_b32_e32 v4, v6
	v_permlane16_swap_b32_e32 v5, v7
	v_lshl_add_u64 v[14:15], v[2:3], 0, v[12:13]
	global_store_dwordx4 v[14:15], v[4:7], off
	v_mov_b64_e32 v[8:9], v[24:25]
	v_mov_b64_e32 v[10:11], v[20:21]
	s_nop 1
	v_permlane16_swap_b32_e32 v8, v10
	v_permlane16_swap_b32_e32 v9, v11
	v_lshl_add_u64 v[14:15], v[2:3], 0, v[12:13]
	global_store_dwordx4 v[14:15], v[8:11], off offset:128
	s_cbranch_scc0 .LBB0_119

; template <int MI, bool SWAP, bool F8 = false>
; __device__ __forceinline__ void gemm_core(const bf16_t* __restrict__ A, int lda, const bf16_t* __restrict__ B, int ldb,
;                                           int K, char* smem, f32x4 (&acc)[MI][4]) {
;     ...
;   for (int kt = 0; kt < nk; ++kt) {
;     __syncthreads();
; #pragma unroll
;     for (int i = 0; i < MI; ++i) *(u32x4*)(smem + woff + i * 4096) = ra[i];
; #pragma unroll
;     for (int i = 0; i < 4; ++i) *(u32x4*)(smem + 32768 + woff + i * 4096) = rb[i];
;     __syncthreads();
;     if (kt + 1 < nk) {
; #pragma unroll
;       for (int i = 0; i < MI; ++i) ra[i] = *(const u32x4*)(ap + (size_t)(32 * i) * lda + (kt + 1) * 64);
; #pragma unroll
;       for (int i = 0; i < 4; ++i) rb[i] = *(const u32x4*)(bp + (size_t)(32 * i) * ldb + (kt + 1) * 64);
.LBB0_236:
	v_add_u32_e32 v215, v203, v204
	s_barrier
	s_setprio 3
	s_mov_b32 m0, s62
	s_nop 0
	global_load_lds_dwordx4 v252, s[56:57]
	s_add_u32 m0, s62, 0x1000
	s_nop 0
	global_load_lds_dwordx4 v253, s[56:57]
	s_add_u32 s56, s56, 0x20000
	s_addc_u32 s57, s57, 0
	s_add_u32 m0, s62, 0x2000
	s_nop 0
	global_load_lds_dwordx4 v252, s[56:57]
	s_add_u32 m0, s62, 0x3000
	s_nop 0
	global_load_lds_dwordx4 v253, s[56:57]
	s_add_u32 s56, s56, 0x20000
	s_addc_u32 s57, s57, 0
	s_add_u32 m0, s62, 0x4000
	s_nop 0
	global_load_lds_dwordx4 v252, s[56:57]
	s_add_u32 m0, s62, 0x5000
	s_nop 0
	global_load_lds_dwordx4 v253, s[56:57]
	s_add_u32 s56, s56, 0x20000
	s_addc_u32 s57, s57, 0
	s_add_u32 m0, s62, 0x6000
	s_nop 0
	global_load_lds_dwordx4 v252, s[56:57]
	s_add_u32 m0, s62, 0x7000
	s_nop 0
	global_load_lds_dwordx4 v253, s[56:57]
	s_sub_u32 s56, s56, 0x60000
	s_subb_u32 s57, s57, 0
	s_add_u32 m0, s62, 0x8000
	s_nop 0
	global_load_lds_dwordx4 v252, s[58:59]
	s_add_u32 m0, s62, 0x9000
	s_nop 0
	global_load_lds_dwordx4 v253, s[58:59]
	s_add_u32 s58, s58, 0x20000
	s_addc_u32 s59, s59, 0
	s_add_u32 m0, s62, 0xa000
	s_nop 0
	global_load_lds_dwordx4 v252, s[58:59]
	s_add_u32 m0, s62, 0xb000
	s_nop 0
	global_load_lds_dwordx4 v253, s[58:59]
	s_sub_u32 s58, s58, 0x20000
	s_subb_u32 s59, s59, 0
	s_setprio 0
	v_add_u32_e32 v252, 0x80, v252
	v_add_u32_e32 v253, 0x80, v253
	s_waitcnt vmcnt(0)
	s_cmp_gt_u32 s63, 12
	s_cbranch_scc1 .Lcch236_ret
	s_cmp_eq_u32 s63, 0
	s_cbranch_scc1 .Lcch236_h0
	s_cmp_eq_u32 s63, 3
	s_cbranch_scc1 .Lcch236_h1
	s_cmp_eq_u32 s63, 6
	s_cbranch_scc1 .Lcch236_h2
	s_cmp_eq_u32 s63, 9
	s_cbranch_scc1 .Lcch236_h3
	s_cmp_eq_u32 s63, 12
	s_cbranch_scc1 .Lcch236_h4
	s_branch .Lcch236_ret

; template <int MI, bool SWAP, bool F8 = false>
; __device__ __forceinline__ void gemm_core(const bf16_t* __restrict__ A, int lda, const bf16_t* __restrict__ B, int ldb,
;                                           int K, char* smem, f32x4 (&acc)[MI][4]) {
;     ...
;     for (int kk = 0; kk < 2; ++kk) {
;       const int ch = ((kk * 4 + g) ^ (li & 7)) << 4;
;       bf16x8 xf[MI], wf[4];
; #pragma unroll
;       for (int j = 0; j < 4; ++j) wf[j] = *(const bf16x8*)(smem + wrow + ((j & 1) * 16 + (j >> 1) * 64) * 128 + ch);
; #pragma unroll
;       for (int i = 0; i < MI; ++i) xf[i] = *(const bf16x8*)(smem + xrow + i * 2048 + ch);
; #pragma unroll
;       for (int i = 0; i < MI; ++i)
; #pragma unroll
;         for (int j = 0; j < 4; ++j) {
;           if (SWAP) acc[i][j] = __builtin_amdgcn_mfma_f32_16x16x32_bf16(xf[i], wf[j], acc[i][j], 0, 0, 0);
;           else acc[i][j] = __builtin_amdgcn_mfma_f32_16x16x32_bf16(wf[j], xf[i], acc[i][j], 0, 0, 0);
;         }
.Lcch236_ret:
	s_add_u32 s63, s63, 1
	s_barrier
	v_add_u32_e32 v213, v202, v204
	ds_read_b128 v[148:151], v215 offset:32768
	ds_read_b128 v[152:155], v215 offset:34816
	ds_read_b128 v[156:159], v213
	ds_read_b128 v[160:163], v213 offset:2048
	ds_read_b128 v[164:167], v215 offset:40960
	ds_read_b128 v[168:171], v215 offset:43008
	s_waitcnt lgkmcnt(3)
	v_mfma_f32_16x16x32_bf16 v[140:143], v[148:151], v[156:159], v[140:143]
	v_add_u32_e32 v207, v203, v205
	v_add_u32_e32 v206, v202, v205
	v_mfma_f32_16x16x32_bf16 v[136:139], v[152:155], v[156:159], v[136:139]
	s_waitcnt lgkmcnt(1)
	v_mfma_f32_16x16x32_bf16 v[132:135], v[164:167], v[156:159], v[132:135]
	s_waitcnt lgkmcnt(0)
	v_mfma_f32_16x16x32_bf16 v[124:127], v[168:171], v[156:159], v[124:127]
	v_mfma_f32_16x16x32_bf16 v[108:111], v[148:151], v[160:163], v[108:111]
	v_mfma_f32_16x16x32_bf16 v[104:107], v[152:155], v[160:163], v[104:107]
	v_mfma_f32_16x16x32_bf16 v[96:99], v[164:167], v[160:163], v[96:99]
	v_mfma_f32_16x16x32_bf16 v[92:95], v[168:171], v[160:163], v[92:95]
	ds_read_b128 v[156:159], v213 offset:4096
	ds_read_b128 v[160:163], v213 offset:6144
	s_waitcnt lgkmcnt(1)
	v_mfma_f32_16x16x32_bf16 v[88:91], v[148:151], v[156:159], v[88:91]
	v_mfma_f32_16x16x32_bf16 v[84:87], v[152:155], v[156:159], v[84:87]
	v_mfma_f32_16x16x32_bf16 v[80:83], v[164:167], v[156:159], v[80:83]
	v_mfma_f32_16x16x32_bf16 v[60:63], v[168:171], v[156:159], v[60:63]
	s_waitcnt lgkmcnt(0)
	v_mfma_f32_16x16x32_bf16 v[56:59], v[148:151], v[160:163], v[56:59]
	v_mfma_f32_16x16x32_bf16 v[52:55], v[152:155], v[160:163], v[52:55]
	v_mfma_f32_16x16x32_bf16 v[48:51], v[164:167], v[160:163], v[48:51]
	v_mfma_f32_16x16x32_bf16 v[44:47], v[168:171], v[160:163], v[44:47]
	ds_read_b128 v[156:159], v213 offset:8192
	ds_read_b128 v[160:163], v213 offset:10240
	s_waitcnt lgkmcnt(1)
	v_mfma_f32_16x16x32_bf16 v[40:43], v[148:151], v[156:159], v[40:43]
	v_mfma_f32_16x16x32_bf16 v[36:39], v[152:155], v[156:159], v[36:39]
	v_mfma_f32_16x16x32_bf16 v[32:35], v[164:167], v[156:159], v[32:35]
	v_mfma_f32_16x16x32_bf16 v[28:31], v[168:171], v[156:159], v[28:31]
	s_waitcnt lgkmcnt(0)
	v_mfma_f32_16x16x32_bf16 v[24:27], v[148:151], v[160:163], v[24:27]
	v_mfma_f32_16x16x32_bf16 v[20:23], v[152:155], v[160:163], v[20:23]
	v_mfma_f32_16x16x32_bf16 v[68:71], v[164:167], v[160:163], v[68:71]
	v_mfma_f32_16x16x32_bf16 v[64:67], v[168:171], v[160:163], v[64:67]
	ds_read_b128 v[156:159], v213 offset:12288
	ds_read_b128 v[160:163], v213 offset:14336
	ds_read_b128 v[172:175], v207 offset:32768
	ds_read_b128 v[180:183], v207 offset:34816
	s_waitcnt lgkmcnt(3)
	v_mfma_f32_16x16x32_bf16 v[72:75], v[148:151], v[156:159], v[72:75]
	v_mfma_f32_16x16x32_bf16 v[76:79], v[152:155], v[156:159], v[76:79]
	v_mfma_f32_16x16x32_bf16 v[128:131], v[164:167], v[156:159], v[128:131]
	v_mfma_f32_16x16x32_bf16 v[120:123], v[168:171], v[156:159], v[120:123]
	s_waitcnt lgkmcnt(2)
	v_mfma_f32_16x16x32_bf16 v[116:119], v[148:151], v[160:163], v[116:119]
	v_mfma_f32_16x16x32_bf16 v[112:115], v[152:155], v[160:163], v[112:115]
	ds_read_b128 v[148:151], v206
	ds_read_b128 v[152:155], v206 offset:2048
	ds_read_b128 v[192:195], v207 offset:40960
	ds_read_b128 v[196:199], v207 offset:43008
	v_mfma_f32_16x16x32_bf16 v[100:103], v[164:167], v[160:163], v[100:103]
	v_mfma_f32_16x16x32_bf16 v[144:147], v[168:171], v[160:163], v[144:147]
	s_waitcnt lgkmcnt(3)
	v_mfma_f32_16x16x32_bf16 v[140:143], v[172:175], v[148:151], v[140:143]
	v_mfma_f32_16x16x32_bf16 v[136:139], v[180:183], v[148:151], v[136:139]
	s_waitcnt lgkmcnt(1)
	v_mfma_f32_16x16x32_bf16 v[132:135], v[192:195], v[148:151], v[132:135]
	s_waitcnt lgkmcnt(0)
	v_mfma_f32_16x16x32_bf16 v[124:127], v[196:199], v[148:151], v[124:127]
	v_mfma_f32_16x16x32_bf16 v[108:111], v[172:175], v[152:155], v[108:111]
	v_mfma_f32_16x16x32_bf16 v[104:107], v[180:183], v[152:155], v[104:107]
	v_mfma_f32_16x16x32_bf16 v[96:99], v[192:195], v[152:155], v[96:99]
	v_mfma_f32_16x16x32_bf16 v[92:95], v[196:199], v[152:155], v[92:95]
	ds_read_b128 v[148:151], v206 offset:4096
	ds_read_b128 v[152:155], v206 offset:6144
	s_waitcnt lgkmcnt(1)
	v_mfma_f32_16x16x32_bf16 v[88:91], v[172:175], v[148:151], v[88:91]
	ds_read_b128 v[156:159], v206 offset:12288
	ds_read_b128 v[216:219], v206 offset:14336
	v_mfma_f32_16x16x32_bf16 v[84:87], v[180:183], v[148:151], v[84:87]
	v_mfma_f32_16x16x32_bf16 v[80:83], v[192:195], v[148:151], v[80:83]
	v_mfma_f32_16x16x32_bf16 v[60:63], v[196:199], v[148:151], v[60:63]
	ds_read_b128 v[148:151], v206 offset:8192
	s_waitcnt lgkmcnt(3)
	v_mfma_f32_16x16x32_bf16 v[56:59], v[172:175], v[152:155], v[56:59]
	v_mfma_f32_16x16x32_bf16 v[52:55], v[180:183], v[152:155], v[52:55]
	v_mfma_f32_16x16x32_bf16 v[48:51], v[192:195], v[152:155], v[48:51]
	v_mfma_f32_16x16x32_bf16 v[44:47], v[196:199], v[152:155], v[44:47]
	ds_read_b128 v[152:155], v206 offset:10240
	s_waitcnt lgkmcnt(1)
	v_mfma_f32_16x16x32_bf16 v[40:43], v[172:175], v[148:151], v[40:43]
	v_mfma_f32_16x16x32_bf16 v[36:39], v[180:183], v[148:151], v[36:39]
	v_mfma_f32_16x16x32_bf16 v[32:35], v[192:195], v[148:151], v[32:35]
	v_mfma_f32_16x16x32_bf16 v[28:31], v[196:199], v[148:151], v[28:31]
	s_waitcnt lgkmcnt(0)
	v_mfma_f32_16x16x32_bf16 v[24:27], v[172:175], v[152:155], v[24:27]
	v_mfma_f32_16x16x32_bf16 v[20:23], v[180:183], v[152:155], v[20:23]
	v_mfma_f32_16x16x32_bf16 v[68:71], v[192:195], v[152:155], v[68:71]
	v_mfma_f32_16x16x32_bf16 v[64:67], v[196:199], v[152:155], v[64:67]
	v_mfma_f32_16x16x32_bf16 v[72:75], v[172:175], v[156:159], v[72:75]
	v_mfma_f32_16x16x32_bf16 v[76:79], v[180:183], v[156:159], v[76:79]
	v_mfma_f32_16x16x32_bf16 v[128:131], v[192:195], v[156:159], v[128:131]
	v_mfma_f32_16x16x32_bf16 v[120:123], v[196:199], v[156:159], v[120:123]
	v_mfma_f32_16x16x32_bf16 v[116:119], v[172:175], v[216:219], v[116:119]
	v_mfma_f32_16x16x32_bf16 v[112:115], v[180:183], v[216:219], v[112:115]
	v_mfma_f32_16x16x32_bf16 v[100:103], v[192:195], v[216:219], v[100:103]
	v_mfma_f32_16x16x32_bf16 v[144:147], v[196:199], v[216:219], v[144:147]
	s_add_u32 s20, s20, 0x80
	s_addc_u32 s21, s21, 0
	s_cmpk_lg_i32 s20, 0x780
	s_cbranch_scc1 .LBB0_236
; template <int MI, bool SWAP, bool F8 = false>
; __device__ __forceinline__ void gemm_core(const bf16_t* __restrict__ A, int lda, const bf16_t* __restrict__ B, int ldb,
;                                           int K, char* smem, f32x4 (&acc)[MI][4]) {
;     ...
;   for (int kt = 0; kt < nk; ++kt) {
;     __syncthreads();
; #pragma unroll
;     for (int i = 0; i < MI; ++i) *(u32x4*)(smem + woff + i * 4096) = ra[i];
; #pragma unroll
;     for (int i = 0; i < 4; ++i) *(u32x4*)(smem + 32768 + woff + i * 4096) = rb[i];
;     __syncthreads();
;     if (kt + 1 < nk) {
; #pragma unroll
;       for (int i = 0; i < MI; ++i) ra[i] = *(const u32x4*)(ap + (size_t)(32 * i) * lda + (kt + 1) * 64);
; #pragma unroll
;       for (int i = 0; i < 4; ++i) rb[i] = *(const u32x4*)(bp + (size_t)(32 * i) * ldb + (kt + 1) * 64);
;     }
;     if (F8) {
;       const int c0 = (g ^ (li & 7)) << 4, c1 = ((4 + g) ^ (li & 7)) << 4;
;       i32x8 wf8[4];
; #pragma unroll
;       for (int j = 0; j < 4; ++j) {
;         const char* rp = smem + wrow + ((j & 1) * 16 + (j >> 1) * 64) * 128;
;         const u32x4 lo = *(const u32x4*)(rp + c0), hi = *(const u32x4*)(rp + c1);
;         wf8[j] = (i32x8){(int)lo.x, (int)lo.y, (int)lo.z, (int)lo.w, (int)hi.x, (int)hi.y, (int)hi.z, (int)hi.w};
;       }
; #pragma unroll
;       for (int i = 0; i < MI; ++i) {
;         const char* rp = smem + xrow + i * 2048;
;         const u32x4 lo = *(const u32x4*)(rp + c0), hi = *(const u32x4*)(rp + c1);
;         const i32x8 xf8 = {(int)lo.x, (int)lo.y, (int)lo.z, (int)lo.w, (int)hi.x, (int)hi.y, (int)hi.z, (int)hi.w};
; #pragma unroll
;         for (int j = 0; j < 4; ++j)
;           acc[i][j] = __builtin_amdgcn_mfma_scale_f32_16x16x128_f8f6f4(wf8[j], xf8, acc[i][j], 0, 0, 0, 0x77777777, 0, 0x7f7f7f7f);
;       }
;     } else {
; #pragma unroll
;     for (int kk = 0; kk < 2; ++kk) {
;       const int ch = ((kk * 4 + g) ^ (li & 7)) << 4;
;       bf16x8 xf[MI], wf[4];
; #pragma unroll
;       for (int j = 0; j < 4; ++j) wf[j] = *(const bf16x8*)(smem + wrow + ((j & 1) * 16 + (j >> 1) * 64) * 128 + ch);
; #pragma unroll
;       for (int i = 0; i < MI; ++i) xf[i] = *(const bf16x8*)(smem + xrow + i * 2048 + ch);
; #pragma unroll
;       for (int i = 0; i < MI; ++i)
; #pragma unroll
;         for (int j = 0; j < 4; ++j) {
	s_barrier
	s_setprio 3
	s_mov_b32 m0, s62
	s_nop 0
	global_load_lds_dwordx4 v252, s[56:57]
	s_add_u32 m0, s62, 0x1000
	s_nop 0
	global_load_lds_dwordx4 v253, s[56:57]
	s_add_u32 s56, s56, 0x20000
	s_addc_u32 s57, s57, 0
	s_add_u32 m0, s62, 0x2000
	s_nop 0
	global_load_lds_dwordx4 v252, s[56:57]
	s_add_u32 m0, s62, 0x3000
	s_nop 0
	global_load_lds_dwordx4 v253, s[56:57]
	s_add_u32 s56, s56, 0x20000
	s_addc_u32 s57, s57, 0
	s_add_u32 m0, s62, 0x4000
	s_nop 0
	global_load_lds_dwordx4 v252, s[56:57]
	s_add_u32 m0, s62, 0x5000
	s_nop 0
	global_load_lds_dwordx4 v253, s[56:57]
	s_add_u32 s56, s56, 0x20000
	s_addc_u32 s57, s57, 0
	s_add_u32 m0, s62, 0x6000
	s_nop 0
	global_load_lds_dwordx4 v252, s[56:57]
	s_add_u32 m0, s62, 0x7000
	s_nop 0
	global_load_lds_dwordx4 v253, s[56:57]
	s_sub_u32 s56, s56, 0x60000
	s_subb_u32 s57, s57, 0
	s_add_u32 m0, s62, 0x8000
	s_nop 0
	global_load_lds_dwordx4 v252, s[58:59]
	s_add_u32 m0, s62, 0x9000
	s_nop 0
	global_load_lds_dwordx4 v253, s[58:59]
	s_add_u32 s58, s58, 0x20000
	s_addc_u32 s59, s59, 0
	s_add_u32 m0, s62, 0xa000
	s_nop 0
	global_load_lds_dwordx4 v252, s[58:59]
	s_add_u32 m0, s62, 0xb000
	s_nop 0
	global_load_lds_dwordx4 v253, s[58:59]
	s_sub_u32 s58, s58, 0x20000
	s_subb_u32 s59, s59, 0
	s_setprio 0
	s_waitcnt vmcnt(0)
	s_barrier
	ds_read_b128 v[148:151], v215 offset:32768
	ds_read_b128 v[152:155], v215 offset:34816
	ds_read_b128 v[156:159], v215 offset:40960
	ds_read_b128 v[160:163], v215 offset:43008
	ds_read_b128 v[164:167], v213
	ds_read_b128 v[168:171], v213 offset:2048
	ds_read_b128 v[172:175], v213 offset:4096
	ds_read_b128 v[176:179], v213 offset:6144
	ds_read_b128 v[180:183], v213 offset:8192
	ds_read_b128 v[184:187], v213 offset:10240
	ds_read_b128 v[188:191], v213 offset:12288
	ds_read_b128 v[192:195], v213 offset:14336
	s_waitcnt lgkmcnt(7)
	v_mfma_f32_16x16x32_bf16 v[132:135], v[156:159], v[164:167], v[132:135]
	s_lshl_b64 s[10:11], s[10:11], 2
	s_add_u32 s10, s16, s10
	s_addc_u32 s11, s17, s11
	v_mfma_f32_16x16x32_bf16 v[140:143], v[148:151], v[164:167], v[140:143]
	s_lshl_b32 s20, s26, 2
	s_add_u32 s10, s10, s20
	s_addc_u32 s11, s11, 0
	v_mfma_f32_16x16x32_bf16 v[136:139], v[152:155], v[164:167], v[136:139]
	s_add_i32 s25, s25, s78
	s_add_i32 s24, s24, s71
	s_add_i32 s23, s23, s76
	v_mfma_f32_16x16x32_bf16 v[124:127], v[160:163], v[164:167], v[124:127]
	s_cmpk_gt_i32 s25, 0x1ff
	s_waitcnt lgkmcnt(6)
	v_mfma_f32_16x16x32_bf16 v[108:111], v[148:151], v[168:171], v[108:111]
	v_mfma_f32_16x16x32_bf16 v[104:107], v[152:155], v[168:171], v[104:107]
	v_mfma_f32_16x16x32_bf16 v[96:99], v[156:159], v[168:171], v[96:99]
	v_mfma_f32_16x16x32_bf16 v[92:95], v[160:163], v[168:171], v[92:95]
	s_waitcnt lgkmcnt(5)
	v_mfma_f32_16x16x32_bf16 v[88:91], v[148:151], v[172:175], v[88:91]
	v_mfma_f32_16x16x32_bf16 v[84:87], v[152:155], v[172:175], v[84:87]
	v_mfma_f32_16x16x32_bf16 v[80:83], v[156:159], v[172:175], v[80:83]
	v_mfma_f32_16x16x32_bf16 v[60:63], v[160:163], v[172:175], v[60:63]
	s_waitcnt lgkmcnt(4)
	v_mfma_f32_16x16x32_bf16 v[56:59], v[148:151], v[176:179], v[56:59]
	v_mfma_f32_16x16x32_bf16 v[52:55], v[152:155], v[176:179], v[52:55]
	v_mfma_f32_16x16x32_bf16 v[48:51], v[156:159], v[176:179], v[48:51]
	v_mfma_f32_16x16x32_bf16 v[44:47], v[160:163], v[176:179], v[44:47]
	s_waitcnt lgkmcnt(3)
	v_mfma_f32_16x16x32_bf16 v[40:43], v[148:151], v[180:183], v[40:43]
	v_mfma_f32_16x16x32_bf16 v[36:39], v[152:155], v[180:183], v[36:39]
	v_mfma_f32_16x16x32_bf16 v[32:35], v[156:159], v[180:183], v[32:35]
	v_mfma_f32_16x16x32_bf16 v[28:31], v[160:163], v[180:183], v[28:31]
	s_waitcnt lgkmcnt(2)
	v_mfma_f32_16x16x32_bf16 v[24:27], v[148:151], v[184:187], v[24:27]
	v_mfma_f32_16x16x32_bf16 v[20:23], v[152:155], v[184:187], v[20:23]
	v_mfma_f32_16x16x32_bf16 v[164:167], v[156:159], v[184:187], v[68:71]
	v_mfma_f32_16x16x32_bf16 v[168:171], v[160:163], v[184:187], v[64:67]
	s_waitcnt lgkmcnt(1)
	v_mfma_f32_16x16x32_bf16 v[172:175], v[148:151], v[188:191], v[72:75]
	v_mfma_f32_16x16x32_bf16 v[176:179], v[152:155], v[188:191], v[76:79]
	v_mfma_f32_16x16x32_bf16 v[180:183], v[156:159], v[188:191], v[128:131]
	v_mfma_f32_16x16x32_bf16 v[184:187], v[160:163], v[188:191], v[120:123]
	s_waitcnt lgkmcnt(0)
	v_mfma_f32_16x16x32_bf16 v[148:151], v[148:151], v[192:195], v[116:119]
	v_mfma_f32_16x16x32_bf16 v[152:155], v[152:155], v[192:195], v[112:115]
	v_mfma_f32_16x16x32_bf16 v[156:159], v[156:159], v[192:195], v[100:103]
	v_mfma_f32_16x16x32_bf16 v[144:147], v[160:163], v[192:195], v[144:147]
	ds_read_b128 v[160:163], v207 offset:32768
	ds_read_b128 v[188:191], v207 offset:34816
	ds_read_b128 v[192:195], v207 offset:40960
	ds_read_b128 v[196:199], v207 offset:43008
	ds_read_b128 v[64:67], v206
	ds_read_b128 v[68:71], v206 offset:2048
	ds_read_b128 v[72:75], v206 offset:4096
	ds_read_b128 v[76:79], v206 offset:6144
	ds_read_b128 v[200:203], v206 offset:8192
	ds_read_b128 v[216:219], v206 offset:10240
	ds_read_b128 v[220:223], v206 offset:12288
	ds_read_b128 v[204:207], v206 offset:14336
	s_waitcnt lgkmcnt(7)
; template <bool ACCUM, int MI>
; __device__ void gemm_tile_f32(const bf16_t* A, int lda, const bf16_t* B, int ldb, int K, float* C, int ldc, char* smem) {
;     ...
; #pragma unroll
;   for (int i = 0; i < MI; ++i)
; #pragma unroll
;     for (int j = 0; j < 4; ++j) {
;       f32x4* cp = (f32x4*)(C + (size_t)MROW(i) * ldc + NCOL(j));
;       f32x4 v = acc[i][j];
;       if (ACCUM) v += *cp;
;       *cp = v;
;     }
	v_mfma_f32_16x16x32_bf16 v[224:227], v[192:195], v[64:67], v[132:135]
	v_mfma_f32_16x16x32_bf16 v[228:231], v[196:199], v[64:67], v[124:127]
	s_waitcnt lgkmcnt(6)
	v_mfma_f32_16x16x32_bf16 v[128:131], v[160:163], v[68:71], v[108:111]
	v_mfma_f32_16x16x32_bf16 v[124:127], v[188:191], v[68:71], v[104:107]
	s_waitcnt lgkmcnt(5)
	v_mfma_f32_16x16x32_bf16 v[112:115], v[160:163], v[72:75], v[88:91]
	v_mfma_f32_16x16x32_bf16 v[108:111], v[188:191], v[72:75], v[84:87]
	v_mfma_f32_16x16x32_bf16 v[104:107], v[192:195], v[72:75], v[80:83]
	v_mfma_f32_16x16x32_bf16 v[100:103], v[196:199], v[72:75], v[60:63]
	s_waitcnt lgkmcnt(3)
	v_mfma_f32_16x16x32_bf16 v[72:75], v[192:195], v[200:203], v[32:35]
	s_waitcnt lgkmcnt(0)
	v_mfma_f32_16x16x32_bf16 v[32:35], v[160:163], v[204:207], v[148:151]
	v_mfma_f32_16x16x32_bf16 v[60:63], v[188:191], v[216:219], v[20:23]
	v_mfma_f32_16x16x32_bf16 v[20:23], v[196:199], v[204:207], v[144:147]
	v_mfma_f32_16x16x32_bf16 v[140:143], v[160:163], v[64:67], v[140:143]
	v_mfma_f32_16x16x32_bf16 v[136:139], v[188:191], v[64:67], v[136:139]
	v_mfma_f32_16x16x32_bf16 v[120:123], v[192:195], v[68:71], v[96:99]
	v_mfma_f32_16x16x32_bf16 v[116:119], v[196:199], v[68:71], v[92:95]
	v_mfma_f32_16x16x32_bf16 v[96:99], v[160:163], v[76:79], v[56:59]
	v_mfma_f32_16x16x32_bf16 v[92:95], v[188:191], v[76:79], v[52:55]
	v_mfma_f32_16x16x32_bf16 v[88:91], v[192:195], v[76:79], v[48:51]
	v_mfma_f32_16x16x32_bf16 v[84:87], v[196:199], v[76:79], v[44:47]
	v_mfma_f32_16x16x32_bf16 v[80:83], v[160:163], v[200:203], v[40:43]
	v_mfma_f32_16x16x32_bf16 v[76:79], v[188:191], v[200:203], v[36:39]
	v_mfma_f32_16x16x32_bf16 v[68:71], v[196:199], v[200:203], v[28:31]
	v_mfma_f32_16x16x32_bf16 v[64:67], v[160:163], v[216:219], v[24:27]
	v_mfma_f32_16x16x32_bf16 v[56:59], v[192:195], v[216:219], v[164:167]
	v_mfma_f32_16x16x32_bf16 v[52:55], v[196:199], v[216:219], v[168:171]
	v_mfma_f32_16x16x32_bf16 v[48:51], v[160:163], v[220:223], v[172:175]
	v_mfma_f32_16x16x32_bf16 v[44:47], v[188:191], v[220:223], v[176:179]
	v_mfma_f32_16x16x32_bf16 v[40:43], v[192:195], v[220:223], v[180:183]
	v_mfma_f32_16x16x32_bf16 v[36:39], v[196:199], v[220:223], v[184:187]
	v_mfma_f32_16x16x32_bf16 v[28:31], v[188:191], v[204:207], v[152:155]
	v_mfma_f32_16x16x32_bf16 v[24:27], v[192:195], v[204:207], v[156:159]
	s_nop 7
	s_nop 7
	s_nop 7
	global_store_dwordx4 v237, v[140:143], s[98:99]
	global_store_dwordx4 v237, v[136:139], s[98:99] offset:64
	global_store_dwordx4 v237, v[224:227], s[98:99] offset:256
	global_store_dwordx4 v237, v[228:231], s[98:99] offset:320
	v_add_u32_e32 v237, 0x10000, v237
	global_store_dwordx4 v237, v[128:131], s[98:99]
	global_store_dwordx4 v237, v[124:127], s[98:99] offset:64
	global_store_dwordx4 v237, v[120:123], s[98:99] offset:256
	global_store_dwordx4 v237, v[116:119], s[98:99] offset:320
	v_add_u32_e32 v237, 0x10000, v237
	global_store_dwordx4 v237, v[112:115], s[98:99]
	global_store_dwordx4 v237, v[108:111], s[98:99] offset:64
	global_store_dwordx4 v237, v[104:107], s[98:99] offset:256
	global_store_dwordx4 v237, v[100:103], s[98:99] offset:320
	v_add_u32_e32 v237, 0x10000, v237
	global_store_dwordx4 v237, v[96:99], s[98:99]
	global_store_dwordx4 v237, v[92:95], s[98:99] offset:64
	global_store_dwordx4 v237, v[88:91], s[98:99] offset:256
	global_store_dwordx4 v237, v[84:87], s[98:99] offset:320
	v_add_u32_e32 v237, 0x10000, v237
	global_store_dwordx4 v237, v[80:83], s[98:99]
	global_store_dwordx4 v237, v[76:79], s[98:99] offset:64
	global_store_dwordx4 v237, v[72:75], s[98:99] offset:256
	global_store_dwordx4 v237, v[68:71], s[98:99] offset:320
	v_add_u32_e32 v237, 0x10000, v237
	global_store_dwordx4 v237, v[64:67], s[98:99]
	global_store_dwordx4 v237, v[60:63], s[98:99] offset:64
	global_store_dwordx4 v237, v[56:59], s[98:99] offset:256
	global_store_dwordx4 v237, v[52:55], s[98:99] offset:320
	v_add_u32_e32 v237, 0x10000, v237
	global_store_dwordx4 v237, v[48:51], s[98:99]
	global_store_dwordx4 v237, v[44:47], s[98:99] offset:64
	global_store_dwordx4 v237, v[40:43], s[98:99] offset:256
	global_store_dwordx4 v237, v[36:39], s[98:99] offset:320
	v_add_u32_e32 v237, 0x10000, v237
	global_store_dwordx4 v237, v[32:35], s[98:99]
	global_store_dwordx4 v237, v[28:31], s[98:99] offset:64
	global_store_dwordx4 v237, v[24:27], s[98:99] offset:256
	global_store_dwordx4 v237, v[20:23], s[98:99] offset:320
	s_cbranch_scc0 .LBB0_235

; template <int MI, bool SWAP, bool F8 = false>
; __device__ __forceinline__ void gemm_core(const bf16_t* __restrict__ A, int lda, const bf16_t* __restrict__ B, int ldb,
;                                           int K, char* smem, f32x4 (&acc)[MI][4]) {
;     ...
;   for (int kt = 0; kt < nk; ++kt) {
;     __syncthreads();
; #pragma unroll
;     for (int i = 0; i < MI; ++i) *(u32x4*)(smem + woff + i * 4096) = ra[i];
; #pragma unroll
;     for (int i = 0; i < 4; ++i) *(u32x4*)(smem + 32768 + woff + i * 4096) = rb[i];
;     __syncthreads();
;     if (kt + 1 < nk) {
; #pragma unroll
;       for (int i = 0; i < MI; ++i) ra[i] = *(const u32x4*)(ap + (size_t)(32 * i) * lda + (kt + 1) * 64);
; #pragma unroll
;       for (int i = 0; i < 4; ++i) rb[i] = *(const u32x4*)(bp + (size_t)(32 * i) * ldb + (kt + 1) * 64);
;     }
;     if (F8) {
;       const int c0 = (g ^ (li & 7)) << 4, c1 = ((4 + g) ^ (li & 7)) << 4;
;       i32x8 wf8[4];
; #pragma unroll
;       for (int j = 0; j < 4; ++j) {
;         const char* rp = smem + wrow + ((j & 1) * 16 + (j >> 1) * 64) * 128;
;         const u32x4 lo = *(const u32x4*)(rp + c0), hi = *(const u32x4*)(rp + c1);
;         wf8[j] = (i32x8){(int)lo.x, (int)lo.y, (int)lo.z, (int)lo.w, (int)hi.x, (int)hi.y, (int)hi.z, (int)hi.w};
;       }
; #pragma unroll
;       for (int i = 0; i < MI; ++i) {
;         const char* rp = smem + xrow + i * 2048;
;         const u32x4 lo = *(const u32x4*)(rp + c0), hi = *(const u32x4*)(rp + c1);
;         const i32x8 xf8 = {(int)lo.x, (int)lo.y, (int)lo.z, (int)lo.w, (int)hi.x, (int)hi.y, (int)hi.z, (int)hi.w};
; #pragma unroll
;         for (int j = 0; j < 4; ++j)
;           acc[i][j] = __builtin_amdgcn_mfma_scale_f32_16x16x128_f8f6f4(wf8[j], xf8, acc[i][j], 0, 0, 0, 0x77777777, 0, 0x7f7f7f7f);
;       }
;     } else {
; #pragma unroll
;     for (int kk = 0; kk < 2; ++kk) {
;       const int ch = ((kk * 4 + g) ^ (li & 7)) << 4;
;       bf16x8 xf[MI], wf[4];
; #pragma unroll
;       for (int j = 0; j < 4; ++j) wf[j] = *(const bf16x8*)(smem + wrow + ((j & 1) * 16 + (j >> 1) * 64) * 128 + ch);
; #pragma unroll
;       for (int i = 0; i < MI; ++i) xf[i] = *(const bf16x8*)(smem + xrow + i * 2048 + ch);
; #pragma unroll
;       for (int i = 0; i < MI; ++i)
; #pragma unroll
;         for (int j = 0; j < 4; ++j) {
.LBB0_301:
	v_add_u32_e32 v213, v204, v205
	s_barrier
	s_setprio 3
	s_mov_b32 m0, s62
	s_nop 0
	global_load_lds_dwordx4 v252, s[56:57]
	s_add_u32 m0, s62, 0x1000
	s_nop 0
	global_load_lds_dwordx4 v253, s[56:57]
	s_add_u32 s56, s56, 0x20000
	s_addc_u32 s57, s57, 0
	s_add_u32 m0, s62, 0x2000
	s_nop 0
	global_load_lds_dwordx4 v252, s[56:57]
	s_add_u32 m0, s62, 0x3000
	s_nop 0
	global_load_lds_dwordx4 v253, s[56:57]
	s_add_u32 s56, s56, 0x20000
	s_addc_u32 s57, s57, 0
	s_add_u32 m0, s62, 0x4000
	s_nop 0
	global_load_lds_dwordx4 v252, s[56:57]
	s_add_u32 m0, s62, 0x5000
	s_nop 0
	global_load_lds_dwordx4 v253, s[56:57]
	s_add_u32 s56, s56, 0x20000
	s_addc_u32 s57, s57, 0
	s_add_u32 m0, s62, 0x6000
	s_nop 0
	global_load_lds_dwordx4 v252, s[56:57]
	s_add_u32 m0, s62, 0x7000
	s_nop 0
	global_load_lds_dwordx4 v253, s[56:57]
	s_sub_u32 s56, s56, 0x60000
	s_subb_u32 s57, s57, 0
	s_add_u32 m0, s62, 0x8000
	s_nop 0
	global_load_lds_dwordx4 v252, s[58:59]
	s_add_u32 m0, s62, 0x9000
	s_nop 0
	global_load_lds_dwordx4 v253, s[58:59]
	s_add_u32 s58, s58, 0x20000
	s_addc_u32 s59, s59, 0
	s_add_u32 m0, s62, 0xa000
	s_nop 0
	global_load_lds_dwordx4 v252, s[58:59]
	s_add_u32 m0, s62, 0xb000
	s_nop 0
	global_load_lds_dwordx4 v253, s[58:59]
	s_sub_u32 s58, s58, 0x20000
	s_subb_u32 s59, s59, 0
	s_setprio 0
	v_add_u32_e32 v252, 0x80, v252
	v_add_u32_e32 v253, 0x80, v253
	s_waitcnt vmcnt(0)
	s_barrier
	v_add_u32_e32 v0, v203, v205
	ds_read_b128 v[136:139], v213 offset:32768
	ds_read_b128 v[144:147], v213 offset:34816
	ds_read_b128 v[152:155], v0
	ds_read_b128 v[156:159], v0 offset:2048
	ds_read_b128 v[164:167], v213 offset:40960
	ds_read_b128 v[168:171], v213 offset:43008
	s_waitcnt lgkmcnt(3)
	v_mfma_f32_16x16x32_bf16 v[148:151], v[136:139], v[152:155], v[148:151]
	v_add_u32_e32 v215, v204, v206
	v_add_u32_e32 v207, v203, v206
	v_mfma_f32_16x16x32_bf16 v[140:143], v[144:147], v[152:155], v[140:143]
	s_waitcnt lgkmcnt(1)
	v_mfma_f32_16x16x32_bf16 v[132:135], v[164:167], v[152:155], v[132:135]
	s_waitcnt lgkmcnt(0)
	v_mfma_f32_16x16x32_bf16 v[128:131], v[168:171], v[152:155], v[128:131]
	v_mfma_f32_16x16x32_bf16 v[124:127], v[136:139], v[156:159], v[124:127]
	v_mfma_f32_16x16x32_bf16 v[120:123], v[144:147], v[156:159], v[120:123]
	v_mfma_f32_16x16x32_bf16 v[116:119], v[164:167], v[156:159], v[116:119]
	v_mfma_f32_16x16x32_bf16 v[112:115], v[168:171], v[156:159], v[112:115]
	ds_read_b128 v[152:155], v0 offset:4096
	ds_read_b128 v[156:159], v0 offset:6144
	s_waitcnt lgkmcnt(1)
	v_mfma_f32_16x16x32_bf16 v[108:111], v[136:139], v[152:155], v[108:111]
	v_mfma_f32_16x16x32_bf16 v[104:107], v[144:147], v[152:155], v[104:107]
	v_mfma_f32_16x16x32_bf16 v[100:103], v[164:167], v[152:155], v[100:103]
	v_mfma_f32_16x16x32_bf16 v[96:99], v[168:171], v[152:155], v[96:99]
	s_waitcnt lgkmcnt(0)
	v_mfma_f32_16x16x32_bf16 v[92:95], v[136:139], v[156:159], v[92:95]
	v_mfma_f32_16x16x32_bf16 v[88:91], v[144:147], v[156:159], v[88:91]
	v_mfma_f32_16x16x32_bf16 v[84:87], v[164:167], v[156:159], v[84:87]
	v_mfma_f32_16x16x32_bf16 v[80:83], v[168:171], v[156:159], v[80:83]
	ds_read_b128 v[152:155], v0 offset:8192
	ds_read_b128 v[156:159], v0 offset:10240
	s_waitcnt lgkmcnt(1)
	v_mfma_f32_16x16x32_bf16 v[68:71], v[136:139], v[152:155], v[68:71]
	v_mfma_f32_16x16x32_bf16 v[64:67], v[144:147], v[152:155], v[64:67]
	v_mfma_f32_16x16x32_bf16 v[60:63], v[164:167], v[152:155], v[60:63]
	v_mfma_f32_16x16x32_bf16 v[56:59], v[168:171], v[152:155], v[56:59]
	s_waitcnt lgkmcnt(0)
	v_mfma_f32_16x16x32_bf16 v[48:51], v[136:139], v[156:159], v[48:51]
	v_mfma_f32_16x16x32_bf16 v[44:47], v[144:147], v[156:159], v[44:47]
	v_mfma_f32_16x16x32_bf16 v[40:43], v[164:167], v[156:159], v[40:43]
	v_mfma_f32_16x16x32_bf16 v[36:39], v[168:171], v[156:159], v[36:39]
	ds_read_b128 v[152:155], v0 offset:12288
	ds_read_b128 v[156:159], v0 offset:14336
	ds_read_b128 v[172:175], v215 offset:32768
	ds_read_b128 v[180:183], v215 offset:34816
	s_waitcnt lgkmcnt(3)
	v_mfma_f32_16x16x32_bf16 v[28:31], v[136:139], v[152:155], v[28:31]
	v_mfma_f32_16x16x32_bf16 v[24:27], v[144:147], v[152:155], v[24:27]
	v_mfma_f32_16x16x32_bf16 v[76:79], v[164:167], v[152:155], v[76:79]
	v_mfma_f32_16x16x32_bf16 v[72:75], v[168:171], v[152:155], v[72:75]
	s_waitcnt lgkmcnt(2)
	v_mfma_f32_16x16x32_bf16 v[52:55], v[136:139], v[156:159], v[52:55]
	v_mfma_f32_16x16x32_bf16 v[32:35], v[144:147], v[156:159], v[32:35]
	ds_read_b128 v[136:139], v207
	ds_read_b128 v[144:147], v207 offset:2048
	ds_read_b128 v[192:195], v215 offset:40960
	ds_read_b128 v[196:199], v215 offset:43008
	v_mfma_f32_16x16x32_bf16 v[20:23], v[164:167], v[156:159], v[20:23]
	v_mfma_f32_16x16x32_bf16 v[160:163], v[168:171], v[156:159], v[160:163]
	s_waitcnt lgkmcnt(3)
	v_mfma_f32_16x16x32_bf16 v[148:151], v[172:175], v[136:139], v[148:151]
	v_mfma_f32_16x16x32_bf16 v[140:143], v[180:183], v[136:139], v[140:143]
	s_waitcnt lgkmcnt(1)
	v_mfma_f32_16x16x32_bf16 v[132:135], v[192:195], v[136:139], v[132:135]
	s_waitcnt lgkmcnt(0)
	v_mfma_f32_16x16x32_bf16 v[128:131], v[196:199], v[136:139], v[128:131]
	v_mfma_f32_16x16x32_bf16 v[124:127], v[172:175], v[144:147], v[124:127]
	v_mfma_f32_16x16x32_bf16 v[120:123], v[180:183], v[144:147], v[120:123]
	v_mfma_f32_16x16x32_bf16 v[116:119], v[192:195], v[144:147], v[116:119]
	v_mfma_f32_16x16x32_bf16 v[112:115], v[196:199], v[144:147], v[112:115]
	ds_read_b128 v[136:139], v207 offset:4096
	ds_read_b128 v[144:147], v207 offset:6144
	s_waitcnt lgkmcnt(1)
; template <int MI, bool SWAP, bool F8 = false>
; __device__ __forceinline__ void gemm_core(const bf16_t* __restrict__ A, int lda, const bf16_t* __restrict__ B, int ldb,
;                                           int K, char* smem, f32x4 (&acc)[MI][4]) {
;     ...
;   for (int kt = 0; kt < nk; ++kt) {
;     __syncthreads();
; #pragma unroll
;     for (int i = 0; i < MI; ++i) *(u32x4*)(smem + woff + i * 4096) = ra[i];
; #pragma unroll
;     for (int i = 0; i < 4; ++i) *(u32x4*)(smem + 32768 + woff + i * 4096) = rb[i];
;     __syncthreads();
;     if (kt + 1 < nk) {
; #pragma unroll
;       for (int i = 0; i < MI; ++i) ra[i] = *(const u32x4*)(ap + (size_t)(32 * i) * lda + (kt + 1) * 64);
; #pragma unroll
;       for (int i = 0; i < 4; ++i) rb[i] = *(const u32x4*)(bp + (size_t)(32 * i) * ldb + (kt + 1) * 64);
;     }
;     if (F8) {
;       const int c0 = (g ^ (li & 7)) << 4, c1 = ((4 + g) ^ (li & 7)) << 4;
;       i32x8 wf8[4];
; #pragma unroll
;       for (int j = 0; j < 4; ++j) {
;         const char* rp = smem + wrow + ((j & 1) * 16 + (j >> 1) * 64) * 128;
;         const u32x4 lo = *(const u32x4*)(rp + c0), hi = *(const u32x4*)(rp + c1);
;         wf8[j] = (i32x8){(int)lo.x, (int)lo.y, (int)lo.z, (int)lo.w, (int)hi.x, (int)hi.y, (int)hi.z, (int)hi.w};
;       }
; #pragma unroll
;       for (int i = 0; i < MI; ++i) {
;         const char* rp = smem + xrow + i * 2048;
;         const u32x4 lo = *(const u32x4*)(rp + c0), hi = *(const u32x4*)(rp + c1);
;         const i32x8 xf8 = {(int)lo.x, (int)lo.y, (int)lo.z, (int)lo.w, (int)hi.x, (int)hi.y, (int)hi.z, (int)hi.w};
; #pragma unroll
;         for (int j = 0; j < 4; ++j)
;           acc[i][j] = __builtin_amdgcn_mfma_scale_f32_16x16x128_f8f6f4(wf8[j], xf8, acc[i][j], 0, 0, 0, 0x77777777, 0, 0x7f7f7f7f);
;       }
;     } else {
; #pragma unroll
;     for (int kk = 0; kk < 2; ++kk) {
;       const int ch = ((kk * 4 + g) ^ (li & 7)) << 4;
;       bf16x8 xf[MI], wf[4];
; #pragma unroll
;       for (int j = 0; j < 4; ++j) wf[j] = *(const bf16x8*)(smem + wrow + ((j & 1) * 16 + (j >> 1) * 64) * 128 + ch);
; #pragma unroll
;       for (int i = 0; i < MI; ++i) xf[i] = *(const bf16x8*)(smem + xrow + i * 2048 + ch);
; #pragma unroll
;       for (int i = 0; i < MI; ++i)
; #pragma unroll
;         for (int j = 0; j < 4; ++j) {
	v_mfma_f32_16x16x32_bf16 v[108:111], v[172:175], v[136:139], v[108:111]
	ds_read_b128 v[152:155], v207 offset:12288
	ds_read_b128 v[216:219], v207 offset:14336
	v_mfma_f32_16x16x32_bf16 v[104:107], v[180:183], v[136:139], v[104:107]
	v_mfma_f32_16x16x32_bf16 v[100:103], v[192:195], v[136:139], v[100:103]
	v_mfma_f32_16x16x32_bf16 v[96:99], v[196:199], v[136:139], v[96:99]
	ds_read_b128 v[136:139], v207 offset:8192
	s_waitcnt lgkmcnt(3)
	v_mfma_f32_16x16x32_bf16 v[92:95], v[172:175], v[144:147], v[92:95]
	v_mfma_f32_16x16x32_bf16 v[88:91], v[180:183], v[144:147], v[88:91]
	v_mfma_f32_16x16x32_bf16 v[84:87], v[192:195], v[144:147], v[84:87]
	v_mfma_f32_16x16x32_bf16 v[80:83], v[196:199], v[144:147], v[80:83]
	ds_read_b128 v[144:147], v207 offset:10240
	s_waitcnt lgkmcnt(1)
	v_mfma_f32_16x16x32_bf16 v[68:71], v[172:175], v[136:139], v[68:71]
	v_mfma_f32_16x16x32_bf16 v[64:67], v[180:183], v[136:139], v[64:67]
	v_mfma_f32_16x16x32_bf16 v[60:63], v[192:195], v[136:139], v[60:63]
	v_mfma_f32_16x16x32_bf16 v[56:59], v[196:199], v[136:139], v[56:59]
	s_waitcnt lgkmcnt(0)
	v_mfma_f32_16x16x32_bf16 v[48:51], v[172:175], v[144:147], v[48:51]
	v_mfma_f32_16x16x32_bf16 v[44:47], v[180:183], v[144:147], v[44:47]
	v_mfma_f32_16x16x32_bf16 v[40:43], v[192:195], v[144:147], v[40:43]
	v_mfma_f32_16x16x32_bf16 v[36:39], v[196:199], v[144:147], v[36:39]
	v_mfma_f32_16x16x32_bf16 v[28:31], v[172:175], v[152:155], v[28:31]
	v_mfma_f32_16x16x32_bf16 v[24:27], v[180:183], v[152:155], v[24:27]
	v_mfma_f32_16x16x32_bf16 v[76:79], v[192:195], v[152:155], v[76:79]
	v_mfma_f32_16x16x32_bf16 v[72:75], v[196:199], v[152:155], v[72:75]
	v_mfma_f32_16x16x32_bf16 v[52:55], v[172:175], v[216:219], v[52:55]
	v_mfma_f32_16x16x32_bf16 v[32:35], v[180:183], v[216:219], v[32:35]
	v_mfma_f32_16x16x32_bf16 v[20:23], v[192:195], v[216:219], v[20:23]
	v_mfma_f32_16x16x32_bf16 v[160:163], v[196:199], v[216:219], v[160:163]
	s_add_u32 s26, s26, 0x80
	s_addc_u32 s27, s27, 0
	s_cmpk_lg_i32 s26, 0x780
	s_cbranch_scc1 .LBB0_301
	s_barrier
	s_setprio 3
	s_mov_b32 m0, s62
	s_nop 0
	global_load_lds_dwordx4 v252, s[56:57]
	s_add_u32 m0, s62, 0x1000
	s_nop 0
	global_load_lds_dwordx4 v253, s[56:57]
	s_add_u32 s56, s56, 0x20000
	s_addc_u32 s57, s57, 0
	s_add_u32 m0, s62, 0x2000
	s_nop 0
	global_load_lds_dwordx4 v252, s[56:57]
	s_add_u32 m0, s62, 0x3000
	s_nop 0
	global_load_lds_dwordx4 v253, s[56:57]
	s_add_u32 s56, s56, 0x20000
	s_addc_u32 s57, s57, 0
	s_add_u32 m0, s62, 0x4000
	s_nop 0
	global_load_lds_dwordx4 v252, s[56:57]
	s_add_u32 m0, s62, 0x5000
	s_nop 0
	global_load_lds_dwordx4 v253, s[56:57]
	s_add_u32 s56, s56, 0x20000
	s_addc_u32 s57, s57, 0
	s_add_u32 m0, s62, 0x6000
	s_nop 0
	global_load_lds_dwordx4 v252, s[56:57]
	s_add_u32 m0, s62, 0x7000
	s_nop 0
	global_load_lds_dwordx4 v253, s[56:57]
	s_sub_u32 s56, s56, 0x60000
	s_subb_u32 s57, s57, 0
	s_add_u32 m0, s62, 0x8000
	s_nop 0
	global_load_lds_dwordx4 v252, s[58:59]
	s_add_u32 m0, s62, 0x9000
	s_nop 0
	global_load_lds_dwordx4 v253, s[58:59]
	s_add_u32 s58, s58, 0x20000
	s_addc_u32 s59, s59, 0
	s_add_u32 m0, s62, 0xa000
	s_nop 0
	global_load_lds_dwordx4 v252, s[58:59]
	s_add_u32 m0, s62, 0xb000
	s_nop 0
	global_load_lds_dwordx4 v253, s[58:59]
	s_sub_u32 s58, s58, 0x20000
	s_subb_u32 s59, s59, 0
	s_setprio 0
	s_waitcnt vmcnt(0)
	s_barrier
	v_bfe_u32 v12, v208, 4, 1
	v_mul_u32_u24_e32 v12, 24, v12
	v_mov_b32_e32 v13, 0
	ds_read_b128 v[136:139], v213 offset:32768
	ds_read_b128 v[144:147], v213 offset:34816
	ds_read_b128 v[152:155], v0
	ds_read_b128 v[156:159], v0 offset:2048
	ds_read_b128 v[164:167], v213 offset:40960
	ds_read_b128 v[168:171], v213 offset:43008
	s_waitcnt lgkmcnt(3)
	v_mfma_f32_16x16x32_bf16 v[148:151], v[136:139], v[152:155], v[148:151]
	s_cmp_eq_u32 s42, 6
	s_cselect_b64 s[26:27], -1, 0
	s_cmp_lg_u32 s42, 6
	v_mfma_f32_16x16x32_bf16 v[140:143], v[144:147], v[152:155], v[140:143]
	s_cselect_b64 s[30:31], -1, 0
	s_and_b64 vcc, exec, s[26:27]
	s_waitcnt lgkmcnt(1)
	v_mfma_f32_16x16x32_bf16 v[132:135], v[164:167], v[152:155], v[132:135]
	s_waitcnt lgkmcnt(0)
	v_mfma_f32_16x16x32_bf16 v[128:131], v[168:171], v[152:155], v[128:131]
	v_mfma_f32_16x16x32_bf16 v[172:175], v[136:139], v[156:159], v[124:127]
	s_nop 2
	ds_read_b128 v[124:127], v0 offset:4096
	ds_read_b128 v[152:155], v0 offset:6144
	s_waitcnt lgkmcnt(0)
	v_mfma_f32_16x16x32_bf16 v[176:179], v[164:167], v[152:155], v[84:87]
	v_mfma_f32_16x16x32_bf16 v[180:183], v[168:171], v[152:155], v[80:83]
	s_nop 2
	ds_read_b128 v[80:83], v0 offset:8192
	ds_read_b128 v[84:87], v0 offset:10240
	s_waitcnt lgkmcnt(1)
	v_mfma_f32_16x16x32_bf16 v[196:199], v[168:171], v[80:83], v[56:59]
	s_waitcnt lgkmcnt(0)
	v_mfma_f32_16x16x32_bf16 v[200:203], v[136:139], v[84:87], v[48:51]
	s_nop 2
	ds_read_b128 v[48:51], v0 offset:12288
	ds_read_b128 v[56:59], v0 offset:14336
	v_mfma_f32_16x16x32_bf16 v[116:119], v[164:167], v[156:159], v[116:119]
	v_mfma_f32_16x16x32_bf16 v[112:115], v[168:171], v[156:159], v[112:115]
	v_mfma_f32_16x16x32_bf16 v[100:103], v[164:167], v[124:127], v[100:103]
	v_mfma_f32_16x16x32_bf16 v[96:99], v[168:171], v[124:127], v[96:99]
	v_mfma_f32_16x16x32_bf16 v[192:195], v[164:167], v[80:83], v[60:63]
	v_mfma_f32_16x16x32_bf16 v[40:43], v[164:167], v[84:87], v[40:43]
	v_mfma_f32_16x16x32_bf16 v[36:39], v[168:171], v[84:87], v[36:39]
	s_waitcnt lgkmcnt(1)
	v_mfma_f32_16x16x32_bf16 v[28:31], v[136:139], v[48:51], v[28:31]
	v_mfma_f32_16x16x32_bf16 v[24:27], v[144:147], v[48:51], v[24:27]
	v_mfma_f32_16x16x32_bf16 v[76:79], v[164:167], v[48:51], v[76:79]
	v_mfma_f32_16x16x32_bf16 v[216:219], v[168:171], v[48:51], v[72:75]
	s_waitcnt lgkmcnt(0)
; template <int MI, bool SWAP, bool F8 = false>
; __device__ __forceinline__ void gemm_core(const bf16_t* __restrict__ A, int lda, const bf16_t* __restrict__ B, int ldb,
;                                           int K, char* smem, f32x4 (&acc)[MI][4]) {
;     ...
;     for (int kk = 0; kk < 2; ++kk) {
;       const int ch = ((kk * 4 + g) ^ (li & 7)) << 4;
;       bf16x8 xf[MI], wf[4];
; #pragma unroll
;       for (int j = 0; j < 4; ++j) wf[j] = *(const bf16x8*)(smem + wrow + ((j & 1) * 16 + (j >> 1) * 64) * 128 + ch);
; #pragma unroll
;       for (int i = 0; i < MI; ++i) xf[i] = *(const bf16x8*)(smem + xrow + i * 2048 + ch);
; #pragma unroll
;       for (int i = 0; i < MI; ++i)
; #pragma unroll
;         for (int j = 0; j < 4; ++j) {
;           if (SWAP) acc[i][j] = __builtin_amdgcn_mfma_f32_16x16x32_bf16(xf[i], wf[j], acc[i][j], 0, 0, 0);
;           else acc[i][j] = __builtin_amdgcn_mfma_f32_16x16x32_bf16(wf[j], xf[i], acc[i][j], 0, 0, 0);
;         }
; __device__ void even_in_tile(const P& p, int li_even, int tm, int tn, char* smem) {
;     ...
;   if (seg != 6) {
;     const float* ctab = (const float*)(ws + OFF_COS);
;     const float* stab = (const float*)(ws + OFF_SIN);
; #pragma unroll
;     for (int i = 0; i < MI; ++i) {
;       const int s = s0 + MROW(i);
; #pragma unroll
;       for (int jj = 0; jj < 2; ++jj) {
;         const int d = wn * 32 + jj * 16 + g * 4;
;         const f32x4 c = *(const f32x4*)(ctab + s * 64 + d);
;         const f32x4 sn = *(const f32x4*)(stab + s * 64 + d);
	v_mfma_f32_16x16x32_bf16 v[224:227], v[144:147], v[56:59], v[32:35]
	v_mfma_f32_16x16x32_bf16 v[20:23], v[164:167], v[56:59], v[20:23]
	ds_read_b128 v[164:167], v215 offset:32768
	v_mfma_f32_16x16x32_bf16 v[160:163], v[168:171], v[56:59], v[160:163]
	ds_read_b128 v[168:171], v215 offset:34816
	ds_read_b128 v[32:35], v207
	ds_read_b128 v[48:51], v207 offset:2048
	ds_read_b128 v[228:231], v215 offset:40960
	ds_read_b128 v[232:235], v215 offset:43008
	v_mfma_f32_16x16x32_bf16 v[120:123], v[144:147], v[156:159], v[120:123]
	v_mov_b32_e32 v215, v208
	v_mfma_f32_16x16x32_bf16 v[108:111], v[136:139], v[124:127], v[108:111]
	v_mfma_f32_16x16x32_bf16 v[104:107], v[144:147], v[124:127], v[104:107]
	v_mfma_f32_16x16x32_bf16 v[92:95], v[136:139], v[152:155], v[92:95]
	v_mfma_f32_16x16x32_bf16 v[156:159], v[144:147], v[152:155], v[88:91]
	v_mfma_f32_16x16x32_bf16 v[184:187], v[136:139], v[80:83], v[68:71]
	v_mfma_f32_16x16x32_bf16 v[188:191], v[144:147], v[80:83], v[64:67]
	v_mfma_f32_16x16x32_bf16 v[44:47], v[144:147], v[84:87], v[44:47]
	v_mfma_f32_16x16x32_bf16 v[220:223], v[136:139], v[56:59], v[52:55]
	s_waitcnt lgkmcnt(3)
	v_mfma_f32_16x16x32_bf16 v[124:127], v[164:167], v[32:35], v[148:151]
	v_mfma_f32_16x16x32_bf16 v[150:153], v[168:171], v[32:35], v[140:143]
	s_waitcnt lgkmcnt(1)
	v_mfma_f32_16x16x32_bf16 v[88:91], v[228:231], v[32:35], v[132:135]
	s_waitcnt lgkmcnt(0)
	v_mfma_f32_16x16x32_bf16 v[84:87], v[232:235], v[32:35], v[128:131]
	v_mfma_f32_16x16x32_bf16 v[134:137], v[164:167], v[48:51], v[172:175]
	v_mfma_f32_16x16x32_bf16 v[138:141], v[168:171], v[48:51], v[120:123]
	v_mfma_f32_16x16x32_bf16 v[80:83], v[228:231], v[48:51], v[116:119]
	v_mfma_f32_16x16x32_bf16 v[72:75], v[232:235], v[48:51], v[112:115]
	ds_read_b128 v[32:35], v207 offset:4096
	ds_read_b128 v[48:51], v207 offset:6144
	s_waitcnt lgkmcnt(1)
	v_mfma_f32_16x16x32_bf16 v[142:145], v[164:167], v[32:35], v[108:111]
	v_mfma_f32_16x16x32_bf16 v[146:149], v[168:171], v[32:35], v[104:107]
	v_mfma_f32_16x16x32_bf16 v[68:71], v[228:231], v[32:35], v[100:103]
	v_mfma_f32_16x16x32_bf16 v[64:67], v[232:235], v[32:35], v[96:99]
	s_waitcnt lgkmcnt(0)
	v_mfma_f32_16x16x32_bf16 v[128:131], v[164:167], v[48:51], v[92:95]
	ds_read_b128 v[32:35], v207 offset:8192
	s_nop 1
	ds_read_b128 v[92:95], v207 offset:10240
	v_mfma_f32_16x16x32_bf16 v[120:123], v[168:171], v[48:51], v[156:159]
	v_mfma_f32_16x16x32_bf16 v[60:63], v[228:231], v[48:51], v[176:179]
	v_mfma_f32_16x16x32_bf16 v[56:59], v[232:235], v[48:51], v[180:183]
	s_waitcnt lgkmcnt(1)
	v_mfma_f32_16x16x32_bf16 v[112:115], v[164:167], v[32:35], v[184:187]
	v_mfma_f32_16x16x32_bf16 v[108:111], v[168:171], v[32:35], v[188:191]
	v_mfma_f32_16x16x32_bf16 v[52:55], v[228:231], v[32:35], v[192:195]
	v_mfma_f32_16x16x32_bf16 v[48:51], v[232:235], v[32:35], v[196:199]
	ds_read_b128 v[32:35], v207 offset:12288
	ds_read_b128 v[116:119], v207 offset:14336
	s_waitcnt lgkmcnt(2)
	v_mfma_f32_16x16x32_bf16 v[104:107], v[164:167], v[92:95], v[200:203]
	v_and_b32_e32 v213, 15, v215
	v_mfma_f32_16x16x32_bf16 v[100:103], v[168:171], v[92:95], v[44:47]
	v_mfma_f32_16x16x32_bf16 v[44:47], v[228:231], v[92:95], v[40:43]
	v_mfma_f32_16x16x32_bf16 v[40:43], v[232:235], v[92:95], v[36:39]
	s_waitcnt lgkmcnt(1)
	v_mfma_f32_16x16x32_bf16 v[96:99], v[164:167], v[32:35], v[28:31]
	v_mfma_f32_16x16x32_bf16 v[92:95], v[168:171], v[32:35], v[24:27]
	v_mfma_f32_16x16x32_bf16 v[36:39], v[228:231], v[32:35], v[76:79]
	v_mfma_f32_16x16x32_bf16 v[32:35], v[232:235], v[32:35], v[216:219]
	s_waitcnt lgkmcnt(0)
	v_mfma_f32_16x16x32_bf16 v[76:79], v[164:167], v[116:119], v[220:223]
	s_nop 0
	v_bfe_u32 v218, v215, 6, 1
	v_bfe_u32 v219, v215, 4, 2
	v_mfma_f32_16x16x32_bf16 v[28:31], v[168:171], v[116:119], v[224:227]
	v_mfma_f32_16x16x32_bf16 v[24:27], v[228:231], v[116:119], v[20:23]
	v_mfma_f32_16x16x32_bf16 v[20:23], v[232:235], v[116:119], v[160:163]
	s_cbranch_vccnz .LBB0_315
	v_and_b32_e32 v0, 0x3ffff80, v215
	v_add_u32_e32 v0, s41, v0
	s_add_u32 s34, s45, 0x4000
	v_or_b32_e32 v0, v0, v213
	s_addc_u32 s35, s48, 0
	v_lshlrev_b32_e32 v2, 6, v0
	s_add_u32 s36, s45, 0x104000
	v_ashrrev_i32_e32 v3, 31, v2
	s_addc_u32 s37, s48, 0
	v_lshlrev_b64 v[116:117], 2, v[2:3]
	v_lshlrev_b32_e32 v0, 4, v219
	v_lshl_add_u64 v[118:119], s[34:35], 0, v[116:117]
	v_lshl_add_u64 v[116:117], s[36:37], 0, v[116:117]
	v_lshl_or_b32 v0, v218, 7, v0
	v_lshl_add_u64 v[132:133], v[118:119], 0, v[0:1]
	v_lshl_add_u64 v[162:163], v[116:117], 0, v[0:1]
	v_lshl_add_u32 v236, v2, 2, v0
	global_load_dwordx4 v[164:167], v236, s[34:35]
	global_load_dwordx4 v[168:171], v236, s[36:37]
	global_load_dwordx4 v[172:175], v236, s[34:35] offset:64
	global_load_dwordx4 v[176:179], v236, s[36:37] offset:64
	v_add_u32_e32 v236, 0x1000, v236
	global_load_dwordx4 v[180:183], v236, s[34:35]
	global_load_dwordx4 v[184:187], v236, s[36:37]
	global_load_dwordx4 v[188:191], v236, s[34:35] offset:64
	global_load_dwordx4 v[192:195], v236, s[36:37] offset:64
	v_add_u32_e32 v236, 0x1000, v236
	global_load_dwordx4 v[196:199], v236, s[34:35]
	global_load_dwordx4 v[200:203], v236, s[36:37]
	global_load_dwordx4 v[204:207], v236, s[34:35] offset:64
	global_load_dwordx4 v[220:223], v236, s[36:37] offset:64
	v_add_u32_e32 v236, 0x1000, v236
	global_load_dwordx4 v[224:227], v236, s[34:35]
	global_load_dwordx4 v[228:231], v236, s[36:37]
	global_load_dwordx4 v[232:235], v236, s[34:35] offset:64
	global_load_dwordx4 v[4:7], v236, s[36:37] offset:64
	v_add_u32_e32 v236, 0x1000, v236
	s_waitcnt vmcnt(14)
; __device__ void even_in_tile(const P& p, int li_even, int tm, int tn, char* smem) {
;     ...
; #pragma unroll
;     for (int i = 0; i < MI; ++i) {
;       const int s = s0 + MROW(i);
; #pragma unroll
;       for (int jj = 0; jj < 2; ++jj) {
;         const int d = wn * 32 + jj * 16 + g * 4;
;         const f32x4 c = *(const f32x4*)(ctab + s * 64 + d);
;         const f32x4 sn = *(const f32x4*)(stab + s * 64 + d);
; #pragma unroll
;         for (int r = 0; r < 4; ++r) {
;           const float a = acc[i][jj][r], bb = acc[i][jj + 2][r];
;           acc[i][jj][r] = a * c[r] - bb * sn[r];
;           acc[i][jj + 2][r] = bb * c[r] + a * sn[r];
;         }
;       }
;     }
	v_mov_b32_e32 v154, v164
	v_mov_b32_e32 v155, v165
	v_mov_b32_e32 v156, v166
	v_mov_b32_e32 v157, v167
	v_mov_b32_e32 v158, v168
	v_mov_b32_e32 v159, v169
	v_mov_b32_e32 v160, v170
	v_mov_b32_e32 v161, v171
	global_load_dwordx4 v[164:167], v236, s[34:35]
	global_load_dwordx4 v[168:171], v236, s[36:37]
	v_pk_mul_f32 v[116:117], v[88:89], v[158:159]
	v_pk_mul_f32 v[118:119], v[124:125], v[158:159]
	v_pk_fma_f32 v[116:117], v[124:125], v[154:155], v[116:117] neg_lo:[0,0,1] neg_hi:[0,0,1]
	v_pk_fma_f32 v[88:89], v[88:89], v[154:155], v[118:119]
	v_mul_f32_e32 v118, v126, v156
	v_mul_f32_e32 v124, v90, v160
	v_mul_f32_e32 v154, v90, v156
	v_mul_f32_e32 v156, v126, v160
	v_mov_b32_e32 v90, v127
	v_mov_b32_e32 v160, v157
	v_mov_b32_e32 v126, v91
	v_pk_mul_f32 v[158:159], v[90:91], v[160:161]
	v_pk_mul_f32 v[90:91], v[126:127], v[160:161]
	v_mov_b32_e32 v119, v158
	v_mov_b32_e32 v155, v90
	v_mov_b32_e32 v157, v91
	v_mov_b32_e32 v125, v159
	v_pk_add_f32 v[90:91], v[154:155], v[156:157]
	v_pk_add_f32 v[118:119], v[118:119], v[124:125] neg_lo:[0,1] neg_hi:[0,1]
	s_waitcnt vmcnt(14)
	v_mov_b32_e32 v154, v172
	v_mov_b32_e32 v155, v173
	v_mov_b32_e32 v156, v174
	v_mov_b32_e32 v157, v175
	v_mov_b32_e32 v158, v176
	v_mov_b32_e32 v159, v177
	v_mov_b32_e32 v160, v178
	v_mov_b32_e32 v161, v179
	global_load_dwordx4 v[172:175], v236, s[34:35] offset:64
	global_load_dwordx4 v[176:179], v236, s[36:37] offset:64
	v_add_u32_e32 v236, 0x1000, v236
	v_pk_mul_f32 v[124:125], v[84:85], v[158:159]
	v_pk_mul_f32 v[126:127], v[150:151], v[158:159]
	v_pk_fma_f32 v[124:125], v[150:151], v[154:155], v[124:125] neg_lo:[0,0,1] neg_hi:[0,0,1]
	v_pk_fma_f32 v[84:85], v[84:85], v[154:155], v[126:127]
	v_mul_f32_e32 v132, v86, v160
	v_mul_f32_e32 v150, v86, v156
	v_mul_f32_e32 v154, v152, v160
	v_mov_b32_e32 v86, v153
	v_mov_b32_e32 v160, v157
	v_mul_f32_e32 v126, v152, v156
	v_pk_mul_f32 v[156:157], v[86:87], v[160:161]
	v_mov_b32_e32 v152, v87
	v_mov_b32_e32 v127, v156
	v_mov_b32_e32 v133, v157
	v_pk_add_f32 v[126:127], v[126:127], v[132:133] neg_lo:[0,1] neg_hi:[0,1]
	v_or_b32_e32 v132, 0x400, v2
	v_pk_mul_f32 v[86:87], v[152:153], v[160:161]
	v_ashrrev_i32_e32 v133, 31, v132
	v_mov_b32_e32 v151, v86
	v_mov_b32_e32 v155, v87
	v_lshlrev_b64 v[132:133], 2, v[132:133]
	v_pk_add_f32 v[86:87], v[150:151], v[154:155]
	v_lshl_add_u64 v[150:151], s[34:35], 0, v[132:133]
	v_lshl_add_u64 v[132:133], s[36:37], 0, v[132:133]
	v_lshl_add_u64 v[158:159], v[150:151], 0, v[0:1]
	v_lshl_add_u64 v[160:161], v[132:133], 0, v[0:1]
	s_waitcnt vmcnt(14)
	v_mov_b32_e32 v150, v180
	v_mov_b32_e32 v151, v181
	v_mov_b32_e32 v152, v182
	v_mov_b32_e32 v153, v183
	v_mov_b32_e32 v154, v184
	v_mov_b32_e32 v155, v185
	v_mov_b32_e32 v156, v186
	v_mov_b32_e32 v157, v187
	global_load_dwordx4 v[180:183], v236, s[34:35]
	global_load_dwordx4 v[184:187], v236, s[36:37]
	v_pk_mul_f32 v[132:133], v[80:81], v[154:155]
	s_nop 0
	v_pk_fma_f32 v[132:133], v[134:135], v[150:151], v[132:133] neg_lo:[0,0,1] neg_hi:[0,0,1]
	v_pk_mul_f32 v[134:135], v[134:135], v[154:155]
	v_mul_f32_e32 v154, v136, v156
	v_pk_fma_f32 v[80:81], v[80:81], v[150:151], v[134:135]
	v_mul_f32_e32 v134, v136, v152
	v_mul_f32_e32 v150, v82, v156
	v_mul_f32_e32 v152, v82, v152
	v_mov_b32_e32 v82, v137
	v_mov_b32_e32 v156, v153
	v_mov_b32_e32 v136, v83
	v_pk_mul_f32 v[162:163], v[82:83], v[156:157]
	v_pk_mul_f32 v[82:83], v[136:137], v[156:157]
	v_mov_b32_e32 v135, v162
	v_mov_b32_e32 v151, v163
	v_mov_b32_e32 v153, v82
	v_mov_b32_e32 v155, v83
	v_pk_add_f32 v[134:135], v[134:135], v[150:151] neg_lo:[0,1] neg_hi:[0,1]
	v_pk_add_f32 v[82:83], v[152:153], v[154:155]
	s_waitcnt vmcnt(14)
	v_mov_b32_e32 v150, v188
	v_mov_b32_e32 v151, v189
	v_mov_b32_e32 v152, v190
	v_mov_b32_e32 v153, v191
	v_mov_b32_e32 v154, v192
	v_mov_b32_e32 v155, v193
	v_mov_b32_e32 v156, v194
	v_mov_b32_e32 v157, v195
	global_load_dwordx4 v[188:191], v236, s[34:35] offset:64
	global_load_dwordx4 v[192:195], v236, s[36:37] offset:64
	v_add_u32_e32 v236, 0x1000, v236
	v_pk_mul_f32 v[136:137], v[72:73], v[154:155]
	s_nop 0
	v_pk_fma_f32 v[136:137], v[138:139], v[150:151], v[136:137] neg_lo:[0,0,1] neg_hi:[0,0,1]
	v_pk_mul_f32 v[138:139], v[138:139], v[154:155]
	v_mul_f32_e32 v154, v140, v156
	v_pk_fma_f32 v[72:73], v[72:73], v[150:151], v[138:139]
	v_mul_f32_e32 v138, v140, v152
	v_mul_f32_e32 v150, v74, v156
	v_mul_f32_e32 v152, v74, v152
	v_mov_b32_e32 v74, v141
	v_mov_b32_e32 v156, v153
	v_mov_b32_e32 v140, v75
	v_pk_mul_f32 v[158:159], v[74:75], v[156:157]
	v_pk_mul_f32 v[74:75], v[140:141], v[156:157]
	v_or_b32_e32 v140, 0x800, v2
	v_ashrrev_i32_e32 v141, 31, v140
	v_mov_b32_e32 v139, v158
	v_mov_b32_e32 v151, v159
	v_lshlrev_b64 v[140:141], 2, v[140:141]
	v_pk_add_f32 v[138:139], v[138:139], v[150:151] neg_lo:[0,1] neg_hi:[0,1]
	v_lshl_add_u64 v[150:151], s[34:35], 0, v[140:141]
	v_lshl_add_u64 v[140:141], s[36:37], 0, v[140:141]
	v_mov_b32_e32 v153, v74
	v_mov_b32_e32 v155, v75
	v_lshl_add_u64 v[158:159], v[150:151], 0, v[0:1]
	v_lshl_add_u64 v[160:161], v[140:141], 0, v[0:1]
	v_pk_add_f32 v[74:75], v[152:153], v[154:155]
	s_waitcnt vmcnt(14)
; __device__ void even_in_tile(const P& p, int li_even, int tm, int tn, char* smem) {
;     ...
; #pragma unroll
;     for (int i = 0; i < MI; ++i) {
;       const int s = s0 + MROW(i);
; #pragma unroll
;       for (int jj = 0; jj < 2; ++jj) {
;         const int d = wn * 32 + jj * 16 + g * 4;
;         const f32x4 c = *(const f32x4*)(ctab + s * 64 + d);
;         const f32x4 sn = *(const f32x4*)(stab + s * 64 + d);
; #pragma unroll
;         for (int r = 0; r < 4; ++r) {
;           const float a = acc[i][jj][r], bb = acc[i][jj + 2][r];
;           acc[i][jj][r] = a * c[r] - bb * sn[r];
;           acc[i][jj + 2][r] = bb * c[r] + a * sn[r];
;         }
;       }
;     }
	v_mov_b32_e32 v150, v196
	v_mov_b32_e32 v151, v197
	v_mov_b32_e32 v152, v198
	v_mov_b32_e32 v153, v199
	v_mov_b32_e32 v154, v200
	v_mov_b32_e32 v155, v201
	v_mov_b32_e32 v156, v202
	v_mov_b32_e32 v157, v203
	global_load_dwordx4 v[196:199], v236, s[34:35]
	global_load_dwordx4 v[200:203], v236, s[36:37]
	v_pk_mul_f32 v[140:141], v[68:69], v[154:155]
	s_nop 0
	v_pk_fma_f32 v[140:141], v[142:143], v[150:151], v[140:141] neg_lo:[0,0,1] neg_hi:[0,0,1]
	v_pk_mul_f32 v[142:143], v[142:143], v[154:155]
	v_mul_f32_e32 v154, v144, v156
	v_pk_fma_f32 v[68:69], v[68:69], v[150:151], v[142:143]
	v_mul_f32_e32 v142, v144, v152
	v_mul_f32_e32 v150, v70, v156
	v_mul_f32_e32 v152, v70, v152
	v_mov_b32_e32 v70, v145
	v_mov_b32_e32 v156, v153
	v_mov_b32_e32 v144, v71
	v_pk_mul_f32 v[162:163], v[70:71], v[156:157]
	v_pk_mul_f32 v[70:71], v[144:145], v[156:157]
	v_mov_b32_e32 v143, v162
	v_mov_b32_e32 v151, v163
	v_mov_b32_e32 v153, v70
	v_mov_b32_e32 v155, v71
	v_pk_add_f32 v[142:143], v[142:143], v[150:151] neg_lo:[0,1] neg_hi:[0,1]
	v_pk_add_f32 v[70:71], v[152:153], v[154:155]
	s_waitcnt vmcnt(14)
	v_mov_b32_e32 v150, v204
	v_mov_b32_e32 v151, v205
	v_mov_b32_e32 v152, v206
	v_mov_b32_e32 v153, v207
	v_mov_b32_e32 v154, v220
	v_mov_b32_e32 v155, v221
	v_mov_b32_e32 v156, v222
	v_mov_b32_e32 v157, v223
	global_load_dwordx4 v[204:207], v236, s[34:35] offset:64
	global_load_dwordx4 v[220:223], v236, s[36:37] offset:64
	v_add_u32_e32 v236, 0x1000, v236
	v_pk_mul_f32 v[144:145], v[64:65], v[154:155]
	s_nop 0
	v_pk_fma_f32 v[144:145], v[146:147], v[150:151], v[144:145] neg_lo:[0,0,1] neg_hi:[0,0,1]
	v_pk_mul_f32 v[146:147], v[146:147], v[154:155]
	v_mul_f32_e32 v154, v148, v156
	v_pk_fma_f32 v[64:65], v[64:65], v[150:151], v[146:147]
	v_mul_f32_e32 v146, v148, v152
	v_mul_f32_e32 v150, v66, v156
	v_mul_f32_e32 v152, v66, v152
	v_mov_b32_e32 v66, v149
	v_mov_b32_e32 v156, v153
	v_mov_b32_e32 v148, v67
	v_pk_mul_f32 v[158:159], v[66:67], v[156:157]
	v_pk_mul_f32 v[66:67], v[148:149], v[156:157]
	v_or_b32_e32 v148, 0xc00, v2
	v_ashrrev_i32_e32 v149, 31, v148
	v_mov_b32_e32 v147, v158
	v_mov_b32_e32 v151, v159
	v_lshlrev_b64 v[148:149], 2, v[148:149]
	v_pk_add_f32 v[146:147], v[146:147], v[150:151] neg_lo:[0,1] neg_hi:[0,1]
	v_lshl_add_u64 v[150:151], s[34:35], 0, v[148:149]
	v_lshl_add_u64 v[148:149], s[36:37], 0, v[148:149]
	v_mov_b32_e32 v153, v66
	v_mov_b32_e32 v155, v67
	v_lshl_add_u64 v[158:159], v[150:151], 0, v[0:1]
	v_lshl_add_u64 v[160:161], v[148:149], 0, v[0:1]
	v_pk_add_f32 v[66:67], v[152:153], v[154:155]
	s_waitcnt vmcnt(14)
	v_mov_b32_e32 v150, v224
	v_mov_b32_e32 v151, v225
	v_mov_b32_e32 v152, v226
	v_mov_b32_e32 v153, v227
	v_mov_b32_e32 v154, v228
	v_mov_b32_e32 v155, v229
	v_mov_b32_e32 v156, v230
	v_mov_b32_e32 v157, v231
	global_load_dwordx4 v[224:227], v236, s[34:35]
	global_load_dwordx4 v[228:231], v236, s[36:37]
	v_pk_mul_f32 v[148:149], v[60:61], v[154:155]
	s_nop 0
	v_pk_fma_f32 v[148:149], v[128:129], v[150:151], v[148:149] neg_lo:[0,0,1] neg_hi:[0,0,1]
	v_pk_mul_f32 v[128:129], v[128:129], v[154:155]
	v_mul_f32_e32 v154, v130, v156
	v_pk_fma_f32 v[60:61], v[60:61], v[150:151], v[128:129]
	v_mul_f32_e32 v128, v130, v152
	v_mul_f32_e32 v150, v62, v156
	v_mul_f32_e32 v152, v62, v152
	v_mov_b32_e32 v62, v131
	v_mov_b32_e32 v156, v153
	v_mov_b32_e32 v130, v63
	v_pk_mul_f32 v[162:163], v[62:63], v[156:157]
	v_pk_mul_f32 v[62:63], v[130:131], v[156:157]
	v_mov_b32_e32 v129, v162
	v_mov_b32_e32 v153, v62
	v_mov_b32_e32 v155, v63
	v_pk_add_f32 v[62:63], v[152:153], v[154:155]
	s_nop 0
	v_mov_b32_e32 v151, v163
	v_pk_add_f32 v[150:151], v[128:129], v[150:151] neg_lo:[0,1] neg_hi:[0,1]
	s_waitcnt vmcnt(14)
	v_mov_b32_e32 v152, v232
	v_mov_b32_e32 v153, v233
	v_mov_b32_e32 v154, v234
	v_mov_b32_e32 v155, v235
	v_mov_b32_e32 v156, v4
	v_mov_b32_e32 v157, v5
	v_mov_b32_e32 v158, v6
	v_mov_b32_e32 v159, v7
	global_load_dwordx4 v[232:235], v236, s[34:35] offset:64
	global_load_dwordx4 v[4:7], v236, s[36:37] offset:64
	v_pk_mul_f32 v[128:129], v[56:57], v[156:157]
	s_nop 0
	v_pk_fma_f32 v[128:129], v[120:121], v[152:153], v[128:129] neg_lo:[0,0,1] neg_hi:[0,0,1]
	v_pk_mul_f32 v[120:121], v[120:121], v[156:157]
	v_mul_f32_e32 v130, v58, v158
	v_pk_fma_f32 v[56:57], v[56:57], v[152:153], v[120:121]
	v_mul_f32_e32 v120, v122, v154
	v_mul_f32_e32 v152, v58, v154
	v_mul_f32_e32 v154, v122, v158
	v_mov_b32_e32 v58, v123
	v_mov_b32_e32 v158, v155
	v_pk_mul_f32 v[156:157], v[58:59], v[158:159]
	v_mov_b32_e32 v122, v59
	v_mov_b32_e32 v121, v156
	v_mov_b32_e32 v131, v157
	v_pk_add_f32 v[130:131], v[120:121], v[130:131] neg_lo:[0,1] neg_hi:[0,1]
	v_or_b32_e32 v120, 0x1000, v2
	v_ashrrev_i32_e32 v121, 31, v120
	v_lshlrev_b64 v[120:121], 2, v[120:121]
	v_pk_mul_f32 v[58:59], v[122:123], v[158:159]
	v_lshl_add_u64 v[122:123], s[34:35], 0, v[120:121]
	v_lshl_add_u64 v[120:121], s[36:37], 0, v[120:121]
	v_mov_b32_e32 v153, v58
	v_mov_b32_e32 v155, v59
	v_lshl_add_u64 v[160:161], v[122:123], 0, v[0:1]
	v_lshl_add_u64 v[162:163], v[120:121], 0, v[0:1]
	v_pk_add_f32 v[58:59], v[152:153], v[154:155]
	s_waitcnt vmcnt(14)
	v_mov_b32_e32 v152, v164
	v_mov_b32_e32 v153, v165
	v_mov_b32_e32 v154, v166
	v_mov_b32_e32 v155, v167
	v_mov_b32_e32 v156, v168
	v_mov_b32_e32 v157, v169
	v_mov_b32_e32 v158, v170
	v_mov_b32_e32 v159, v171
	v_pk_mul_f32 v[120:121], v[52:53], v[156:157]
	s_nop 0
	v_pk_fma_f32 v[120:121], v[112:113], v[152:153], v[120:121] neg_lo:[0,0,1] neg_hi:[0,0,1]
	v_pk_mul_f32 v[112:113], v[112:113], v[156:157]
	v_mul_f32_e32 v122, v54, v158
	v_pk_fma_f32 v[52:53], v[52:53], v[152:153], v[112:113]
	v_mul_f32_e32 v112, v114, v154
	v_mul_f32_e32 v152, v54, v154
	v_mul_f32_e32 v154, v114, v158
	v_mov_b32_e32 v54, v115
	v_mov_b32_e32 v158, v155
	v_mov_b32_e32 v114, v55
	v_pk_mul_f32 v[156:157], v[54:55], v[158:159]
	v_pk_mul_f32 v[54:55], v[114:115], v[158:159]
	v_mov_b32_e32 v113, v156
	v_mov_b32_e32 v153, v54
	v_mov_b32_e32 v155, v55
	v_mov_b32_e32 v123, v157
	v_pk_add_f32 v[54:55], v[152:153], v[154:155]
	v_pk_add_f32 v[122:123], v[112:113], v[122:123] neg_lo:[0,1] neg_hi:[0,1]
	s_waitcnt vmcnt(12)
; __device__ void even_in_tile(const P& p, int li_even, int tm, int tn, char* smem) {
;     ...
; #pragma unroll
;     for (int i = 0; i < MI; ++i) {
;       const int s = s0 + MROW(i);
; #pragma unroll
;       for (int jj = 0; jj < 2; ++jj) {
;         const int d = wn * 32 + jj * 16 + g * 4;
;         const f32x4 c = *(const f32x4*)(ctab + s * 64 + d);
;         const f32x4 sn = *(const f32x4*)(stab + s * 64 + d);
; #pragma unroll
;         for (int r = 0; r < 4; ++r) {
;           const float a = acc[i][jj][r], bb = acc[i][jj + 2][r];
;           acc[i][jj][r] = a * c[r] - bb * sn[r];
;           acc[i][jj + 2][r] = bb * c[r] + a * sn[r];
;         }
;       }
;     }
	v_mov_b32_e32 v152, v172
	v_mov_b32_e32 v153, v173
	v_mov_b32_e32 v154, v174
	v_mov_b32_e32 v155, v175
	v_mov_b32_e32 v156, v176
	v_mov_b32_e32 v157, v177
	v_mov_b32_e32 v158, v178
	v_mov_b32_e32 v159, v179
	v_pk_mul_f32 v[112:113], v[48:49], v[156:157]
	s_nop 0
	v_pk_fma_f32 v[112:113], v[108:109], v[152:153], v[112:113] neg_lo:[0,0,1] neg_hi:[0,0,1]
	v_pk_mul_f32 v[108:109], v[108:109], v[156:157]
	v_mul_f32_e32 v114, v50, v158
	v_pk_fma_f32 v[48:49], v[48:49], v[152:153], v[108:109]
	v_mul_f32_e32 v108, v110, v154
	v_mul_f32_e32 v152, v50, v154
	v_mul_f32_e32 v154, v110, v158
	v_mov_b32_e32 v50, v111
	v_mov_b32_e32 v158, v155
	v_pk_mul_f32 v[156:157], v[50:51], v[158:159]
	v_mov_b32_e32 v110, v51
	v_mov_b32_e32 v109, v156
	v_mov_b32_e32 v115, v157
	v_pk_add_f32 v[114:115], v[108:109], v[114:115] neg_lo:[0,1] neg_hi:[0,1]
	v_or_b32_e32 v108, 0x1400, v2
	v_ashrrev_i32_e32 v109, 31, v108
	v_lshlrev_b64 v[108:109], 2, v[108:109]
	v_pk_mul_f32 v[50:51], v[110:111], v[158:159]
	v_lshl_add_u64 v[110:111], s[34:35], 0, v[108:109]
	v_lshl_add_u64 v[108:109], s[36:37], 0, v[108:109]
	v_mov_b32_e32 v153, v50
	v_mov_b32_e32 v155, v51
	v_lshl_add_u64 v[160:161], v[110:111], 0, v[0:1]
	v_lshl_add_u64 v[162:163], v[108:109], 0, v[0:1]
	v_pk_add_f32 v[50:51], v[152:153], v[154:155]
	s_waitcnt vmcnt(10)
	v_mov_b32_e32 v152, v180
	v_mov_b32_e32 v153, v181
	v_mov_b32_e32 v154, v182
	v_mov_b32_e32 v155, v183
	v_mov_b32_e32 v156, v184
	v_mov_b32_e32 v157, v185
	v_mov_b32_e32 v158, v186
	v_mov_b32_e32 v159, v187
	v_pk_mul_f32 v[108:109], v[44:45], v[156:157]
	s_nop 0
	v_pk_fma_f32 v[108:109], v[104:105], v[152:153], v[108:109] neg_lo:[0,0,1] neg_hi:[0,0,1]
	v_pk_mul_f32 v[104:105], v[104:105], v[156:157]
	v_mul_f32_e32 v110, v46, v158
	v_pk_fma_f32 v[44:45], v[44:45], v[152:153], v[104:105]
	v_mul_f32_e32 v104, v106, v154
	v_mul_f32_e32 v152, v46, v154
	v_mul_f32_e32 v154, v106, v158
	v_mov_b32_e32 v46, v107
	v_mov_b32_e32 v158, v155
	v_mov_b32_e32 v106, v47
	v_pk_mul_f32 v[156:157], v[46:47], v[158:159]
	v_pk_mul_f32 v[46:47], v[106:107], v[158:159]
	v_mov_b32_e32 v105, v156
	v_mov_b32_e32 v153, v46
	v_mov_b32_e32 v155, v47
	v_mov_b32_e32 v111, v157
	v_pk_add_f32 v[46:47], v[152:153], v[154:155]
	v_pk_add_f32 v[110:111], v[104:105], v[110:111] neg_lo:[0,1] neg_hi:[0,1]
	s_waitcnt vmcnt(8)
	v_mov_b32_e32 v152, v188
	v_mov_b32_e32 v153, v189
	v_mov_b32_e32 v154, v190
	v_mov_b32_e32 v155, v191
	v_mov_b32_e32 v156, v192
	v_mov_b32_e32 v157, v193
	v_mov_b32_e32 v158, v194
	v_mov_b32_e32 v159, v195
	v_pk_mul_f32 v[104:105], v[40:41], v[156:157]
	s_nop 0
	v_pk_fma_f32 v[104:105], v[100:101], v[152:153], v[104:105] neg_lo:[0,0,1] neg_hi:[0,0,1]
	v_pk_mul_f32 v[100:101], v[100:101], v[156:157]
	v_mul_f32_e32 v106, v42, v158
	v_pk_fma_f32 v[40:41], v[40:41], v[152:153], v[100:101]
	v_mul_f32_e32 v100, v102, v154
	v_mul_f32_e32 v152, v42, v154
	v_mul_f32_e32 v154, v102, v158
	v_mov_b32_e32 v42, v103
	v_mov_b32_e32 v158, v155
	v_pk_mul_f32 v[156:157], v[42:43], v[158:159]
	v_mov_b32_e32 v102, v43
	v_mov_b32_e32 v101, v156
	v_mov_b32_e32 v107, v157
	v_pk_add_f32 v[106:107], v[100:101], v[106:107] neg_lo:[0,1] neg_hi:[0,1]
	v_or_b32_e32 v100, 0x1800, v2
	v_ashrrev_i32_e32 v101, 31, v100
	v_lshlrev_b64 v[100:101], 2, v[100:101]
	v_pk_mul_f32 v[42:43], v[102:103], v[158:159]
	v_lshl_add_u64 v[102:103], s[34:35], 0, v[100:101]
	v_lshl_add_u64 v[100:101], s[36:37], 0, v[100:101]
	v_mov_b32_e32 v153, v42
	v_mov_b32_e32 v155, v43
	v_lshl_add_u64 v[160:161], v[102:103], 0, v[0:1]
	v_lshl_add_u64 v[162:163], v[100:101], 0, v[0:1]
	v_pk_add_f32 v[42:43], v[152:153], v[154:155]
	v_or_b32_e32 v2, 0x1c00, v2
	v_ashrrev_i32_e32 v3, 31, v2
	v_lshlrev_b64 v[2:3], 2, v[2:3]
	s_waitcnt vmcnt(6)
	v_mov_b32_e32 v152, v196
	v_mov_b32_e32 v153, v197
	v_mov_b32_e32 v154, v198
	v_mov_b32_e32 v155, v199
	v_mov_b32_e32 v156, v200
	v_mov_b32_e32 v157, v201
	v_mov_b32_e32 v158, v202
	v_mov_b32_e32 v159, v203
	v_pk_mul_f32 v[100:101], v[36:37], v[156:157]
	s_nop 0
	v_pk_fma_f32 v[100:101], v[96:97], v[152:153], v[100:101] neg_lo:[0,0,1] neg_hi:[0,0,1]
	v_pk_mul_f32 v[96:97], v[96:97], v[156:157]
	v_mul_f32_e32 v102, v38, v158
	v_pk_fma_f32 v[36:37], v[36:37], v[152:153], v[96:97]
	v_mul_f32_e32 v96, v98, v154
	v_mul_f32_e32 v152, v38, v154
	v_mul_f32_e32 v154, v98, v158
	v_mov_b32_e32 v38, v99
	v_mov_b32_e32 v158, v155
	v_mov_b32_e32 v98, v39
	v_pk_mul_f32 v[156:157], v[38:39], v[158:159]
	v_pk_mul_f32 v[38:39], v[98:99], v[158:159]
	v_mov_b32_e32 v97, v156
	v_mov_b32_e32 v153, v38
	v_mov_b32_e32 v155, v39
	v_mov_b32_e32 v103, v157
	v_pk_add_f32 v[38:39], v[152:153], v[154:155]
	v_pk_add_f32 v[102:103], v[96:97], v[102:103] neg_lo:[0,1] neg_hi:[0,1]
	s_waitcnt vmcnt(4)
; __device__ void even_in_tile(const P& p, int li_even, int tm, int tn, char* smem) {
;     ...
; #pragma unroll
;     for (int i = 0; i < MI; ++i) {
;       const int s = s0 + MROW(i);
; #pragma unroll
;       for (int jj = 0; jj < 2; ++jj) {
;         const int d = wn * 32 + jj * 16 + g * 4;
;         const f32x4 c = *(const f32x4*)(ctab + s * 64 + d);
;         const f32x4 sn = *(const f32x4*)(stab + s * 64 + d);
; #pragma unroll
;         for (int r = 0; r < 4; ++r) {
;           const float a = acc[i][jj][r], bb = acc[i][jj + 2][r];
;           acc[i][jj][r] = a * c[r] - bb * sn[r];
;           acc[i][jj + 2][r] = bb * c[r] + a * sn[r];
;         }
;       }
;     }
;   }
;   if (seg == 1) {
	v_mov_b32_e32 v152, v204
	v_mov_b32_e32 v153, v205
	v_mov_b32_e32 v154, v206
	v_mov_b32_e32 v155, v207
	v_mov_b32_e32 v156, v220
	v_mov_b32_e32 v157, v221
	v_mov_b32_e32 v158, v222
	v_mov_b32_e32 v159, v223
	v_pk_mul_f32 v[96:97], v[32:33], v[156:157]
	s_nop 0
	v_pk_fma_f32 v[96:97], v[92:93], v[152:153], v[96:97] neg_lo:[0,0,1] neg_hi:[0,0,1]
	v_pk_mul_f32 v[92:93], v[92:93], v[156:157]
	v_mul_f32_e32 v98, v34, v158
	v_pk_fma_f32 v[32:33], v[32:33], v[152:153], v[92:93]
	v_mul_f32_e32 v92, v94, v154
	v_mul_f32_e32 v152, v34, v154
	v_mul_f32_e32 v154, v94, v158
	v_mov_b32_e32 v34, v95
	v_mov_b32_e32 v158, v155
	v_pk_mul_f32 v[156:157], v[34:35], v[158:159]
	v_mov_b32_e32 v94, v35
	v_mov_b32_e32 v93, v156
	v_mov_b32_e32 v99, v157
	v_pk_add_f32 v[98:99], v[92:93], v[98:99] neg_lo:[0,1] neg_hi:[0,1]
	v_pk_mul_f32 v[34:35], v[94:95], v[158:159]
	v_lshl_add_u64 v[92:93], s[34:35], 0, v[2:3]
	v_lshl_add_u64 v[2:3], s[36:37], 0, v[2:3]
	v_mov_b32_e32 v153, v34
	v_mov_b32_e32 v155, v35
	v_lshl_add_u64 v[160:161], v[92:93], 0, v[0:1]
	v_lshl_add_u64 v[2:3], v[2:3], 0, v[0:1]
	v_pk_add_f32 v[34:35], v[152:153], v[154:155]
	s_waitcnt vmcnt(2)
	v_mov_b32_e32 v152, v224
	v_mov_b32_e32 v153, v225
	v_mov_b32_e32 v154, v226
	v_mov_b32_e32 v155, v227
	v_mov_b32_e32 v156, v228
	v_mov_b32_e32 v157, v229
	v_mov_b32_e32 v158, v230
	v_mov_b32_e32 v159, v231
	v_pk_mul_f32 v[92:93], v[24:25], v[156:157]
	s_nop 0
	v_pk_fma_f32 v[92:93], v[76:77], v[152:153], v[92:93] neg_lo:[0,0,1] neg_hi:[0,0,1]
	v_pk_mul_f32 v[76:77], v[76:77], v[156:157]
	v_mul_f32_e32 v94, v26, v158
	v_pk_fma_f32 v[24:25], v[24:25], v[152:153], v[76:77]
	v_mul_f32_e32 v76, v78, v154
	v_mul_f32_e32 v152, v26, v154
	v_mul_f32_e32 v154, v78, v158
	v_mov_b32_e32 v26, v79
	v_mov_b32_e32 v158, v155
	v_mov_b32_e32 v78, v27
	v_pk_mul_f32 v[156:157], v[26:27], v[158:159]
	v_pk_mul_f32 v[26:27], v[78:79], v[158:159]
	v_mov_b32_e32 v77, v156
	v_mov_b32_e32 v95, v157
	v_mov_b32_e32 v153, v26
	v_mov_b32_e32 v155, v27
	v_pk_add_f32 v[94:95], v[76:77], v[94:95] neg_lo:[0,1] neg_hi:[0,1]
	v_pk_add_f32 v[26:27], v[152:153], v[154:155]
	s_waitcnt vmcnt(0)
	v_mov_b32_e32 v76, v232
	v_mov_b32_e32 v77, v233
	v_mov_b32_e32 v78, v234
	v_mov_b32_e32 v79, v235
	v_mov_b32_e32 v152, v4
	v_mov_b32_e32 v153, v5
	v_mov_b32_e32 v154, v6
	v_mov_b32_e32 v155, v7
	v_pk_mul_f32 v[2:3], v[20:21], v[152:153]
	s_nop 0
	v_pk_fma_f32 v[156:157], v[28:29], v[76:77], v[2:3] neg_lo:[0,0,1] neg_hi:[0,0,1]
	v_pk_mul_f32 v[2:3], v[28:29], v[152:153]
	v_mul_f32_e32 v28, v22, v154
	v_pk_fma_f32 v[20:21], v[20:21], v[76:77], v[2:3]
	v_mul_f32_e32 v2, v30, v78
	v_mul_f32_e32 v76, v22, v78
	v_mul_f32_e32 v78, v30, v154
	v_mov_b32_e32 v22, v31
	v_mov_b32_e32 v154, v79
	v_pk_mul_f32 v[152:153], v[22:23], v[154:155]
	v_mov_b32_e32 v30, v23
	v_mov_b32_e32 v3, v152
	v_mov_b32_e32 v29, v153
	v_pk_add_f32 v[158:159], v[2:3], v[28:29] neg_lo:[0,1] neg_hi:[0,1]
	v_pk_mul_f32 v[2:3], v[30:31], v[154:155]
	v_mov_b64_e32 v[28:29], v[156:157]
	v_mov_b32_e32 v77, v2
	v_mov_b32_e32 v79, v3
	v_pk_add_f32 v[22:23], v[76:77], v[78:79]
	v_mov_b64_e32 v[76:77], v[92:93]
	v_mov_b64_e32 v[78:79], v[94:95]
	v_mov_b64_e32 v[92:93], v[96:97]
	v_mov_b64_e32 v[94:95], v[98:99]
	v_mov_b64_e32 v[96:97], v[100:101]
	v_mov_b64_e32 v[98:99], v[102:103]
	v_mov_b64_e32 v[100:101], v[104:105]
	v_mov_b64_e32 v[102:103], v[106:107]
	v_mov_b64_e32 v[104:105], v[108:109]
	v_mov_b64_e32 v[106:107], v[110:111]
	v_mov_b64_e32 v[108:109], v[112:113]
	v_mov_b64_e32 v[110:111], v[114:115]
	v_mov_b64_e32 v[112:113], v[120:121]
	v_mov_b64_e32 v[114:115], v[122:123]
	v_mov_b64_e32 v[120:121], v[128:129]
	v_mov_b64_e32 v[122:123], v[130:131]
	v_mov_b64_e32 v[128:129], v[148:149]
	v_mov_b64_e32 v[130:131], v[150:151]
	v_mov_b64_e32 v[148:149], v[146:147]
	v_mov_b64_e32 v[146:147], v[144:145]
	v_mov_b64_e32 v[144:145], v[142:143]
	v_mov_b64_e32 v[142:143], v[140:141]
	v_mov_b64_e32 v[140:141], v[138:139]
	v_mov_b64_e32 v[152:153], v[126:127]
	v_mov_b64_e32 v[138:139], v[136:137]
	v_mov_b64_e32 v[136:137], v[134:135]
	v_mov_b64_e32 v[150:151], v[124:125]
	v_mov_b64_e32 v[126:127], v[118:119]
	v_mov_b64_e32 v[30:31], v[158:159]
	v_mov_b64_e32 v[134:135], v[132:133]
	v_mov_b64_e32 v[124:125], v[116:117]
	s_cmp_eq_u32 s42, 1
	s_cselect_b64 s[34:35], -1, 0
	s_cmp_lg_u32 s42, 1
	s_cbranch_scc0 .LBB0_316

; template <int MI, bool SWAP, bool F8 = false>
; __device__ __forceinline__ void gemm_core(const bf16_t* __restrict__ A, int lda, const bf16_t* __restrict__ B, int ldb,
;                                           int K, char* smem, f32x4 (&acc)[MI][4]) {
;     ...
;   for (int kt = 0; kt < nk; ++kt) {
;     __syncthreads();
; #pragma unroll
;     for (int i = 0; i < MI; ++i) *(u32x4*)(smem + woff + i * 4096) = ra[i];
; #pragma unroll
;     for (int i = 0; i < 4; ++i) *(u32x4*)(smem + 32768 + woff + i * 4096) = rb[i];
;     __syncthreads();
;     if (kt + 1 < nk) {
; #pragma unroll
;       for (int i = 0; i < MI; ++i) ra[i] = *(const u32x4*)(ap + (size_t)(32 * i) * lda + (kt + 1) * 64);
; #pragma unroll
;       for (int i = 0; i < 4; ++i) rb[i] = *(const u32x4*)(bp + (size_t)(32 * i) * ldb + (kt + 1) * 64);
;     }
;     if (F8) {
;       const int c0 = (g ^ (li & 7)) << 4, c1 = ((4 + g) ^ (li & 7)) << 4;
;       i32x8 wf8[4];
; #pragma unroll
;       for (int j = 0; j < 4; ++j) {
;         const char* rp = smem + wrow + ((j & 1) * 16 + (j >> 1) * 64) * 128;
;         const u32x4 lo = *(const u32x4*)(rp + c0), hi = *(const u32x4*)(rp + c1);
;         wf8[j] = (i32x8){(int)lo.x, (int)lo.y, (int)lo.z, (int)lo.w, (int)hi.x, (int)hi.y, (int)hi.z, (int)hi.w};
;       }
; #pragma unroll
;       for (int i = 0; i < MI; ++i) {
;         const char* rp = smem + xrow + i * 2048;
;         const u32x4 lo = *(const u32x4*)(rp + c0), hi = *(const u32x4*)(rp + c1);
;         const i32x8 xf8 = {(int)lo.x, (int)lo.y, (int)lo.z, (int)lo.w, (int)hi.x, (int)hi.y, (int)hi.z, (int)hi.w};
; #pragma unroll
;         for (int j = 0; j < 4; ++j)
;           acc[i][j] = __builtin_amdgcn_mfma_scale_f32_16x16x128_f8f6f4(wf8[j], xf8, acc[i][j], 0, 0, 0, 0x77777777, 0, 0x7f7f7f7f);
;       }
;     } else {
; #pragma unroll
;     for (int kk = 0; kk < 2; ++kk) {
;       const int ch = ((kk * 4 + g) ^ (li & 7)) << 4;
;       bf16x8 xf[MI], wf[4];
; #pragma unroll
;       for (int j = 0; j < 4; ++j) wf[j] = *(const bf16x8*)(smem + wrow + ((j & 1) * 16 + (j >> 1) * 64) * 128 + ch);
; #pragma unroll
;       for (int i = 0; i < MI; ++i) xf[i] = *(const bf16x8*)(smem + xrow + i * 2048 + ch);
; #pragma unroll
;       for (int i = 0; i < MI; ++i)
; #pragma unroll
;         for (int j = 0; j < 4; ++j) {
.LBB0_313:
	v_add_u32_e32 v215, v204, v205
	v_add_u32_e32 v213, v203, v205
	s_waitcnt vmcnt(63) expcnt(7) lgkmcnt(15)
	s_barrier
	s_setprio 3
	s_mov_b32 m0, s62
	s_nop 0
	global_load_lds_dwordx4 v252, s[56:57]
	s_add_u32 m0, s62, 0x1000
	s_nop 0
	global_load_lds_dwordx4 v253, s[56:57]
	s_add_u32 s56, s56, 0x20000
	s_addc_u32 s57, s57, 0
	s_add_u32 m0, s62, 0x2000
	s_nop 0
	global_load_lds_dwordx4 v252, s[56:57]
	s_add_u32 m0, s62, 0x3000
	s_nop 0
	global_load_lds_dwordx4 v253, s[56:57]
	s_add_u32 s56, s56, 0x20000
	s_addc_u32 s57, s57, 0
	s_add_u32 m0, s62, 0x4000
	s_nop 0
	global_load_lds_dwordx4 v252, s[56:57]
	s_add_u32 m0, s62, 0x5000
	s_nop 0
	global_load_lds_dwordx4 v253, s[56:57]
	s_add_u32 s56, s56, 0x20000
	s_addc_u32 s57, s57, 0
	s_add_u32 m0, s62, 0x6000
	s_nop 0
	global_load_lds_dwordx4 v252, s[56:57]
	s_add_u32 m0, s62, 0x7000
	s_nop 0
	global_load_lds_dwordx4 v253, s[56:57]
	s_sub_u32 s56, s56, 0x60000
	s_subb_u32 s57, s57, 0
	s_add_u32 m0, s62, 0x8000
	s_nop 0
	global_load_lds_dwordx4 v252, s[58:59]
	s_add_u32 m0, s62, 0x9000
	s_nop 0
	global_load_lds_dwordx4 v253, s[58:59]
	s_add_u32 s58, s58, 0x20000
	s_addc_u32 s59, s59, 0
	s_add_u32 m0, s62, 0xa000
	s_nop 0
	global_load_lds_dwordx4 v252, s[58:59]
	s_add_u32 m0, s62, 0xb000
	s_nop 0
	global_load_lds_dwordx4 v253, s[58:59]
	s_sub_u32 s58, s58, 0x20000
	s_subb_u32 s59, s59, 0
	s_setprio 0
	v_add_u32_e32 v252, 0x80, v252
	v_add_u32_e32 v253, 0x80, v253
	s_waitcnt vmcnt(0)
	s_barrier
	ds_read_b128 v[148:151], v213
	ds_read_b128 v[152:155], v215 offset:32768
	ds_read_b128 v[156:159], v215 offset:34816
	ds_read_b128 v[160:163], v213 offset:2048
	ds_read_b128 v[164:167], v215 offset:40960
	ds_read_b128 v[168:171], v215 offset:43008
	s_waitcnt lgkmcnt(4)
	v_mfma_f32_16x16x32_bf16 v[140:143], v[148:151], v[152:155], v[140:143]
	v_add_u32_e32 v0, v203, v206
	v_add_u32_e32 v207, v204, v206
	s_waitcnt lgkmcnt(3)
	v_mfma_f32_16x16x32_bf16 v[136:139], v[148:151], v[156:159], v[136:139]
	s_waitcnt lgkmcnt(1)
	v_mfma_f32_16x16x32_bf16 v[132:135], v[148:151], v[164:167], v[132:135]
	s_waitcnt lgkmcnt(0)
	v_mfma_f32_16x16x32_bf16 v[128:131], v[148:151], v[168:171], v[128:131]
	v_mfma_f32_16x16x32_bf16 v[124:127], v[160:163], v[152:155], v[124:127]
	v_mfma_f32_16x16x32_bf16 v[120:123], v[160:163], v[156:159], v[120:123]
	v_mfma_f32_16x16x32_bf16 v[116:119], v[160:163], v[164:167], v[116:119]
	v_mfma_f32_16x16x32_bf16 v[112:115], v[160:163], v[168:171], v[112:115]
	ds_read_b128 v[148:151], v213 offset:4096
	ds_read_b128 v[160:163], v213 offset:6144
	s_waitcnt lgkmcnt(1)
	v_mfma_f32_16x16x32_bf16 v[108:111], v[148:151], v[152:155], v[108:111]
	v_mfma_f32_16x16x32_bf16 v[104:107], v[148:151], v[156:159], v[104:107]
	v_mfma_f32_16x16x32_bf16 v[100:103], v[148:151], v[164:167], v[100:103]
	v_mfma_f32_16x16x32_bf16 v[96:99], v[148:151], v[168:171], v[96:99]
	s_waitcnt lgkmcnt(0)
	v_mfma_f32_16x16x32_bf16 v[92:95], v[160:163], v[152:155], v[92:95]
	v_mfma_f32_16x16x32_bf16 v[88:91], v[160:163], v[156:159], v[88:91]
	v_mfma_f32_16x16x32_bf16 v[80:83], v[160:163], v[164:167], v[80:83]
	v_mfma_f32_16x16x32_bf16 v[72:75], v[160:163], v[168:171], v[72:75]
	ds_read_b128 v[148:151], v213 offset:8192
	ds_read_b128 v[160:163], v213 offset:10240
	s_waitcnt lgkmcnt(1)
	v_mfma_f32_16x16x32_bf16 v[64:67], v[148:151], v[152:155], v[64:67]
	v_mfma_f32_16x16x32_bf16 v[60:63], v[148:151], v[156:159], v[60:63]
	v_mfma_f32_16x16x32_bf16 v[52:55], v[148:151], v[164:167], v[52:55]
	v_mfma_f32_16x16x32_bf16 v[48:51], v[148:151], v[168:171], v[48:51]
	s_waitcnt lgkmcnt(0)
	v_mfma_f32_16x16x32_bf16 v[44:47], v[160:163], v[152:155], v[44:47]
	v_mfma_f32_16x16x32_bf16 v[40:43], v[160:163], v[156:159], v[40:43]
	v_mfma_f32_16x16x32_bf16 v[36:39], v[160:163], v[164:167], v[36:39]
	v_mfma_f32_16x16x32_bf16 v[32:35], v[160:163], v[168:171], v[32:35]
	ds_read_b128 v[148:151], v213 offset:12288
	ds_read_b128 v[160:163], v213 offset:14336
	s_waitcnt lgkmcnt(1)
	v_mfma_f32_16x16x32_bf16 v[24:27], v[148:151], v[156:159], v[24:27]
	s_waitcnt lgkmcnt(0)
	v_mfma_f32_16x16x32_bf16 v[56:59], v[160:163], v[156:159], v[56:59]
	v_mfma_f32_16x16x32_bf16 v[68:71], v[160:163], v[152:155], v[68:71]
	v_mfma_f32_16x16x32_bf16 v[20:23], v[160:163], v[164:167], v[20:23]
	v_mfma_f32_16x16x32_bf16 v[144:147], v[160:163], v[168:171], v[144:147]
	v_mfma_f32_16x16x32_bf16 v[28:31], v[148:151], v[152:155], v[28:31]
	v_mfma_f32_16x16x32_bf16 v[84:87], v[148:151], v[164:167], v[84:87]
	v_mfma_f32_16x16x32_bf16 v[76:79], v[148:151], v[168:171], v[76:79]
	ds_read_b128 v[148:151], v0
	ds_read_b128 v[168:171], v207 offset:32768
	ds_read_b128 v[180:183], v207 offset:34816
	ds_read_b128 v[152:155], v0 offset:2048
	ds_read_b128 v[192:195], v207 offset:40960
	ds_read_b128 v[196:199], v207 offset:43008
	s_waitcnt lgkmcnt(4)
	v_mfma_f32_16x16x32_bf16 v[140:143], v[148:151], v[168:171], v[140:143]
	s_waitcnt lgkmcnt(3)
	v_mfma_f32_16x16x32_bf16 v[136:139], v[148:151], v[180:183], v[136:139]
	s_waitcnt lgkmcnt(1)
	v_mfma_f32_16x16x32_bf16 v[132:135], v[148:151], v[192:195], v[132:135]
	s_waitcnt lgkmcnt(0)
	v_mfma_f32_16x16x32_bf16 v[128:131], v[148:151], v[196:199], v[128:131]
	v_mfma_f32_16x16x32_bf16 v[124:127], v[152:155], v[168:171], v[124:127]
	v_mfma_f32_16x16x32_bf16 v[120:123], v[152:155], v[180:183], v[120:123]
	v_mfma_f32_16x16x32_bf16 v[116:119], v[152:155], v[192:195], v[116:119]
	v_mfma_f32_16x16x32_bf16 v[112:115], v[152:155], v[196:199], v[112:115]
	ds_read_b128 v[148:151], v0 offset:4096
	ds_read_b128 v[152:155], v0 offset:6144
	ds_read_b128 v[156:159], v0 offset:12288
	ds_read_b128 v[216:219], v0 offset:14336
	s_waitcnt lgkmcnt(3)
; template <int MI, bool SWAP, bool F8 = false>
; __device__ __forceinline__ void gemm_core(const bf16_t* __restrict__ A, int lda, const bf16_t* __restrict__ B, int ldb,
;                                           int K, char* smem, f32x4 (&acc)[MI][4]) {
;     ...
;   for (int kt = 0; kt < nk; ++kt) {
;     __syncthreads();
; #pragma unroll
;     for (int i = 0; i < MI; ++i) *(u32x4*)(smem + woff + i * 4096) = ra[i];
; #pragma unroll
;     for (int i = 0; i < 4; ++i) *(u32x4*)(smem + 32768 + woff + i * 4096) = rb[i];
;     __syncthreads();
;     if (kt + 1 < nk) {
; #pragma unroll
;       for (int i = 0; i < MI; ++i) ra[i] = *(const u32x4*)(ap + (size_t)(32 * i) * lda + (kt + 1) * 64);
; #pragma unroll
;       for (int i = 0; i < 4; ++i) rb[i] = *(const u32x4*)(bp + (size_t)(32 * i) * ldb + (kt + 1) * 64);
;     }
;     if (F8) {
;       const int c0 = (g ^ (li & 7)) << 4, c1 = ((4 + g) ^ (li & 7)) << 4;
;       i32x8 wf8[4];
; #pragma unroll
;       for (int j = 0; j < 4; ++j) {
;         const char* rp = smem + wrow + ((j & 1) * 16 + (j >> 1) * 64) * 128;
;         const u32x4 lo = *(const u32x4*)(rp + c0), hi = *(const u32x4*)(rp + c1);
;         wf8[j] = (i32x8){(int)lo.x, (int)lo.y, (int)lo.z, (int)lo.w, (int)hi.x, (int)hi.y, (int)hi.z, (int)hi.w};
;       }
; #pragma unroll
;       for (int i = 0; i < MI; ++i) {
;         const char* rp = smem + xrow + i * 2048;
;         const u32x4 lo = *(const u32x4*)(rp + c0), hi = *(const u32x4*)(rp + c1);
;         const i32x8 xf8 = {(int)lo.x, (int)lo.y, (int)lo.z, (int)lo.w, (int)hi.x, (int)hi.y, (int)hi.z, (int)hi.w};
; #pragma unroll
;         for (int j = 0; j < 4; ++j)
;           acc[i][j] = __builtin_amdgcn_mfma_scale_f32_16x16x128_f8f6f4(wf8[j], xf8, acc[i][j], 0, 0, 0, 0x77777777, 0, 0x7f7f7f7f);
;       }
;     } else {
; #pragma unroll
;     for (int kk = 0; kk < 2; ++kk) {
;       const int ch = ((kk * 4 + g) ^ (li & 7)) << 4;
;       bf16x8 xf[MI], wf[4];
; #pragma unroll
;       for (int j = 0; j < 4; ++j) wf[j] = *(const bf16x8*)(smem + wrow + ((j & 1) * 16 + (j >> 1) * 64) * 128 + ch);
; #pragma unroll
;       for (int i = 0; i < MI; ++i) xf[i] = *(const bf16x8*)(smem + xrow + i * 2048 + ch);
; #pragma unroll
;       for (int i = 0; i < MI; ++i)
; #pragma unroll
;         for (int j = 0; j < 4; ++j) {
	v_mfma_f32_16x16x32_bf16 v[108:111], v[148:151], v[168:171], v[108:111]
	v_mfma_f32_16x16x32_bf16 v[104:107], v[148:151], v[180:183], v[104:107]
	v_mfma_f32_16x16x32_bf16 v[100:103], v[148:151], v[192:195], v[100:103]
	v_mfma_f32_16x16x32_bf16 v[96:99], v[148:151], v[196:199], v[96:99]
	ds_read_b128 v[148:151], v0 offset:8192
	s_waitcnt lgkmcnt(3)
	v_mfma_f32_16x16x32_bf16 v[92:95], v[152:155], v[168:171], v[92:95]
	v_mfma_f32_16x16x32_bf16 v[88:91], v[152:155], v[180:183], v[88:91]
	v_mfma_f32_16x16x32_bf16 v[80:83], v[152:155], v[192:195], v[80:83]
	v_mfma_f32_16x16x32_bf16 v[72:75], v[152:155], v[196:199], v[72:75]
	ds_read_b128 v[152:155], v0 offset:10240
	s_waitcnt lgkmcnt(1)
	v_mfma_f32_16x16x32_bf16 v[64:67], v[148:151], v[168:171], v[64:67]
	v_mfma_f32_16x16x32_bf16 v[60:63], v[148:151], v[180:183], v[60:63]
	v_mfma_f32_16x16x32_bf16 v[52:55], v[148:151], v[192:195], v[52:55]
	v_mfma_f32_16x16x32_bf16 v[48:51], v[148:151], v[196:199], v[48:51]
	s_waitcnt lgkmcnt(0)
	v_mfma_f32_16x16x32_bf16 v[44:47], v[152:155], v[168:171], v[44:47]
	v_mfma_f32_16x16x32_bf16 v[40:43], v[152:155], v[180:183], v[40:43]
	v_mfma_f32_16x16x32_bf16 v[36:39], v[152:155], v[192:195], v[36:39]
	v_mfma_f32_16x16x32_bf16 v[32:35], v[152:155], v[196:199], v[32:35]
	v_mfma_f32_16x16x32_bf16 v[28:31], v[156:159], v[168:171], v[28:31]
	v_mfma_f32_16x16x32_bf16 v[24:27], v[156:159], v[180:183], v[24:27]
	v_mfma_f32_16x16x32_bf16 v[84:87], v[156:159], v[192:195], v[84:87]
	v_mfma_f32_16x16x32_bf16 v[76:79], v[156:159], v[196:199], v[76:79]
	v_mfma_f32_16x16x32_bf16 v[68:71], v[216:219], v[168:171], v[68:71]
	v_mfma_f32_16x16x32_bf16 v[56:59], v[216:219], v[180:183], v[56:59]
	v_mfma_f32_16x16x32_bf16 v[20:23], v[216:219], v[192:195], v[20:23]
	v_mfma_f32_16x16x32_bf16 v[144:147], v[216:219], v[196:199], v[144:147]
	s_add_u32 s8, s8, 0x80
	s_addc_u32 s9, s9, 0
	s_cmpk_lg_i32 s8, 0x780
	s_cbranch_scc1 .LBB0_313
	s_barrier
	s_setprio 3
	s_mov_b32 m0, s62
	s_nop 0
	global_load_lds_dwordx4 v252, s[56:57]
	s_add_u32 m0, s62, 0x1000
	s_nop 0
	global_load_lds_dwordx4 v253, s[56:57]
	s_add_u32 s56, s56, 0x20000
	s_addc_u32 s57, s57, 0
	s_add_u32 m0, s62, 0x2000
	s_nop 0
	global_load_lds_dwordx4 v252, s[56:57]
	s_add_u32 m0, s62, 0x3000
	s_nop 0
	global_load_lds_dwordx4 v253, s[56:57]
	s_add_u32 s56, s56, 0x20000
	s_addc_u32 s57, s57, 0
	s_add_u32 m0, s62, 0x4000
	s_nop 0
	global_load_lds_dwordx4 v252, s[56:57]
	s_add_u32 m0, s62, 0x5000
	s_nop 0
	global_load_lds_dwordx4 v253, s[56:57]
	s_add_u32 s56, s56, 0x20000
	s_addc_u32 s57, s57, 0
	s_add_u32 m0, s62, 0x6000
	s_nop 0
	global_load_lds_dwordx4 v252, s[56:57]
	s_add_u32 m0, s62, 0x7000
	s_nop 0
	global_load_lds_dwordx4 v253, s[56:57]
	s_sub_u32 s56, s56, 0x60000
	s_subb_u32 s57, s57, 0
	s_add_u32 m0, s62, 0x8000
	s_nop 0
	global_load_lds_dwordx4 v252, s[58:59]
	s_add_u32 m0, s62, 0x9000
	s_nop 0
	global_load_lds_dwordx4 v253, s[58:59]
	s_add_u32 s58, s58, 0x20000
	s_addc_u32 s59, s59, 0
	s_add_u32 m0, s62, 0xa000
	s_nop 0
	global_load_lds_dwordx4 v252, s[58:59]
	s_add_u32 m0, s62, 0xb000
	s_nop 0
	global_load_lds_dwordx4 v253, s[58:59]
	s_sub_u32 s58, s58, 0x20000
	s_subb_u32 s59, s59, 0
	s_setprio 0
	s_waitcnt vmcnt(0)
	s_barrier
	v_bfe_u32 v12, v208, 4, 1
	v_mul_u32_u24_e32 v12, 24, v12
	v_mov_b32_e32 v13, 0
	ds_read_b128 v[148:151], v215 offset:32768
	ds_read_b128 v[152:155], v215 offset:34816
	ds_read_b128 v[156:159], v215 offset:40960
	ds_read_b128 v[160:163], v215 offset:43008
	ds_read_b128 v[164:167], v213
	ds_read_b128 v[168:171], v213 offset:2048
	ds_read_b128 v[172:175], v213 offset:4096
	ds_read_b128 v[176:179], v213 offset:6144
	ds_read_b128 v[180:183], v213 offset:8192
	ds_read_b128 v[184:187], v213 offset:10240
	ds_read_b128 v[188:191], v213 offset:12288
	ds_read_b128 v[192:195], v213 offset:14336
	s_cmp_eq_u32 s42, 2
	s_mov_b32 s7, 0x6000000
	s_cselect_b32 s7, 0x2000000, s7
	s_waitcnt lgkmcnt(7)
	v_mfma_f32_16x16x32_bf16 v[140:143], v[164:167], v[148:151], v[140:143]
	s_add_u32 s8, s40, s7
	s_addc_u32 s9, s39, 0
	s_ashr_i32 s7, s6, 31
	v_mfma_f32_16x16x32_bf16 v[136:139], v[164:167], v[152:155], v[136:139]
	s_lshl_b64 s[6:7], s[6:7], 20
	s_add_u32 s6, s8, s6
	s_addc_u32 s7, s9, s7
	v_mfma_f32_16x16x32_bf16 v[132:135], v[164:167], v[156:159], v[132:135]
	s_lshl_b32 s8, s41, 1
	s_add_u32 s6, s6, s8
	s_addc_u32 s7, s7, 0
	v_mfma_f32_16x16x32_bf16 v[128:131], v[164:167], v[160:163], v[128:131]
	s_waitcnt lgkmcnt(6)
	v_mfma_f32_16x16x32_bf16 v[124:127], v[168:171], v[148:151], v[124:127]
	v_mfma_f32_16x16x32_bf16 v[120:123], v[168:171], v[152:155], v[120:123]
	v_mfma_f32_16x16x32_bf16 v[116:119], v[168:171], v[156:159], v[116:119]
	v_mfma_f32_16x16x32_bf16 v[112:115], v[168:171], v[160:163], v[112:115]
	s_waitcnt lgkmcnt(5)
	v_mfma_f32_16x16x32_bf16 v[108:111], v[172:175], v[148:151], v[108:111]
	v_mfma_f32_16x16x32_bf16 v[104:107], v[172:175], v[152:155], v[104:107]
	v_mfma_f32_16x16x32_bf16 v[100:103], v[172:175], v[156:159], v[100:103]
	v_mfma_f32_16x16x32_bf16 v[96:99], v[172:175], v[160:163], v[96:99]
	s_waitcnt lgkmcnt(4)
	v_mfma_f32_16x16x32_bf16 v[92:95], v[176:179], v[148:151], v[92:95]
	v_mfma_f32_16x16x32_bf16 v[88:91], v[176:179], v[152:155], v[88:91]
	v_mfma_f32_16x16x32_bf16 v[80:83], v[176:179], v[156:159], v[80:83]
	v_mfma_f32_16x16x32_bf16 v[72:75], v[176:179], v[160:163], v[72:75]
	s_waitcnt lgkmcnt(3)
	v_mfma_f32_16x16x32_bf16 v[64:67], v[180:183], v[148:151], v[64:67]
	v_mfma_f32_16x16x32_bf16 v[60:63], v[180:183], v[152:155], v[60:63]
	v_mfma_f32_16x16x32_bf16 v[52:55], v[180:183], v[156:159], v[52:55]
	v_mfma_f32_16x16x32_bf16 v[48:51], v[180:183], v[160:163], v[48:51]
	s_waitcnt lgkmcnt(2)
; template <int MI, bool SWAP, bool F8 = false>
; __device__ __forceinline__ void gemm_core(const bf16_t* __restrict__ A, int lda, const bf16_t* __restrict__ B, int ldb,
;                                           int K, char* smem, f32x4 (&acc)[MI][4]) {
;     ...
; #pragma unroll
;     for (int kk = 0; kk < 2; ++kk) {
;       const int ch = ((kk * 4 + g) ^ (li & 7)) << 4;
;       bf16x8 xf[MI], wf[4];
; #pragma unroll
;       for (int j = 0; j < 4; ++j) wf[j] = *(const bf16x8*)(smem + wrow + ((j & 1) * 16 + (j >> 1) * 64) * 128 + ch);
; #pragma unroll
;       for (int i = 0; i < MI; ++i) xf[i] = *(const bf16x8*)(smem + xrow + i * 2048 + ch);
; #pragma unroll
;       for (int i = 0; i < MI; ++i)
; #pragma unroll
;         for (int j = 0; j < 4; ++j) {
;           if (SWAP) acc[i][j] = __builtin_amdgcn_mfma_f32_16x16x32_bf16(xf[i], wf[j], acc[i][j], 0, 0, 0);
;           else acc[i][j] = __builtin_amdgcn_mfma_f32_16x16x32_bf16(wf[j], xf[i], acc[i][j], 0, 0, 0);
;         }
; __device__ void even_in_tile(const P& p, int li_even, int tm, int tn, char* smem) {
;     ...
;   if (seg == 2 || seg == 5) {
;     gemm_core<MI, true>(A, 1024, B, 1024, 1024, smem, acc);
;     EPI_COORDS
;     bf16_t* dst = R + (seg == 2 ? R_MVT : R_RVT) + (size_t)bh * 128 * 4096;
; #pragma unroll
;     for (int i = 0; i < MI; ++i)
; #pragma unroll
;       for (int j = 0; j < 4; ++j) {
;         u32x2 v;
;         v.x = pk_bf16(acc[i][j][0], acc[i][j][1]);
;         v.y = pk_bf16(acc[i][j][2], acc[i][j][3]);
;         *(u32x2*)(dst + (size_t)NCOLS(j) * 4096 + s0 + MROWS(i)) = v;
;       }
	v_mfma_f32_16x16x32_bf16 v[44:47], v[184:187], v[148:151], v[44:47]
	v_mfma_f32_16x16x32_bf16 v[40:43], v[184:187], v[152:155], v[40:43]
	v_mfma_f32_16x16x32_bf16 v[36:39], v[184:187], v[156:159], v[36:39]
	v_mfma_f32_16x16x32_bf16 v[32:35], v[184:187], v[160:163], v[32:35]
	s_waitcnt lgkmcnt(1)
	v_mfma_f32_16x16x32_bf16 v[28:31], v[188:191], v[148:151], v[28:31]
	v_mfma_f32_16x16x32_bf16 v[24:27], v[188:191], v[152:155], v[24:27]
	v_mfma_f32_16x16x32_bf16 v[164:167], v[188:191], v[156:159], v[84:87]
	v_mfma_f32_16x16x32_bf16 v[168:171], v[188:191], v[160:163], v[76:79]
	s_waitcnt lgkmcnt(0)
	v_mfma_f32_16x16x32_bf16 v[148:151], v[192:195], v[148:151], v[68:71]
	v_mfma_f32_16x16x32_bf16 v[152:155], v[192:195], v[152:155], v[56:59]
	v_mfma_f32_16x16x32_bf16 v[20:23], v[192:195], v[156:159], v[20:23]
	v_mfma_f32_16x16x32_bf16 v[144:147], v[192:195], v[160:163], v[144:147]
	ds_read_b128 v[156:159], v207 offset:32768
	ds_read_b128 v[160:163], v207 offset:34816
	ds_read_b128 v[172:175], v207 offset:40960
	ds_read_b128 v[176:179], v207 offset:43008
	ds_read_b128 v[56:59], v0
	ds_read_b128 v[68:71], v0 offset:2048
	ds_read_b128 v[76:79], v0 offset:4096
	ds_read_b128 v[84:87], v0 offset:6144
	ds_read_b128 v[180:183], v0 offset:8192
	ds_read_b128 v[184:187], v0 offset:10240
	ds_read_b128 v[188:191], v0 offset:12288
	ds_read_b128 v[192:195], v0 offset:14336
	v_mov_b32_e32 v0, v208
	s_waitcnt lgkmcnt(7)
	v_mfma_f32_16x16x32_bf16 v[140:143], v[56:59], v[156:159], v[140:143]
	v_and_b32_e32 v2, 15, v0
	v_lshrrev_b32_e32 v3, 1, v0
	v_mfma_f32_16x16x32_bf16 v[196:199], v[56:59], v[160:163], v[136:139]
	s_nop 2
	v_and_or_b32 v136, v3, 32, v2
	v_and_b32_e32 v2, 0xffffff80, v0
	v_lshrrev_b32_e32 v0, 2, v0
	v_and_or_b32 v2, v0, 12, v2
	v_ashrrev_i32_e32 v3, 31, v2
	v_lshl_add_u64 v[2:3], v[2:3], 1, s[6:7]
	v_lshlrev_b32_e32 v0, 13, v136
	v_mfma_f32_16x16x32_bf16 v[200:203], v[56:59], v[172:175], v[132:135]
	v_cvt_pk_bf16_f32 v138, v140, v141
	v_cvt_pk_bf16_f32 v139, v142, v143
	v_lshl_add_u64 v[136:137], v[2:3], 0, v[0:1]
	v_mfma_f32_16x16x32_bf16 v[132:135], v[56:59], v[176:179], v[128:131]
	global_store_dwordx2 v[136:137], v[138:139], off
	v_or_b32_e32 v138, 0x20000, v0
	v_mov_b32_e32 v139, v1
	s_waitcnt lgkmcnt(6)
	v_mfma_f32_16x16x32_bf16 v[128:131], v[68:71], v[156:159], v[124:127]
	v_cvt_pk_bf16_f32 v140, v196, v197
	v_cvt_pk_bf16_f32 v141, v198, v199
	v_lshl_add_u64 v[142:143], v[2:3], 0, v[138:139]
	v_mfma_f32_16x16x32_bf16 v[124:127], v[68:71], v[160:163], v[120:123]
	global_store_dwordx2 v[142:143], v[140:141], off
	v_or_b32_e32 v140, 0x80000, v0
	v_or_b32_e32 v0, 0xa0000, v0
	v_mfma_f32_16x16x32_bf16 v[120:123], v[68:71], v[172:175], v[116:119]
	v_cvt_pk_bf16_f32 v132, v132, v133
	v_cvt_pk_bf16_f32 v133, v134, v135
	v_lshl_add_u64 v[134:135], v[2:3], 0, v[0:1]
	v_mfma_f32_16x16x32_bf16 v[116:119], v[68:71], v[176:179], v[112:115]
	global_store_dwordx2 v[134:135], v[132:133], off
	v_lshl_add_u64 v[132:133], v[2:3], 0, 32
	s_mov_b64 s[6:7], 0x60
	s_waitcnt lgkmcnt(5)
	v_mfma_f32_16x16x32_bf16 v[112:115], v[76:79], v[156:159], v[108:111]
	v_mov_b32_e32 v141, v1
	s_nop 1
	v_cvt_pk_bf16_f32 v116, v116, v117
	v_cvt_pk_bf16_f32 v117, v118, v119
	v_mfma_f32_16x16x32_bf16 v[108:111], v[76:79], v[160:163], v[104:107]
	v_lshl_add_u64 v[118:119], v[132:133], 0, v[0:1]
	global_store_dwordx2 v[118:119], v[116:117], off
	v_lshl_add_u64 v[116:117], v[2:3], 0, 64
	v_mfma_f32_16x16x32_bf16 v[104:107], v[76:79], v[172:175], v[100:103]
	v_cvt_pk_bf16_f32 v142, v200, v201
	v_cvt_pk_bf16_f32 v143, v202, v203
	v_cvt_pk_bf16_f32 v128, v128, v129
	v_mfma_f32_16x16x32_bf16 v[100:103], v[76:79], v[176:179], v[96:99]
	v_cvt_pk_bf16_f32 v129, v130, v131
	v_cvt_pk_bf16_f32 v124, v124, v125
	v_cvt_pk_bf16_f32 v125, v126, v127
	s_waitcnt lgkmcnt(4)
	v_mfma_f32_16x16x32_bf16 v[96:99], v[84:87], v[156:159], v[92:95]
	v_lshl_add_u64 v[126:127], v[132:133], 0, v[138:139]
	s_nop 1
	v_cvt_pk_bf16_f32 v100, v100, v101
	v_cvt_pk_bf16_f32 v101, v102, v103
	v_mfma_f32_16x16x32_bf16 v[92:95], v[84:87], v[160:163], v[88:91]
	v_lshl_add_u64 v[102:103], v[116:117], 0, v[0:1]
	global_store_dwordx2 v[102:103], v[100:101], off
	v_lshl_add_u64 v[100:101], v[2:3], 0, s[6:7]
	v_mfma_f32_16x16x32_bf16 v[88:91], v[84:87], v[172:175], v[80:83]
	s_mov_b64 s[6:7], 0x80
	v_cvt_pk_bf16_f32 v120, v120, v121
	v_cvt_pk_bf16_f32 v121, v122, v123
	v_mfma_f32_16x16x32_bf16 v[84:87], v[84:87], v[176:179], v[72:75]
	v_lshl_add_u64 v[122:123], v[132:133], 0, v[140:141]
	v_cvt_pk_bf16_f32 v112, v112, v113
	v_cvt_pk_bf16_f32 v113, v114, v115
	s_waitcnt lgkmcnt(3)
	v_mfma_f32_16x16x32_bf16 v[68:71], v[180:183], v[176:179], v[48:51]
	v_cvt_pk_bf16_f32 v108, v108, v109
	s_nop 1
	v_cvt_pk_bf16_f32 v84, v84, v85
	v_cvt_pk_bf16_f32 v85, v86, v87
	v_mfma_f32_16x16x32_bf16 v[72:75], v[180:183], v[172:175], v[52:55]
	v_lshl_add_u64 v[86:87], v[100:101], 0, v[0:1]
	global_store_dwordx2 v[86:87], v[84:85], off
	v_lshl_add_u64 v[84:85], v[2:3], 0, s[6:7]
	s_waitcnt lgkmcnt(2)
; __device__ void even_in_tile(const P& p, int li_even, int tm, int tn, char* smem) {
;     ...
;   if (seg == 2 || seg == 5) {
;     gemm_core<MI, true>(A, 1024, B, 1024, 1024, smem, acc);
;     EPI_COORDS
;     bf16_t* dst = R + (seg == 2 ? R_MVT : R_RVT) + (size_t)bh * 128 * 4096;
; #pragma unroll
;     for (int i = 0; i < MI; ++i)
; #pragma unroll
;       for (int j = 0; j < 4; ++j) {
;         u32x2 v;
;         v.x = pk_bf16(acc[i][j][0], acc[i][j][1]);
;         v.y = pk_bf16(acc[i][j][2], acc[i][j][3]);
;         *(u32x2*)(dst + (size_t)NCOLS(j) * 4096 + s0 + MROWS(i)) = v;
;       }
;     return;
	v_mfma_f32_16x16x32_bf16 v[52:55], v[184:187], v[176:179], v[32:35]
	v_cvt_pk_bf16_f32 v68, v68, v69
	v_cvt_pk_bf16_f32 v69, v70, v71
	v_lshl_add_u64 v[70:71], v[84:85], 0, v[0:1]
	s_mov_b64 s[6:7], 0xa0
	v_mfma_f32_16x16x32_bf16 v[80:83], v[180:183], v[156:159], v[64:67]
	global_store_dwordx2 v[70:71], v[68:69], off
	v_lshl_add_u64 v[68:69], v[2:3], 0, s[6:7]
	s_nop 0
	v_cvt_pk_bf16_f32 v52, v52, v53
	v_mfma_f32_16x16x32_bf16 v[76:79], v[180:183], v[160:163], v[60:63]
	v_cvt_pk_bf16_f32 v53, v54, v55
	v_lshl_add_u64 v[54:55], v[68:69], 0, v[0:1]
	s_mov_b64 s[6:7], 0xc0
	v_mfma_f32_16x16x32_bf16 v[64:67], v[184:187], v[156:159], v[44:47]
	global_store_dwordx2 v[54:55], v[52:53], off
	v_lshl_add_u64 v[52:53], v[2:3], 0, s[6:7]
	s_mov_b64 s[6:7], 0xe0
	v_mfma_f32_16x16x32_bf16 v[60:63], v[184:187], v[160:163], v[40:43]
	v_cvt_pk_bf16_f32 v109, v110, v111
	v_lshl_add_u64 v[110:111], v[116:117], 0, v[138:139]
	v_cvt_pk_bf16_f32 v104, v104, v105
	v_mfma_f32_16x16x32_bf16 v[56:59], v[184:187], v[172:175], v[36:39]
	v_cvt_pk_bf16_f32 v105, v106, v107
	v_lshl_add_u64 v[106:107], v[116:117], 0, v[140:141]
	v_cvt_pk_bf16_f32 v96, v96, v97
	s_waitcnt lgkmcnt(1)
	v_mfma_f32_16x16x32_bf16 v[48:51], v[188:191], v[156:159], v[28:31]
	v_cvt_pk_bf16_f32 v97, v98, v99
	v_cvt_pk_bf16_f32 v92, v92, v93
	v_cvt_pk_bf16_f32 v93, v94, v95
	v_mfma_f32_16x16x32_bf16 v[44:47], v[188:191], v[160:163], v[24:27]
	v_lshl_add_u64 v[94:95], v[100:101], 0, v[138:139]
	v_cvt_pk_bf16_f32 v88, v88, v89
	v_cvt_pk_bf16_f32 v89, v90, v91
	v_mfma_f32_16x16x32_bf16 v[40:43], v[188:191], v[172:175], v[164:167]
	v_lshl_add_u64 v[90:91], v[100:101], 0, v[140:141]
	v_cvt_pk_bf16_f32 v80, v80, v81
	v_cvt_pk_bf16_f32 v81, v82, v83
	v_mfma_f32_16x16x32_bf16 v[36:39], v[188:191], v[176:179], v[168:171]
	v_cvt_pk_bf16_f32 v76, v76, v77
	v_cvt_pk_bf16_f32 v77, v78, v79
	v_lshl_add_u64 v[78:79], v[84:85], 0, v[138:139]
	s_waitcnt lgkmcnt(0)
	v_mfma_f32_16x16x32_bf16 v[32:35], v[192:195], v[156:159], v[148:151]
	v_cvt_pk_bf16_f32 v72, v72, v73
	v_cvt_pk_bf16_f32 v73, v74, v75
	v_lshl_add_u64 v[74:75], v[84:85], 0, v[140:141]
	v_mfma_f32_16x16x32_bf16 v[28:31], v[192:195], v[160:163], v[152:155]
	v_cvt_pk_bf16_f32 v64, v64, v65
	v_cvt_pk_bf16_f32 v65, v66, v67
	v_cvt_pk_bf16_f32 v60, v60, v61
	v_mfma_f32_16x16x32_bf16 v[24:27], v[192:195], v[172:175], v[20:23]
	v_cvt_pk_bf16_f32 v61, v62, v63
	v_lshl_add_u64 v[62:63], v[68:69], 0, v[138:139]
	v_cvt_pk_bf16_f32 v56, v56, v57
	v_mfma_f32_16x16x32_bf16 v[20:23], v[192:195], v[176:179], v[144:147]
	v_cvt_pk_bf16_f32 v57, v58, v59
	v_lshl_add_u64 v[58:59], v[68:69], 0, v[140:141]
	v_cvt_pk_bf16_f32 v48, v48, v49
	v_lshl_add_u64 v[144:145], v[2:3], 0, v[140:141]
	v_lshl_add_u64 v[2:3], v[2:3], 0, s[6:7]
	v_cvt_pk_bf16_f32 v49, v50, v51
	v_cvt_pk_bf16_f32 v44, v44, v45
	v_cvt_pk_bf16_f32 v45, v46, v47
	v_lshl_add_u64 v[46:47], v[52:53], 0, v[138:139]
	v_cvt_pk_bf16_f32 v40, v40, v41
	v_cvt_pk_bf16_f32 v41, v42, v43
	v_lshl_add_u64 v[42:43], v[52:53], 0, v[140:141]
	v_cvt_pk_bf16_f32 v36, v36, v37
	v_cvt_pk_bf16_f32 v37, v38, v39
	v_lshl_add_u64 v[38:39], v[52:53], 0, v[0:1]
	v_cvt_pk_bf16_f32 v32, v32, v33
	v_cvt_pk_bf16_f32 v33, v34, v35
	v_cvt_pk_bf16_f32 v28, v28, v29
	v_cvt_pk_bf16_f32 v29, v30, v31
	v_lshl_add_u64 v[30:31], v[2:3], 0, v[138:139]
	v_cvt_pk_bf16_f32 v24, v24, v25
	v_cvt_pk_bf16_f32 v25, v26, v27
	v_lshl_add_u64 v[26:27], v[2:3], 0, v[140:141]
	v_cvt_pk_bf16_f32 v20, v20, v21
	v_cvt_pk_bf16_f32 v21, v22, v23
	v_lshl_add_u64 v[2:3], v[2:3], 0, v[0:1]
	global_store_dwordx2 v[144:145], v[142:143], off
	global_store_dwordx2 v[136:137], v[128:129], off offset:32
	global_store_dwordx2 v[126:127], v[124:125], off
	global_store_dwordx2 v[122:123], v[120:121], off
	global_store_dwordx2 v[136:137], v[112:113], off offset:64
	global_store_dwordx2 v[110:111], v[108:109], off
	global_store_dwordx2 v[106:107], v[104:105], off
	global_store_dwordx2 v[136:137], v[96:97], off offset:96
	global_store_dwordx2 v[94:95], v[92:93], off
	global_store_dwordx2 v[90:91], v[88:89], off
	global_store_dwordx2 v[136:137], v[80:81], off offset:128
	global_store_dwordx2 v[78:79], v[76:77], off
	global_store_dwordx2 v[74:75], v[72:73], off
	global_store_dwordx2 v[136:137], v[64:65], off offset:160
	global_store_dwordx2 v[62:63], v[60:61], off
	global_store_dwordx2 v[58:59], v[56:57], off
	global_store_dwordx2 v[136:137], v[48:49], off offset:192
	global_store_dwordx2 v[46:47], v[44:45], off
	global_store_dwordx2 v[42:43], v[40:41], off
	global_store_dwordx2 v[38:39], v[36:37], off
	global_store_dwordx2 v[136:137], v[32:33], off offset:224
	global_store_dwordx2 v[30:31], v[28:29], off
	global_store_dwordx2 v[26:27], v[24:25], off
	global_store_dwordx2 v[2:3], v[20:21], off
	s_branch .LBB0_294

; template <int MI, bool SWAP, bool F8 = false>
; __device__ __forceinline__ void gemm_core(const bf16_t* __restrict__ A, int lda, const bf16_t* __restrict__ B, int ldb,
;                                           int K, char* smem, f32x4 (&acc)[MI][4]) {
;     ...
; #pragma unroll
;     for (int kk = 0; kk < 2; ++kk) {
;       const int ch = ((kk * 4 + g) ^ (li & 7)) << 4;
;       bf16x8 xf[MI], wf[4];
; #pragma unroll
;       for (int j = 0; j < 4; ++j) wf[j] = *(const bf16x8*)(smem + wrow + ((j & 1) * 16 + (j >> 1) * 64) * 128 + ch);
; #pragma unroll
;       for (int i = 0; i < MI; ++i) xf[i] = *(const bf16x8*)(smem + xrow + i * 2048 + ch);
; #pragma unroll
;       for (int i = 0; i < MI; ++i)
; #pragma unroll
;         for (int j = 0; j < 4; ++j) {
;           if (SWAP) acc[i][j] = __builtin_amdgcn_mfma_f32_16x16x32_bf16(xf[i], wf[j], acc[i][j], 0, 0, 0);
;           else acc[i][j] = __builtin_amdgcn_mfma_f32_16x16x32_bf16(wf[j], xf[i], acc[i][j], 0, 0, 0);
;         }
;     }
.Lcch819_ret:
	s_add_u32 s63, s63, 1
	s_barrier
	v_add_u32_e32 v213, v202, v204
	ds_read_b128 v[148:151], v215 offset:32768
	ds_read_b128 v[152:155], v215 offset:34816
	ds_read_b128 v[156:159], v213
	ds_read_b128 v[160:163], v213 offset:2048
	ds_read_b128 v[164:167], v215 offset:40960
	ds_read_b128 v[168:171], v215 offset:43008
	s_waitcnt lgkmcnt(3)
	v_mfma_f32_16x16x32_bf16 v[140:143], v[148:151], v[156:159], v[140:143]
	v_add_u32_e32 v207, v203, v205
	v_add_u32_e32 v206, v202, v205
	v_mfma_f32_16x16x32_bf16 v[136:139], v[152:155], v[156:159], v[136:139]
	s_waitcnt lgkmcnt(1)
	v_mfma_f32_16x16x32_bf16 v[132:135], v[164:167], v[156:159], v[132:135]
	s_waitcnt lgkmcnt(0)
	v_mfma_f32_16x16x32_bf16 v[124:127], v[168:171], v[156:159], v[124:127]
	v_mfma_f32_16x16x32_bf16 v[108:111], v[148:151], v[160:163], v[108:111]
	v_mfma_f32_16x16x32_bf16 v[104:107], v[152:155], v[160:163], v[104:107]
	v_mfma_f32_16x16x32_bf16 v[96:99], v[164:167], v[160:163], v[96:99]
	v_mfma_f32_16x16x32_bf16 v[92:95], v[168:171], v[160:163], v[92:95]
	ds_read_b128 v[156:159], v213 offset:4096
	ds_read_b128 v[160:163], v213 offset:6144
	s_waitcnt lgkmcnt(1)
	v_mfma_f32_16x16x32_bf16 v[88:91], v[148:151], v[156:159], v[88:91]
	v_mfma_f32_16x16x32_bf16 v[84:87], v[152:155], v[156:159], v[84:87]
	v_mfma_f32_16x16x32_bf16 v[80:83], v[164:167], v[156:159], v[80:83]
	v_mfma_f32_16x16x32_bf16 v[60:63], v[168:171], v[156:159], v[60:63]
	s_waitcnt lgkmcnt(0)
	v_mfma_f32_16x16x32_bf16 v[56:59], v[148:151], v[160:163], v[56:59]
	v_mfma_f32_16x16x32_bf16 v[52:55], v[152:155], v[160:163], v[52:55]
	v_mfma_f32_16x16x32_bf16 v[48:51], v[164:167], v[160:163], v[48:51]
	v_mfma_f32_16x16x32_bf16 v[44:47], v[168:171], v[160:163], v[44:47]
	ds_read_b128 v[156:159], v213 offset:8192
	ds_read_b128 v[160:163], v213 offset:10240
	s_waitcnt lgkmcnt(1)
	v_mfma_f32_16x16x32_bf16 v[40:43], v[148:151], v[156:159], v[40:43]
	v_mfma_f32_16x16x32_bf16 v[36:39], v[152:155], v[156:159], v[36:39]
	v_mfma_f32_16x16x32_bf16 v[32:35], v[164:167], v[156:159], v[32:35]
	v_mfma_f32_16x16x32_bf16 v[28:31], v[168:171], v[156:159], v[28:31]
	s_waitcnt lgkmcnt(0)
	v_mfma_f32_16x16x32_bf16 v[24:27], v[148:151], v[160:163], v[24:27]
	v_mfma_f32_16x16x32_bf16 v[20:23], v[152:155], v[160:163], v[20:23]
	v_mfma_f32_16x16x32_bf16 v[68:71], v[164:167], v[160:163], v[68:71]
	v_mfma_f32_16x16x32_bf16 v[64:67], v[168:171], v[160:163], v[64:67]
	ds_read_b128 v[156:159], v213 offset:12288
	ds_read_b128 v[160:163], v213 offset:14336
	ds_read_b128 v[172:175], v207 offset:32768
	ds_read_b128 v[180:183], v207 offset:34816
	s_waitcnt lgkmcnt(3)
	v_mfma_f32_16x16x32_bf16 v[72:75], v[148:151], v[156:159], v[72:75]
	v_mfma_f32_16x16x32_bf16 v[76:79], v[152:155], v[156:159], v[76:79]
	v_mfma_f32_16x16x32_bf16 v[128:131], v[164:167], v[156:159], v[128:131]
	v_mfma_f32_16x16x32_bf16 v[120:123], v[168:171], v[156:159], v[120:123]
	s_waitcnt lgkmcnt(2)
	v_mfma_f32_16x16x32_bf16 v[116:119], v[148:151], v[160:163], v[116:119]
	v_mfma_f32_16x16x32_bf16 v[112:115], v[152:155], v[160:163], v[112:115]
	ds_read_b128 v[148:151], v206
	ds_read_b128 v[152:155], v206 offset:2048
	ds_read_b128 v[192:195], v207 offset:40960
	ds_read_b128 v[196:199], v207 offset:43008
	v_mfma_f32_16x16x32_bf16 v[100:103], v[164:167], v[160:163], v[100:103]
	v_mfma_f32_16x16x32_bf16 v[144:147], v[168:171], v[160:163], v[144:147]
	s_waitcnt lgkmcnt(3)
	v_mfma_f32_16x16x32_bf16 v[140:143], v[172:175], v[148:151], v[140:143]
	v_mfma_f32_16x16x32_bf16 v[136:139], v[180:183], v[148:151], v[136:139]
	s_waitcnt lgkmcnt(1)
	v_mfma_f32_16x16x32_bf16 v[132:135], v[192:195], v[148:151], v[132:135]
	s_waitcnt lgkmcnt(0)
	v_mfma_f32_16x16x32_bf16 v[124:127], v[196:199], v[148:151], v[124:127]
	v_mfma_f32_16x16x32_bf16 v[108:111], v[172:175], v[152:155], v[108:111]
	v_mfma_f32_16x16x32_bf16 v[104:107], v[180:183], v[152:155], v[104:107]
	v_mfma_f32_16x16x32_bf16 v[96:99], v[192:195], v[152:155], v[96:99]
	v_mfma_f32_16x16x32_bf16 v[92:95], v[196:199], v[152:155], v[92:95]
	ds_read_b128 v[148:151], v206 offset:4096
	ds_read_b128 v[152:155], v206 offset:6144
	s_waitcnt lgkmcnt(1)
	v_mfma_f32_16x16x32_bf16 v[88:91], v[172:175], v[148:151], v[88:91]
	ds_read_b128 v[156:159], v206 offset:12288
	ds_read_b128 v[216:219], v206 offset:14336
	v_mfma_f32_16x16x32_bf16 v[84:87], v[180:183], v[148:151], v[84:87]
	v_mfma_f32_16x16x32_bf16 v[80:83], v[192:195], v[148:151], v[80:83]
	v_mfma_f32_16x16x32_bf16 v[60:63], v[196:199], v[148:151], v[60:63]
	ds_read_b128 v[148:151], v206 offset:8192
	s_waitcnt lgkmcnt(3)
	v_mfma_f32_16x16x32_bf16 v[56:59], v[172:175], v[152:155], v[56:59]
	v_mfma_f32_16x16x32_bf16 v[52:55], v[180:183], v[152:155], v[52:55]
	v_mfma_f32_16x16x32_bf16 v[48:51], v[192:195], v[152:155], v[48:51]
	v_mfma_f32_16x16x32_bf16 v[44:47], v[196:199], v[152:155], v[44:47]
	ds_read_b128 v[152:155], v206 offset:10240
	s_waitcnt lgkmcnt(1)
	v_mfma_f32_16x16x32_bf16 v[40:43], v[172:175], v[148:151], v[40:43]
	v_mfma_f32_16x16x32_bf16 v[36:39], v[180:183], v[148:151], v[36:39]
	v_mfma_f32_16x16x32_bf16 v[32:35], v[192:195], v[148:151], v[32:35]
	v_mfma_f32_16x16x32_bf16 v[28:31], v[196:199], v[148:151], v[28:31]
	s_waitcnt lgkmcnt(0)
	v_mfma_f32_16x16x32_bf16 v[24:27], v[172:175], v[152:155], v[24:27]
	v_mfma_f32_16x16x32_bf16 v[20:23], v[180:183], v[152:155], v[20:23]
	v_mfma_f32_16x16x32_bf16 v[68:71], v[192:195], v[152:155], v[68:71]
	v_mfma_f32_16x16x32_bf16 v[64:67], v[196:199], v[152:155], v[64:67]
	v_mfma_f32_16x16x32_bf16 v[72:75], v[172:175], v[156:159], v[72:75]
	v_mfma_f32_16x16x32_bf16 v[76:79], v[180:183], v[156:159], v[76:79]
	v_mfma_f32_16x16x32_bf16 v[128:131], v[192:195], v[156:159], v[128:131]
	v_mfma_f32_16x16x32_bf16 v[120:123], v[196:199], v[156:159], v[120:123]
	v_mfma_f32_16x16x32_bf16 v[116:119], v[172:175], v[216:219], v[116:119]
	v_mfma_f32_16x16x32_bf16 v[112:115], v[180:183], v[216:219], v[112:115]
	v_mfma_f32_16x16x32_bf16 v[100:103], v[192:195], v[216:219], v[100:103]
	v_mfma_f32_16x16x32_bf16 v[144:147], v[196:199], v[216:219], v[144:147]
	s_add_u32 s6, s6, 0x80
	s_addc_u32 s7, s7, 0
	s_cmpk_lg_i32 s6, 0x780
	s_cbranch_scc1 .LBB0_819
; template <int MI, bool SWAP, bool F8 = false>
; __device__ __forceinline__ void gemm_core(const bf16_t* __restrict__ A, int lda, const bf16_t* __restrict__ B, int ldb,
;                                           int K, char* smem, f32x4 (&acc)[MI][4]) {
;     ...
;   for (int kt = 0; kt < nk; ++kt) {
;     __syncthreads();
; #pragma unroll
;     for (int i = 0; i < MI; ++i) *(u32x4*)(smem + woff + i * 4096) = ra[i];
; #pragma unroll
;     for (int i = 0; i < 4; ++i) *(u32x4*)(smem + 32768 + woff + i * 4096) = rb[i];
;     __syncthreads();
;     if (kt + 1 < nk) {
; #pragma unroll
;       for (int i = 0; i < MI; ++i) ra[i] = *(const u32x4*)(ap + (size_t)(32 * i) * lda + (kt + 1) * 64);
; #pragma unroll
;       for (int i = 0; i < 4; ++i) rb[i] = *(const u32x4*)(bp + (size_t)(32 * i) * ldb + (kt + 1) * 64);
;     }
;     if (F8) {
;       const int c0 = (g ^ (li & 7)) << 4, c1 = ((4 + g) ^ (li & 7)) << 4;
;       i32x8 wf8[4];
; #pragma unroll
;       for (int j = 0; j < 4; ++j) {
;         const char* rp = smem + wrow + ((j & 1) * 16 + (j >> 1) * 64) * 128;
;         const u32x4 lo = *(const u32x4*)(rp + c0), hi = *(const u32x4*)(rp + c1);
;         wf8[j] = (i32x8){(int)lo.x, (int)lo.y, (int)lo.z, (int)lo.w, (int)hi.x, (int)hi.y, (int)hi.z, (int)hi.w};
;       }
; #pragma unroll
;       for (int i = 0; i < MI; ++i) {
;         const char* rp = smem + xrow + i * 2048;
;         const u32x4 lo = *(const u32x4*)(rp + c0), hi = *(const u32x4*)(rp + c1);
;         const i32x8 xf8 = {(int)lo.x, (int)lo.y, (int)lo.z, (int)lo.w, (int)hi.x, (int)hi.y, (int)hi.z, (int)hi.w};
; #pragma unroll
;         for (int j = 0; j < 4; ++j)
;           acc[i][j] = __builtin_amdgcn_mfma_scale_f32_16x16x128_f8f6f4(wf8[j], xf8, acc[i][j], 0, 0, 0, 0x77777777, 0, 0x7f7f7f7f);
;       }
;     } else {
; #pragma unroll
;     for (int kk = 0; kk < 2; ++kk) {
;       const int ch = ((kk * 4 + g) ^ (li & 7)) << 4;
;       bf16x8 xf[MI], wf[4];
; #pragma unroll
;       for (int j = 0; j < 4; ++j) wf[j] = *(const bf16x8*)(smem + wrow + ((j & 1) * 16 + (j >> 1) * 64) * 128 + ch);
; #pragma unroll
;       for (int i = 0; i < MI; ++i) xf[i] = *(const bf16x8*)(smem + xrow + i * 2048 + ch);
; #pragma unroll
;       for (int i = 0; i < MI; ++i)
; #pragma unroll
;         for (int j = 0; j < 4; ++j) {
	s_barrier
	s_setprio 3
	s_mov_b32 m0, s62
	s_nop 0
	global_load_lds_dwordx4 v252, s[56:57]
	s_add_u32 m0, s62, 0x1000
	s_nop 0
	global_load_lds_dwordx4 v253, s[56:57]
	s_add_u32 s56, s56, 0x20000
	s_addc_u32 s57, s57, 0
	s_add_u32 m0, s62, 0x2000
	s_nop 0
	global_load_lds_dwordx4 v252, s[56:57]
	s_add_u32 m0, s62, 0x3000
	s_nop 0
	global_load_lds_dwordx4 v253, s[56:57]
	s_add_u32 s56, s56, 0x20000
	s_addc_u32 s57, s57, 0
	s_add_u32 m0, s62, 0x4000
	s_nop 0
	global_load_lds_dwordx4 v252, s[56:57]
	s_add_u32 m0, s62, 0x5000
	s_nop 0
	global_load_lds_dwordx4 v253, s[56:57]
	s_add_u32 s56, s56, 0x20000
	s_addc_u32 s57, s57, 0
	s_add_u32 m0, s62, 0x6000
	s_nop 0
	global_load_lds_dwordx4 v252, s[56:57]
	s_add_u32 m0, s62, 0x7000
	s_nop 0
	global_load_lds_dwordx4 v253, s[56:57]
	s_sub_u32 s56, s56, 0x60000
	s_subb_u32 s57, s57, 0
	s_add_u32 m0, s62, 0x8000
	s_nop 0
	global_load_lds_dwordx4 v252, s[58:59]
	s_add_u32 m0, s62, 0x9000
	s_nop 0
	global_load_lds_dwordx4 v253, s[58:59]
	s_add_u32 s58, s58, 0x20000
	s_addc_u32 s59, s59, 0
	s_add_u32 m0, s62, 0xa000
	s_nop 0
	global_load_lds_dwordx4 v252, s[58:59]
	s_add_u32 m0, s62, 0xb000
	s_nop 0
	global_load_lds_dwordx4 v253, s[58:59]
	s_sub_u32 s58, s58, 0x20000
	s_subb_u32 s59, s59, 0
	s_setprio 0
	s_waitcnt vmcnt(0)
	s_barrier
	ds_read_b128 v[148:151], v215 offset:32768
	ds_read_b128 v[152:155], v215 offset:34816
	ds_read_b128 v[156:159], v215 offset:40960
	ds_read_b128 v[160:163], v215 offset:43008
	ds_read_b128 v[164:167], v213
	ds_read_b128 v[168:171], v213 offset:2048
	ds_read_b128 v[172:175], v213 offset:4096
	ds_read_b128 v[176:179], v213 offset:6144
	ds_read_b128 v[180:183], v213 offset:8192
	ds_read_b128 v[184:187], v213 offset:10240
	ds_read_b128 v[188:191], v213 offset:12288
	ds_read_b128 v[192:195], v213 offset:14336
	s_waitcnt lgkmcnt(7)
	v_mfma_f32_16x16x32_bf16 v[132:135], v[156:159], v[164:167], v[132:135]
	s_lshl_b64 s[0:1], s[0:1], 2
	s_add_u32 s0, s16, s0
	s_addc_u32 s1, s17, s1
	v_mfma_f32_16x16x32_bf16 v[140:143], v[148:151], v[164:167], v[140:143]
	s_lshl_b32 s6, s22, 2
	s_add_u32 s0, s0, s6
	s_addc_u32 s1, s1, 0
	v_mfma_f32_16x16x32_bf16 v[136:139], v[152:155], v[164:167], v[136:139]
	s_add_i32 s21, s21, s78
	s_add_i32 s20, s20, s71
	s_add_i32 s19, s19, s76
	v_mfma_f32_16x16x32_bf16 v[124:127], v[160:163], v[164:167], v[124:127]
	s_cmpk_gt_i32 s21, 0x1ff
	s_waitcnt lgkmcnt(6)
	v_mfma_f32_16x16x32_bf16 v[108:111], v[148:151], v[168:171], v[108:111]
	v_mfma_f32_16x16x32_bf16 v[104:107], v[152:155], v[168:171], v[104:107]
	v_mfma_f32_16x16x32_bf16 v[96:99], v[156:159], v[168:171], v[96:99]
	v_mfma_f32_16x16x32_bf16 v[92:95], v[160:163], v[168:171], v[92:95]
	s_waitcnt lgkmcnt(5)
	v_mfma_f32_16x16x32_bf16 v[88:91], v[148:151], v[172:175], v[88:91]
	v_mfma_f32_16x16x32_bf16 v[84:87], v[152:155], v[172:175], v[84:87]
	v_mfma_f32_16x16x32_bf16 v[80:83], v[156:159], v[172:175], v[80:83]
	v_mfma_f32_16x16x32_bf16 v[60:63], v[160:163], v[172:175], v[60:63]
	s_waitcnt lgkmcnt(4)
	v_mfma_f32_16x16x32_bf16 v[56:59], v[148:151], v[176:179], v[56:59]
	v_mfma_f32_16x16x32_bf16 v[52:55], v[152:155], v[176:179], v[52:55]
	v_mfma_f32_16x16x32_bf16 v[48:51], v[156:159], v[176:179], v[48:51]
	v_mfma_f32_16x16x32_bf16 v[44:47], v[160:163], v[176:179], v[44:47]
	s_waitcnt lgkmcnt(3)
	v_mfma_f32_16x16x32_bf16 v[40:43], v[148:151], v[180:183], v[40:43]
	v_mfma_f32_16x16x32_bf16 v[36:39], v[152:155], v[180:183], v[36:39]
	v_mfma_f32_16x16x32_bf16 v[32:35], v[156:159], v[180:183], v[32:35]
	v_mfma_f32_16x16x32_bf16 v[28:31], v[160:163], v[180:183], v[28:31]
	s_waitcnt lgkmcnt(2)
	v_mfma_f32_16x16x32_bf16 v[24:27], v[148:151], v[184:187], v[24:27]
	v_mfma_f32_16x16x32_bf16 v[20:23], v[152:155], v[184:187], v[20:23]
	v_mfma_f32_16x16x32_bf16 v[164:167], v[156:159], v[184:187], v[68:71]
	v_mfma_f32_16x16x32_bf16 v[168:171], v[160:163], v[184:187], v[64:67]
	s_waitcnt lgkmcnt(1)
	v_mfma_f32_16x16x32_bf16 v[172:175], v[148:151], v[188:191], v[72:75]
	v_mfma_f32_16x16x32_bf16 v[176:179], v[152:155], v[188:191], v[76:79]
	v_mfma_f32_16x16x32_bf16 v[180:183], v[156:159], v[188:191], v[128:131]
	v_mfma_f32_16x16x32_bf16 v[184:187], v[160:163], v[188:191], v[120:123]
	s_waitcnt lgkmcnt(0)
	v_mfma_f32_16x16x32_bf16 v[148:151], v[148:151], v[192:195], v[116:119]
	v_mfma_f32_16x16x32_bf16 v[152:155], v[152:155], v[192:195], v[112:115]
	v_mfma_f32_16x16x32_bf16 v[156:159], v[156:159], v[192:195], v[100:103]
	v_mfma_f32_16x16x32_bf16 v[144:147], v[160:163], v[192:195], v[144:147]
	ds_read_b128 v[160:163], v207 offset:32768
	ds_read_b128 v[188:191], v207 offset:34816
	ds_read_b128 v[192:195], v207 offset:40960
	ds_read_b128 v[196:199], v207 offset:43008
	ds_read_b128 v[64:67], v206
	ds_read_b128 v[68:71], v206 offset:2048
	ds_read_b128 v[72:75], v206 offset:4096
	ds_read_b128 v[76:79], v206 offset:6144
	ds_read_b128 v[200:203], v206 offset:8192
	ds_read_b128 v[216:219], v206 offset:10240
	ds_read_b128 v[220:223], v206 offset:12288
	ds_read_b128 v[204:207], v206 offset:14336
	s_waitcnt lgkmcnt(7)
; template <int MI, bool SWAP, bool F8 = false>
; __device__ __forceinline__ void gemm_core(const bf16_t* __restrict__ A, int lda, const bf16_t* __restrict__ B, int ldb,
;                                           int K, char* smem, f32x4 (&acc)[MI][4]) {
;     ...
; #pragma unroll
;     for (int kk = 0; kk < 2; ++kk) {
;       const int ch = ((kk * 4 + g) ^ (li & 7)) << 4;
;       bf16x8 xf[MI], wf[4];
; #pragma unroll
;       for (int j = 0; j < 4; ++j) wf[j] = *(const bf16x8*)(smem + wrow + ((j & 1) * 16 + (j >> 1) * 64) * 128 + ch);
; #pragma unroll
;       for (int i = 0; i < MI; ++i) xf[i] = *(const bf16x8*)(smem + xrow + i * 2048 + ch);
; #pragma unroll
;       for (int i = 0; i < MI; ++i)
; #pragma unroll
;         for (int j = 0; j < 4; ++j) {
;           if (SWAP) acc[i][j] = __builtin_amdgcn_mfma_f32_16x16x32_bf16(xf[i], wf[j], acc[i][j], 0, 0, 0);
;           else acc[i][j] = __builtin_amdgcn_mfma_f32_16x16x32_bf16(wf[j], xf[i], acc[i][j], 0, 0, 0);
;         }
; template <bool ACCUM, int MI>
; __device__ void gemm_tile_f32(const bf16_t* A, int lda, const bf16_t* B, int ldb, int K, float* C, int ldc, char* smem) {
;     ...
; #pragma unroll
;   for (int i = 0; i < MI; ++i)
; #pragma unroll
;     for (int j = 0; j < 4; ++j) {
;       f32x4* cp = (f32x4*)(C + (size_t)MROW(i) * ldc + NCOL(j));
;       f32x4 v = acc[i][j];
;       if (ACCUM) v += *cp;
;       *cp = v;
;     }
	v_mfma_f32_16x16x32_bf16 v[224:227], v[192:195], v[64:67], v[132:135]
	v_mfma_f32_16x16x32_bf16 v[228:231], v[196:199], v[64:67], v[124:127]
	s_waitcnt lgkmcnt(6)
	v_mfma_f32_16x16x32_bf16 v[128:131], v[160:163], v[68:71], v[108:111]
	v_mfma_f32_16x16x32_bf16 v[124:127], v[188:191], v[68:71], v[104:107]
	s_waitcnt lgkmcnt(5)
	v_mfma_f32_16x16x32_bf16 v[112:115], v[160:163], v[72:75], v[88:91]
	v_mfma_f32_16x16x32_bf16 v[108:111], v[188:191], v[72:75], v[84:87]
	v_mfma_f32_16x16x32_bf16 v[104:107], v[192:195], v[72:75], v[80:83]
	v_mfma_f32_16x16x32_bf16 v[100:103], v[196:199], v[72:75], v[60:63]
	s_waitcnt lgkmcnt(3)
	v_mfma_f32_16x16x32_bf16 v[72:75], v[192:195], v[200:203], v[32:35]
	s_waitcnt lgkmcnt(0)
	v_mfma_f32_16x16x32_bf16 v[32:35], v[160:163], v[204:207], v[148:151]
	v_mfma_f32_16x16x32_bf16 v[60:63], v[188:191], v[216:219], v[20:23]
	v_mfma_f32_16x16x32_bf16 v[20:23], v[196:199], v[204:207], v[144:147]
	v_mfma_f32_16x16x32_bf16 v[140:143], v[160:163], v[64:67], v[140:143]
	v_mfma_f32_16x16x32_bf16 v[136:139], v[188:191], v[64:67], v[136:139]
	v_mfma_f32_16x16x32_bf16 v[120:123], v[192:195], v[68:71], v[96:99]
	v_mfma_f32_16x16x32_bf16 v[116:119], v[196:199], v[68:71], v[92:95]
	v_mfma_f32_16x16x32_bf16 v[96:99], v[160:163], v[76:79], v[56:59]
	v_mfma_f32_16x16x32_bf16 v[92:95], v[188:191], v[76:79], v[52:55]
	v_mfma_f32_16x16x32_bf16 v[88:91], v[192:195], v[76:79], v[48:51]
	v_mfma_f32_16x16x32_bf16 v[84:87], v[196:199], v[76:79], v[44:47]
	v_mfma_f32_16x16x32_bf16 v[80:83], v[160:163], v[200:203], v[40:43]
	v_mfma_f32_16x16x32_bf16 v[76:79], v[188:191], v[200:203], v[36:39]
	v_mfma_f32_16x16x32_bf16 v[68:71], v[196:199], v[200:203], v[28:31]
	v_mfma_f32_16x16x32_bf16 v[64:67], v[160:163], v[216:219], v[24:27]
	v_mfma_f32_16x16x32_bf16 v[56:59], v[192:195], v[216:219], v[164:167]
	v_mfma_f32_16x16x32_bf16 v[52:55], v[196:199], v[216:219], v[168:171]
	v_mfma_f32_16x16x32_bf16 v[48:51], v[160:163], v[220:223], v[172:175]
	v_mfma_f32_16x16x32_bf16 v[44:47], v[188:191], v[220:223], v[176:179]
	v_mfma_f32_16x16x32_bf16 v[40:43], v[192:195], v[220:223], v[180:183]
	v_mfma_f32_16x16x32_bf16 v[36:39], v[196:199], v[220:223], v[184:187]
	v_mfma_f32_16x16x32_bf16 v[28:31], v[188:191], v[204:207], v[152:155]
	v_mfma_f32_16x16x32_bf16 v[24:27], v[192:195], v[204:207], v[156:159]
	s_nop 7
	s_nop 7
	s_nop 7
	global_store_dwordx4 v237, v[140:143], s[98:99]
	global_store_dwordx4 v237, v[136:139], s[98:99] offset:64
	global_store_dwordx4 v237, v[224:227], s[98:99] offset:256
	global_store_dwordx4 v237, v[228:231], s[98:99] offset:320
	v_add_u32_e32 v237, 0x10000, v237
	global_store_dwordx4 v237, v[128:131], s[98:99]
	global_store_dwordx4 v237, v[124:127], s[98:99] offset:64
	global_store_dwordx4 v237, v[120:123], s[98:99] offset:256
	global_store_dwordx4 v237, v[116:119], s[98:99] offset:320
	v_add_u32_e32 v237, 0x10000, v237
	global_store_dwordx4 v237, v[112:115], s[98:99]
	global_store_dwordx4 v237, v[108:111], s[98:99] offset:64
	global_store_dwordx4 v237, v[104:107], s[98:99] offset:256
	global_store_dwordx4 v237, v[100:103], s[98:99] offset:320
	v_add_u32_e32 v237, 0x10000, v237
	global_store_dwordx4 v237, v[96:99], s[98:99]
	global_store_dwordx4 v237, v[92:95], s[98:99] offset:64
	global_store_dwordx4 v237, v[88:91], s[98:99] offset:256
	global_store_dwordx4 v237, v[84:87], s[98:99] offset:320
	v_add_u32_e32 v237, 0x10000, v237
	global_store_dwordx4 v237, v[80:83], s[98:99]
	global_store_dwordx4 v237, v[76:79], s[98:99] offset:64
	global_store_dwordx4 v237, v[72:75], s[98:99] offset:256
	global_store_dwordx4 v237, v[68:71], s[98:99] offset:320
	v_add_u32_e32 v237, 0x10000, v237
	global_store_dwordx4 v237, v[64:67], s[98:99]
	global_store_dwordx4 v237, v[60:63], s[98:99] offset:64
	global_store_dwordx4 v237, v[56:59], s[98:99] offset:256
	global_store_dwordx4 v237, v[52:55], s[98:99] offset:320
	v_add_u32_e32 v237, 0x10000, v237
	global_store_dwordx4 v237, v[48:51], s[98:99]
	global_store_dwordx4 v237, v[44:47], s[98:99] offset:64
	global_store_dwordx4 v237, v[40:43], s[98:99] offset:256
	global_store_dwordx4 v237, v[36:39], s[98:99] offset:320
	v_add_u32_e32 v237, 0x10000, v237
	global_store_dwordx4 v237, v[32:35], s[98:99]
	global_store_dwordx4 v237, v[28:31], s[98:99] offset:64
	global_store_dwordx4 v237, v[24:27], s[98:99] offset:256
	global_store_dwordx4 v237, v[20:23], s[98:99] offset:320
	s_cbranch_scc0 .LBB0_818

; template <int MI, bool SWAP, bool F8 = false>
; __device__ __forceinline__ void gemm_core(const bf16_t* __restrict__ A, int lda, const bf16_t* __restrict__ B, int ldb,
;                                           int K, char* smem, f32x4 (&acc)[MI][4]) {
;     ...
;   for (int kt = 0; kt < nk; ++kt) {
;     __syncthreads();
; #pragma unroll
;     for (int i = 0; i < MI; ++i) *(u32x4*)(smem + woff + i * 4096) = ra[i];
; #pragma unroll
;     for (int i = 0; i < 4; ++i) *(u32x4*)(smem + 32768 + woff + i * 4096) = rb[i];
;     __syncthreads();
;     if (kt + 1 < nk) {
; #pragma unroll
;       for (int i = 0; i < MI; ++i) ra[i] = *(const u32x4*)(ap + (size_t)(32 * i) * lda + (kt + 1) * 64);
; #pragma unroll
;       for (int i = 0; i < 4; ++i) rb[i] = *(const u32x4*)(bp + (size_t)(32 * i) * ldb + (kt + 1) * 64);
;     }
;     if (F8) {
;       const int c0 = (g ^ (li & 7)) << 4, c1 = ((4 + g) ^ (li & 7)) << 4;
;       i32x8 wf8[4];
; #pragma unroll
;       for (int j = 0; j < 4; ++j) {
;         const char* rp = smem + wrow + ((j & 1) * 16 + (j >> 1) * 64) * 128;
;         const u32x4 lo = *(const u32x4*)(rp + c0), hi = *(const u32x4*)(rp + c1);
;         wf8[j] = (i32x8){(int)lo.x, (int)lo.y, (int)lo.z, (int)lo.w, (int)hi.x, (int)hi.y, (int)hi.z, (int)hi.w};
;       }
; #pragma unroll
;       for (int i = 0; i < MI; ++i) {
;         const char* rp = smem + xrow + i * 2048;
;         const u32x4 lo = *(const u32x4*)(rp + c0), hi = *(const u32x4*)(rp + c1);
;         const i32x8 xf8 = {(int)lo.x, (int)lo.y, (int)lo.z, (int)lo.w, (int)hi.x, (int)hi.y, (int)hi.z, (int)hi.w};
; #pragma unroll
;         for (int j = 0; j < 4; ++j)
;           acc[i][j] = __builtin_amdgcn_mfma_scale_f32_16x16x128_f8f6f4(wf8[j], xf8, acc[i][j], 0, 0, 0, 0x77777777, 0, 0x7f7f7f7f);
;       }
.LBB0_944:
	v_add_u32_e32 v222, v215, v218
	v_add_u32_e32 v223, v215, v219
	s_barrier
	s_setprio 3
	s_mov_b32 m0, s62
	s_nop 0
	global_load_lds_dwordx4 v252, s[56:57]
	s_add_u32 m0, s62, 0x1000
	s_nop 0
	global_load_lds_dwordx4 v253, s[56:57]
	s_add_u32 s56, s56, 0x10000
	s_addc_u32 s57, s57, 0
	s_add_u32 m0, s62, 0x2000
	s_nop 0
	global_load_lds_dwordx4 v252, s[56:57]
	s_add_u32 m0, s62, 0x3000
	s_nop 0
	global_load_lds_dwordx4 v253, s[56:57]
	s_add_u32 s56, s56, 0x10000
	s_addc_u32 s57, s57, 0
	s_add_u32 m0, s62, 0x4000
	s_nop 0
	global_load_lds_dwordx4 v252, s[56:57]
	s_add_u32 m0, s62, 0x5000
	s_nop 0
	global_load_lds_dwordx4 v253, s[56:57]
	s_add_u32 s56, s56, 0x10000
	s_addc_u32 s57, s57, 0
	s_add_u32 m0, s62, 0x6000
	s_nop 0
	global_load_lds_dwordx4 v252, s[56:57]
	s_add_u32 m0, s62, 0x7000
	s_nop 0
	global_load_lds_dwordx4 v253, s[56:57]
	s_sub_u32 s56, s56, 0x30000
	s_subb_u32 s57, s57, 0
	s_add_u32 m0, s62, 0x8000
	s_nop 0
	global_load_lds_dwordx4 v252, s[58:59]
	s_add_u32 m0, s62, 0x9000
	s_nop 0
	global_load_lds_dwordx4 v253, s[58:59]
	s_add_u32 s58, s58, 0x10000
	s_addc_u32 s59, s59, 0
	s_add_u32 m0, s62, 0xa000
	s_nop 0
	global_load_lds_dwordx4 v252, s[58:59]
	s_add_u32 m0, s62, 0xb000
	s_nop 0
	global_load_lds_dwordx4 v253, s[58:59]
	s_sub_u32 s58, s58, 0x10000
	s_subb_u32 s59, s59, 0
	s_setprio 0
	v_add_u32_e32 v252, 0x80, v252
	v_add_u32_e32 v253, 0x80, v253
	s_waitcnt vmcnt(0)
	s_barrier
	v_add_u32_e32 v221, v213, v218
	v_add_u32_e32 v220, v213, v219
	ds_read_b128 v[44:47], v222 offset:32768
	ds_read_b128 v[48:51], v223 offset:32768
	ds_read_b128 v[180:183], v221
	ds_read_b128 v[184:187], v220
	ds_read_b128 v[20:23], v222 offset:34816
	ds_read_b128 v[24:27], v223 offset:34816
	ds_read_b128 v[188:191], v221 offset:2048
	ds_read_b128 v[192:195], v220 offset:2048
	ds_read_b128 v[32:35], v223 offset:40960
	ds_read_b128 v[28:31], v222 offset:40960
	ds_read_b128 v[36:39], v222 offset:43008
	ds_read_b128 v[40:43], v223 offset:43008
	s_waitcnt lgkmcnt(8)
	v_mfma_scale_f32_16x16x128_f8f6f4 v[176:179], v[44:51], v[180:187], v[176:179], v239, v238 op_sel_hi:[0,0,0]
	s_waitcnt lgkmcnt(6)
	v_mfma_scale_f32_16x16x128_f8f6f4 v[172:175], v[20:27], v[180:187], v[172:175], v239, v238 op_sel_hi:[0,0,0]
	s_waitcnt lgkmcnt(2)
	v_mfma_scale_f32_16x16x128_f8f6f4 v[168:171], v[28:35], v[180:187], v[168:171], v239, v238 op_sel_hi:[0,0,0]
	s_waitcnt lgkmcnt(0)
	v_mfma_scale_f32_16x16x128_f8f6f4 v[164:167], v[36:43], v[180:187], v[164:167], v239, v238 op_sel_hi:[0,0,0]
	v_mfma_scale_f32_16x16x128_f8f6f4 v[160:163], v[44:51], v[188:195], v[160:163], v239, v238 op_sel_hi:[0,0,0]
	v_mfma_scale_f32_16x16x128_f8f6f4 v[156:159], v[20:27], v[188:195], v[156:159], v239, v238 op_sel_hi:[0,0,0]
	v_mfma_scale_f32_16x16x128_f8f6f4 v[152:155], v[28:35], v[188:195], v[152:155], v239, v238 op_sel_hi:[0,0,0]
	v_mfma_scale_f32_16x16x128_f8f6f4 v[148:151], v[36:43], v[188:195], v[148:151], v239, v238 op_sel_hi:[0,0,0]
	ds_read_b128 v[184:187], v220 offset:4096
	ds_read_b128 v[180:183], v221 offset:4096
	ds_read_b128 v[188:191], v221 offset:6144
	ds_read_b128 v[192:195], v220 offset:6144
	s_waitcnt lgkmcnt(2)
	v_mfma_scale_f32_16x16x128_f8f6f4 v[144:147], v[44:51], v[180:187], v[144:147], v239, v238 op_sel_hi:[0,0,0]
	v_mfma_scale_f32_16x16x128_f8f6f4 v[140:143], v[20:27], v[180:187], v[140:143], v239, v238 op_sel_hi:[0,0,0]
	v_mfma_scale_f32_16x16x128_f8f6f4 v[136:139], v[28:35], v[180:187], v[136:139], v239, v238 op_sel_hi:[0,0,0]
	v_mfma_scale_f32_16x16x128_f8f6f4 v[132:135], v[36:43], v[180:187], v[132:135], v239, v238 op_sel_hi:[0,0,0]
	s_waitcnt lgkmcnt(0)
	v_mfma_scale_f32_16x16x128_f8f6f4 v[128:131], v[44:51], v[188:195], v[128:131], v239, v238 op_sel_hi:[0,0,0]
	v_mfma_scale_f32_16x16x128_f8f6f4 v[124:127], v[20:27], v[188:195], v[124:127], v239, v238 op_sel_hi:[0,0,0]
	v_mfma_scale_f32_16x16x128_f8f6f4 v[120:123], v[28:35], v[188:195], v[120:123], v239, v238 op_sel_hi:[0,0,0]
	v_mfma_scale_f32_16x16x128_f8f6f4 v[116:119], v[36:43], v[188:195], v[116:119], v239, v238 op_sel_hi:[0,0,0]
	ds_read_b128 v[184:187], v220 offset:8192
	ds_read_b128 v[180:183], v221 offset:8192
	ds_read_b128 v[188:191], v221 offset:10240
	ds_read_b128 v[192:195], v220 offset:10240
	s_waitcnt lgkmcnt(0)
	v_mfma_scale_f32_16x16x128_f8f6f4 v[96:99], v[44:51], v[188:195], v[96:99], v239, v238 op_sel_hi:[0,0,0]
	v_mfma_scale_f32_16x16x128_f8f6f4 v[92:95], v[20:27], v[188:195], v[92:95], v239, v238 op_sel_hi:[0,0,0]
	v_mfma_scale_f32_16x16x128_f8f6f4 v[88:91], v[28:35], v[188:195], v[88:91], v239, v238 op_sel_hi:[0,0,0]
	v_mfma_scale_f32_16x16x128_f8f6f4 v[84:87], v[36:43], v[188:195], v[84:87], v239, v238 op_sel_hi:[0,0,0]
	v_mfma_scale_f32_16x16x128_f8f6f4 v[112:115], v[44:51], v[180:187], v[112:115], v239, v238 op_sel_hi:[0,0,0]
	v_mfma_scale_f32_16x16x128_f8f6f4 v[108:111], v[20:27], v[180:187], v[108:111], v239, v238 op_sel_hi:[0,0,0]
	v_mfma_scale_f32_16x16x128_f8f6f4 v[104:107], v[28:35], v[180:187], v[104:107], v239, v238 op_sel_hi:[0,0,0]
	v_mfma_scale_f32_16x16x128_f8f6f4 v[100:103], v[36:43], v[180:187], v[100:103], v239, v238 op_sel_hi:[0,0,0]
	ds_read_b128 v[180:183], v221 offset:12288
	ds_read_b128 v[184:187], v220 offset:12288
	ds_read_b128 v[224:227], v221 offset:14336
	ds_read_b128 v[228:231], v220 offset:14336
	s_waitcnt lgkmcnt(2)
	v_mfma_scale_f32_16x16x128_f8f6f4 v[80:83], v[44:51], v[180:187], v[80:83], v239, v238 op_sel_hi:[0,0,0]
	v_mfma_scale_f32_16x16x128_f8f6f4 v[76:79], v[20:27], v[180:187], v[76:79], v239, v238 op_sel_hi:[0,0,0]
	v_mfma_scale_f32_16x16x128_f8f6f4 v[72:75], v[28:35], v[180:187], v[72:75], v239, v238 op_sel_hi:[0,0,0]
	v_mfma_scale_f32_16x16x128_f8f6f4 v[68:71], v[36:43], v[180:187], v[68:71], v239, v238 op_sel_hi:[0,0,0]
	s_waitcnt lgkmcnt(0)
	v_mfma_scale_f32_16x16x128_f8f6f4 v[64:67], v[44:51], v[224:231], v[64:67], v239, v238 op_sel_hi:[0,0,0]
	v_mfma_scale_f32_16x16x128_f8f6f4 v[60:63], v[20:27], v[224:231], v[60:63], v239, v238 op_sel_hi:[0,0,0]
	v_mfma_scale_f32_16x16x128_f8f6f4 v[56:59], v[28:35], v[224:231], v[56:59], v239, v238 op_sel_hi:[0,0,0]
	v_mfma_scale_f32_16x16x128_f8f6f4 v[52:55], v[36:43], v[224:231], v[52:55], v239, v238 op_sel_hi:[0,0,0]
	s_add_u32 s8, s8, 0x80
	s_addc_u32 s9, s9, 0
	s_cmpk_lg_i32 s8, 0x380
	s_cbranch_scc1 .LBB0_944
; template <int MI, bool SWAP, bool F8 = false>
; __device__ __forceinline__ void gemm_core(const bf16_t* __restrict__ A, int lda, const bf16_t* __restrict__ B, int ldb,
;                                           int K, char* smem, f32x4 (&acc)[MI][4]) {
;     ...
;   for (int kt = 0; kt < nk; ++kt) {
;     __syncthreads();
; #pragma unroll
;     for (int i = 0; i < MI; ++i) *(u32x4*)(smem + woff + i * 4096) = ra[i];
; #pragma unroll
;     for (int i = 0; i < 4; ++i) *(u32x4*)(smem + 32768 + woff + i * 4096) = rb[i];
;     __syncthreads();
;     if (kt + 1 < nk) {
; #pragma unroll
;       for (int i = 0; i < MI; ++i) ra[i] = *(const u32x4*)(ap + (size_t)(32 * i) * lda + (kt + 1) * 64);
; #pragma unroll
;       for (int i = 0; i < 4; ++i) rb[i] = *(const u32x4*)(bp + (size_t)(32 * i) * ldb + (kt + 1) * 64);
;     }
;     if (F8) {
;       const int c0 = (g ^ (li & 7)) << 4, c1 = ((4 + g) ^ (li & 7)) << 4;
;       i32x8 wf8[4];
; #pragma unroll
;       for (int j = 0; j < 4; ++j) {
;         const char* rp = smem + wrow + ((j & 1) * 16 + (j >> 1) * 64) * 128;
;         const u32x4 lo = *(const u32x4*)(rp + c0), hi = *(const u32x4*)(rp + c1);
;         wf8[j] = (i32x8){(int)lo.x, (int)lo.y, (int)lo.z, (int)lo.w, (int)hi.x, (int)hi.y, (int)hi.z, (int)hi.w};
;       }
; #pragma unroll
;       for (int i = 0; i < MI; ++i) {
;         const char* rp = smem + xrow + i * 2048;
;         const u32x4 lo = *(const u32x4*)(rp + c0), hi = *(const u32x4*)(rp + c1);
;         const i32x8 xf8 = {(int)lo.x, (int)lo.y, (int)lo.z, (int)lo.w, (int)hi.x, (int)hi.y, (int)hi.z, (int)hi.w};
; #pragma unroll
;         for (int j = 0; j < 4; ++j)
;           acc[i][j] = __builtin_amdgcn_mfma_scale_f32_16x16x128_f8f6f4(wf8[j], xf8, acc[i][j], 0, 0, 0, 0x77777777, 0, 0x7f7f7f7f);
;       }
	s_barrier
	s_setprio 3
	s_mov_b32 m0, s62
	s_nop 0
	global_load_lds_dwordx4 v252, s[56:57]
	s_add_u32 m0, s62, 0x1000
	s_nop 0
	global_load_lds_dwordx4 v253, s[56:57]
	s_add_u32 s56, s56, 0x10000
	s_addc_u32 s57, s57, 0
	s_add_u32 m0, s62, 0x2000
	s_nop 0
	global_load_lds_dwordx4 v252, s[56:57]
	s_add_u32 m0, s62, 0x3000
	s_nop 0
	global_load_lds_dwordx4 v253, s[56:57]
	s_add_u32 s56, s56, 0x10000
	s_addc_u32 s57, s57, 0
	s_add_u32 m0, s62, 0x4000
	s_nop 0
	global_load_lds_dwordx4 v252, s[56:57]
	s_add_u32 m0, s62, 0x5000
	s_nop 0
	global_load_lds_dwordx4 v253, s[56:57]
	s_add_u32 s56, s56, 0x10000
	s_addc_u32 s57, s57, 0
	s_add_u32 m0, s62, 0x6000
	s_nop 0
	global_load_lds_dwordx4 v252, s[56:57]
	s_add_u32 m0, s62, 0x7000
	s_nop 0
	global_load_lds_dwordx4 v253, s[56:57]
	s_sub_u32 s56, s56, 0x30000
	s_subb_u32 s57, s57, 0
	s_add_u32 m0, s62, 0x8000
	s_nop 0
	global_load_lds_dwordx4 v252, s[58:59]
	s_add_u32 m0, s62, 0x9000
	s_nop 0
	global_load_lds_dwordx4 v253, s[58:59]
	s_add_u32 s58, s58, 0x10000
	s_addc_u32 s59, s59, 0
	s_add_u32 m0, s62, 0xa000
	s_nop 0
	global_load_lds_dwordx4 v252, s[58:59]
	s_add_u32 m0, s62, 0xb000
	s_nop 0
	global_load_lds_dwordx4 v253, s[58:59]
	s_sub_u32 s58, s58, 0x10000
	s_subb_u32 s59, s59, 0
	s_setprio 0
	s_waitcnt vmcnt(0)
	s_barrier
	v_bfe_u32 v12, v208, 4, 1
	v_mul_u32_u24_e32 v12, 24, v12
	v_mov_b32_e32 v13, 0
	ds_read_b128 v[20:23], v222 offset:32768
	ds_read_b128 v[24:27], v223 offset:32768
	ds_read_b128 v[28:31], v222 offset:34816
	ds_read_b128 v[32:35], v223 offset:34816
	ds_read_b128 v[36:39], v222 offset:40960
	ds_read_b128 v[40:43], v223 offset:40960
	ds_read_b128 v[44:47], v222 offset:43008
	ds_read_b128 v[48:51], v223 offset:43008
	ds_read_b128 v[180:183], v221
	ds_read_b128 v[184:187], v220
	s_waitcnt lgkmcnt(0)
	v_mfma_scale_f32_16x16x128_f8f6f4 v[176:179], v[20:27], v[180:187], v[176:179], v239, v238 op_sel_hi:[0,0,0]
	s_lshl_b64 s[6:7], s[6:7], 20
	s_add_u32 s6, s42, s6
	s_addc_u32 s7, s43, s7
	s_lshl_b32 s8, s19, 1
	s_add_u32 s6, s6, s8
	s_addc_u32 s7, s7, 0
	s_add_i32 s18, s18, s78
	v_mfma_scale_f32_16x16x128_f8f6f4 v[172:175], v[28:35], v[180:187], v[172:175], v239, v238 op_sel_hi:[0,0,0]
	s_add_i32 s15, s15, s71
	s_add_i32 s14, s14, s76
	s_cmpk_gt_i32 s18, 0x3ff
	v_mfma_scale_f32_16x16x128_f8f6f4 v[168:171], v[36:43], v[180:187], v[168:171], v239, v238 op_sel_hi:[0,0,0]
	v_mfma_scale_f32_16x16x128_f8f6f4 v[164:167], v[44:51], v[180:187], v[164:167], v239, v238 op_sel_hi:[0,0,0]
	ds_read_b128 v[180:183], v221 offset:2048
	ds_read_b128 v[184:187], v220 offset:2048
	s_waitcnt lgkmcnt(0)
	v_mfma_scale_f32_16x16x128_f8f6f4 v[160:163], v[20:27], v[180:187], v[160:163], v239, v238 op_sel_hi:[0,0,0]
	v_mfma_scale_f32_16x16x128_f8f6f4 v[156:159], v[28:35], v[180:187], v[156:159], v239, v238 op_sel_hi:[0,0,0]
	v_mfma_scale_f32_16x16x128_f8f6f4 v[152:155], v[36:43], v[180:187], v[152:155], v239, v238 op_sel_hi:[0,0,0]
	v_mfma_scale_f32_16x16x128_f8f6f4 v[148:151], v[44:51], v[180:187], v[148:151], v239, v238 op_sel_hi:[0,0,0]
	ds_read_b128 v[180:183], v221 offset:4096
	ds_read_b128 v[184:187], v220 offset:4096
	s_waitcnt lgkmcnt(0)
	v_mfma_scale_f32_16x16x128_f8f6f4 v[144:147], v[20:27], v[180:187], v[144:147], v239, v238 op_sel_hi:[0,0,0]
	v_mfma_scale_f32_16x16x128_f8f6f4 v[140:143], v[28:35], v[180:187], v[140:143], v239, v238 op_sel_hi:[0,0,0]
	v_mfma_scale_f32_16x16x128_f8f6f4 v[136:139], v[36:43], v[180:187], v[136:139], v239, v238 op_sel_hi:[0,0,0]
	v_mfma_scale_f32_16x16x128_f8f6f4 v[132:135], v[44:51], v[180:187], v[132:135], v239, v238 op_sel_hi:[0,0,0]
	ds_read_b128 v[180:183], v221 offset:6144
	ds_read_b128 v[184:187], v220 offset:6144
	s_waitcnt lgkmcnt(0)
	v_mfma_scale_f32_16x16x128_f8f6f4 v[128:131], v[20:27], v[180:187], v[128:131], v239, v238 op_sel_hi:[0,0,0]
	v_mfma_scale_f32_16x16x128_f8f6f4 v[124:127], v[28:35], v[180:187], v[124:127], v239, v238 op_sel_hi:[0,0,0]
	v_mfma_scale_f32_16x16x128_f8f6f4 v[120:123], v[36:43], v[180:187], v[120:123], v239, v238 op_sel_hi:[0,0,0]
	v_mfma_scale_f32_16x16x128_f8f6f4 v[116:119], v[44:51], v[180:187], v[116:119], v239, v238 op_sel_hi:[0,0,0]
	ds_read_b128 v[180:183], v221 offset:8192
	ds_read_b128 v[184:187], v220 offset:8192
	s_waitcnt lgkmcnt(0)
	v_mfma_scale_f32_16x16x128_f8f6f4 v[112:115], v[20:27], v[180:187], v[112:115], v239, v238 op_sel_hi:[0,0,0]
	v_mfma_scale_f32_16x16x128_f8f6f4 v[108:111], v[28:35], v[180:187], v[108:111], v239, v238 op_sel_hi:[0,0,0]
	v_mfma_scale_f32_16x16x128_f8f6f4 v[104:107], v[36:43], v[180:187], v[104:107], v239, v238 op_sel_hi:[0,0,0]
	v_mfma_scale_f32_16x16x128_f8f6f4 v[100:103], v[44:51], v[180:187], v[100:103], v239, v238 op_sel_hi:[0,0,0]
	ds_read_b128 v[180:183], v221 offset:10240
	ds_read_b128 v[184:187], v220 offset:10240
	s_waitcnt lgkmcnt(0)
	v_mfma_scale_f32_16x16x128_f8f6f4 v[96:99], v[20:27], v[180:187], v[96:99], v239, v238 op_sel_hi:[0,0,0]
	v_mfma_scale_f32_16x16x128_f8f6f4 v[92:95], v[28:35], v[180:187], v[92:95], v239, v238 op_sel_hi:[0,0,0]
	v_mfma_scale_f32_16x16x128_f8f6f4 v[88:91], v[36:43], v[180:187], v[88:91], v239, v238 op_sel_hi:[0,0,0]
	v_mfma_scale_f32_16x16x128_f8f6f4 v[84:87], v[44:51], v[180:187], v[84:87], v239, v238 op_sel_hi:[0,0,0]
	ds_read_b128 v[180:183], v221 offset:12288
	ds_read_b128 v[184:187], v220 offset:12288
	s_waitcnt lgkmcnt(0)
	v_mfma_scale_f32_16x16x128_f8f6f4 v[80:83], v[20:27], v[180:187], v[80:83], v239, v238 op_sel_hi:[0,0,0]
	v_mfma_scale_f32_16x16x128_f8f6f4 v[76:79], v[28:35], v[180:187], v[76:79], v239, v238 op_sel_hi:[0,0,0]
	v_mfma_scale_f32_16x16x128_f8f6f4 v[72:75], v[36:43], v[180:187], v[72:75], v239, v238 op_sel_hi:[0,0,0]
	v_mfma_scale_f32_16x16x128_f8f6f4 v[68:71], v[44:51], v[180:187], v[68:71], v239, v238 op_sel_hi:[0,0,0]
	ds_read_b128 v[180:183], v221 offset:14336
	ds_read_b128 v[184:187], v220 offset:14336
	s_waitcnt lgkmcnt(0)
; template <int MI, bool F8 = false>
; __device__ void gemm_tile_bf16(const bf16_t* A, int lda, const bf16_t* B, int ldb, int K, bf16_t* C, int ldc, char* smem) {
;   f32x4 acc[MI][4];
;   gemm_core<MI, false, F8>(A, lda, B, ldb, K, smem, acc);
;   EPI_COORDS
; #pragma unroll
;   for (int i = 0; i < MI; ++i)
; #pragma unroll
;     for (int j = 0; j < 4; ++j) {
;       u32x2 v;
;       v.x = pk_bf16(acc[i][j][0], acc[i][j][1]);
;       v.y = pk_bf16(acc[i][j][2], acc[i][j][3]);
;       *(u32x2*)(C + (size_t)MROW(i) * ldc + NCOL(j)) = v;
;     }
	v_mfma_scale_f32_16x16x128_f8f6f4 v[64:67], v[20:27], v[180:187], v[64:67], v239, v238 op_sel_hi:[0,0,0]
	v_mfma_scale_f32_16x16x128_f8f6f4 v[24:27], v[36:43], v[180:187], v[56:59], v239, v238 op_sel_hi:[0,0,0]
	v_mov_b32_e32 v36, v208
	s_nop 0
	v_lshrrev_b32_e32 v0, 1, v36
	v_and_b32_e32 v2, 0xffffff8f, v36
	v_and_b32_e32 v0, 32, v0
	v_lshrrev_b32_e32 v3, 2, v36
	v_and_or_b32 v0, v3, 12, v0
	v_ashrrev_i32_e32 v3, 31, v2
	v_mfma_scale_f32_16x16x128_f8f6f4 v[28:31], v[28:35], v[180:187], v[60:63], v239, v238 op_sel_hi:[0,0,0]
	v_lshlrev_b64 v[32:33], 12, v[2:3]
	v_lshl_add_u64 v[32:33], s[6:7], 0, v[32:33]
	v_lshlrev_b32_e32 v0, 1, v0
	v_cvt_pk_bf16_f32 v4, v176, v177
	v_cvt_pk_bf16_f32 v5, v178, v179
	v_lshl_add_u64 v[32:33], v[32:33], 0, v[0:1]
	v_cvt_pk_bf16_f32 v6, v172, v173
	v_cvt_pk_bf16_f32 v7, v174, v175
	s_nop 1
	v_permlane16_swap_b32_e32 v4, v6
	v_permlane16_swap_b32_e32 v5, v7
	v_lshl_add_u64 v[14:15], v[32:33], 0, v[12:13]
	global_store_dwordx4 v[14:15], v[4:7], off
	v_cvt_pk_bf16_f32 v8, v168, v169
	v_cvt_pk_bf16_f32 v9, v170, v171
	v_cvt_pk_bf16_f32 v10, v164, v165
	v_cvt_pk_bf16_f32 v11, v166, v167
	s_nop 1
	v_permlane16_swap_b32_e32 v8, v10
	v_permlane16_swap_b32_e32 v9, v11
	v_lshl_add_u64 v[14:15], v[32:33], 0, v[12:13]
	global_store_dwordx4 v[14:15], v[8:11], off offset:128
	v_or_b32_e32 v32, 16, v2
	v_ashrrev_i32_e32 v33, 31, v32
	v_lshlrev_b64 v[32:33], 12, v[32:33]
	v_lshl_add_u64 v[32:33], s[6:7], 0, v[32:33]
	v_cvt_pk_bf16_f32 v4, v160, v161
	v_cvt_pk_bf16_f32 v5, v162, v163
	v_lshl_add_u64 v[32:33], v[32:33], 0, v[0:1]
	v_cvt_pk_bf16_f32 v6, v156, v157
	v_cvt_pk_bf16_f32 v7, v158, v159
	s_nop 1
	v_permlane16_swap_b32_e32 v4, v6
	v_permlane16_swap_b32_e32 v5, v7
	v_lshl_add_u64 v[14:15], v[32:33], 0, v[12:13]
	global_store_dwordx4 v[14:15], v[4:7], off
	v_cvt_pk_bf16_f32 v8, v152, v153
	v_cvt_pk_bf16_f32 v9, v154, v155
	v_cvt_pk_bf16_f32 v10, v148, v149
	v_cvt_pk_bf16_f32 v11, v150, v151
	s_nop 1
	v_permlane16_swap_b32_e32 v8, v10
	v_permlane16_swap_b32_e32 v9, v11
	v_lshl_add_u64 v[14:15], v[32:33], 0, v[12:13]
	global_store_dwordx4 v[14:15], v[8:11], off offset:128
	v_or_b32_e32 v32, 32, v2
	v_ashrrev_i32_e32 v33, 31, v32
	v_lshlrev_b64 v[32:33], 12, v[32:33]
	v_lshl_add_u64 v[32:33], s[6:7], 0, v[32:33]
	v_cvt_pk_bf16_f32 v4, v144, v145
	v_cvt_pk_bf16_f32 v5, v146, v147
	v_lshl_add_u64 v[32:33], v[32:33], 0, v[0:1]
	v_cvt_pk_bf16_f32 v6, v140, v141
	v_cvt_pk_bf16_f32 v7, v142, v143
	s_nop 1
	v_permlane16_swap_b32_e32 v4, v6
	v_permlane16_swap_b32_e32 v5, v7
	v_lshl_add_u64 v[14:15], v[32:33], 0, v[12:13]
	global_store_dwordx4 v[14:15], v[4:7], off
	v_cvt_pk_bf16_f32 v8, v136, v137
	v_cvt_pk_bf16_f32 v9, v138, v139
	v_cvt_pk_bf16_f32 v10, v132, v133
	v_cvt_pk_bf16_f32 v11, v134, v135
	s_nop 1
	v_permlane16_swap_b32_e32 v8, v10
	v_permlane16_swap_b32_e32 v9, v11
	v_lshl_add_u64 v[14:15], v[32:33], 0, v[12:13]
	global_store_dwordx4 v[14:15], v[8:11], off offset:128
	v_or_b32_e32 v32, 48, v2
	v_ashrrev_i32_e32 v33, 31, v32
	v_lshlrev_b64 v[32:33], 12, v[32:33]
	v_lshl_add_u64 v[32:33], s[6:7], 0, v[32:33]
	v_cvt_pk_bf16_f32 v4, v128, v129
	v_cvt_pk_bf16_f32 v5, v130, v131
	v_lshl_add_u64 v[32:33], v[32:33], 0, v[0:1]
	v_cvt_pk_bf16_f32 v6, v124, v125
	v_cvt_pk_bf16_f32 v7, v126, v127
	s_nop 1
	v_permlane16_swap_b32_e32 v4, v6
	v_permlane16_swap_b32_e32 v5, v7
	v_lshl_add_u64 v[14:15], v[32:33], 0, v[12:13]
	global_store_dwordx4 v[14:15], v[4:7], off
	v_cvt_pk_bf16_f32 v8, v120, v121
	v_cvt_pk_bf16_f32 v9, v122, v123
	v_cvt_pk_bf16_f32 v10, v116, v117
	v_cvt_pk_bf16_f32 v11, v118, v119
	s_nop 1
	v_permlane16_swap_b32_e32 v8, v10
; template <int MI, bool F8 = false>
; __device__ void gemm_tile_bf16(const bf16_t* A, int lda, const bf16_t* B, int ldb, int K, bf16_t* C, int ldc, char* smem) {
;   f32x4 acc[MI][4];
;   gemm_core<MI, false, F8>(A, lda, B, ldb, K, smem, acc);
;   EPI_COORDS
; #pragma unroll
;   for (int i = 0; i < MI; ++i)
; #pragma unroll
;     for (int j = 0; j < 4; ++j) {
;       u32x2 v;
;       v.x = pk_bf16(acc[i][j][0], acc[i][j][1]);
;       v.y = pk_bf16(acc[i][j][2], acc[i][j][3]);
;       *(u32x2*)(C + (size_t)MROW(i) * ldc + NCOL(j)) = v;
;     }
	v_permlane16_swap_b32_e32 v9, v11
	v_lshl_add_u64 v[14:15], v[32:33], 0, v[12:13]
	global_store_dwordx4 v[14:15], v[8:11], off offset:128
	v_or_b32_e32 v32, 64, v2
	v_ashrrev_i32_e32 v33, 31, v32
	v_lshlrev_b64 v[32:33], 12, v[32:33]
	v_lshl_add_u64 v[32:33], s[6:7], 0, v[32:33]
	v_cvt_pk_bf16_f32 v4, v112, v113
	v_cvt_pk_bf16_f32 v5, v114, v115
	v_lshl_add_u64 v[32:33], v[32:33], 0, v[0:1]
	v_cvt_pk_bf16_f32 v6, v108, v109
	v_cvt_pk_bf16_f32 v7, v110, v111
	s_nop 1
	v_permlane16_swap_b32_e32 v4, v6
	v_permlane16_swap_b32_e32 v5, v7
	v_lshl_add_u64 v[14:15], v[32:33], 0, v[12:13]
	global_store_dwordx4 v[14:15], v[4:7], off
	v_cvt_pk_bf16_f32 v8, v104, v105
	v_cvt_pk_bf16_f32 v9, v106, v107
	v_cvt_pk_bf16_f32 v10, v100, v101
	v_cvt_pk_bf16_f32 v11, v102, v103
	s_nop 1
	v_permlane16_swap_b32_e32 v8, v10
	v_permlane16_swap_b32_e32 v9, v11
	v_lshl_add_u64 v[14:15], v[32:33], 0, v[12:13]
	global_store_dwordx4 v[14:15], v[8:11], off offset:128
	v_or_b32_e32 v32, 0x50, v2
	v_ashrrev_i32_e32 v33, 31, v32
	v_lshlrev_b64 v[32:33], 12, v[32:33]
	v_lshl_add_u64 v[32:33], s[6:7], 0, v[32:33]
	v_cvt_pk_bf16_f32 v4, v96, v97
	v_cvt_pk_bf16_f32 v5, v98, v99
	v_lshl_add_u64 v[32:33], v[32:33], 0, v[0:1]
	v_or_b32_e32 v2, 0x60, v2
	v_cvt_pk_bf16_f32 v6, v92, v93
	v_cvt_pk_bf16_f32 v7, v94, v95
	v_ashrrev_i32_e32 v3, 31, v2
	s_nop 1
	v_permlane16_swap_b32_e32 v4, v6
	v_permlane16_swap_b32_e32 v5, v7
	v_lshl_add_u64 v[14:15], v[32:33], 0, v[12:13]
	global_store_dwordx4 v[14:15], v[4:7], off
	v_cvt_pk_bf16_f32 v8, v88, v89
	v_cvt_pk_bf16_f32 v9, v90, v91
	v_lshlrev_b64 v[2:3], 12, v[2:3]
	v_cvt_pk_bf16_f32 v10, v84, v85
	v_cvt_pk_bf16_f32 v11, v86, v87
	v_lshl_add_u64 v[2:3], s[6:7], 0, v[2:3]
	v_mfma_scale_f32_16x16x128_f8f6f4 v[20:23], v[44:51], v[180:187], v[52:55], v239, v238 op_sel_hi:[0,0,0]
	s_nop 1
	v_permlane16_swap_b32_e32 v8, v10
	v_permlane16_swap_b32_e32 v9, v11
	v_lshl_add_u64 v[14:15], v[32:33], 0, v[12:13]
	global_store_dwordx4 v[14:15], v[8:11], off offset:128
	v_cvt_pk_bf16_f32 v4, v80, v81
	v_cvt_pk_bf16_f32 v5, v82, v83
	v_lshl_add_u64 v[2:3], v[2:3], 0, v[0:1]
	v_cvt_pk_bf16_f32 v6, v76, v77
	v_cvt_pk_bf16_f32 v7, v78, v79
	s_nop 1
	v_permlane16_swap_b32_e32 v4, v6
	v_permlane16_swap_b32_e32 v5, v7
	v_lshl_add_u64 v[14:15], v[2:3], 0, v[12:13]
	global_store_dwordx4 v[14:15], v[4:7], off
	v_cvt_pk_bf16_f32 v8, v72, v73
	v_cvt_pk_bf16_f32 v9, v74, v75
	v_cvt_pk_bf16_f32 v10, v68, v69
	v_cvt_pk_bf16_f32 v11, v70, v71
	s_nop 1
	v_permlane16_swap_b32_e32 v8, v10
	v_permlane16_swap_b32_e32 v9, v11
	v_lshl_add_u64 v[14:15], v[2:3], 0, v[12:13]
	global_store_dwordx4 v[14:15], v[8:11], off offset:128
	v_or_b32_e32 v2, 0x70, v36
	v_ashrrev_i32_e32 v3, 31, v2
	v_lshlrev_b64 v[2:3], 12, v[2:3]
	v_lshl_add_u64 v[2:3], s[6:7], 0, v[2:3]
	v_cvt_pk_bf16_f32 v32, v64, v65
	v_cvt_pk_bf16_f32 v33, v66, v67
	v_lshl_add_u64 v[2:3], v[2:3], 0, v[0:1]
	v_cvt_pk_bf16_f32 v28, v28, v29
	v_cvt_pk_bf16_f32 v29, v30, v31
	v_cvt_pk_bf16_f32 v24, v24, v25
	v_cvt_pk_bf16_f32 v25, v26, v27
	v_cvt_pk_bf16_f32 v20, v20, v21
	v_cvt_pk_bf16_f32 v21, v22, v23
	v_mov_b64_e32 v[4:5], v[32:33]
	v_mov_b64_e32 v[6:7], v[28:29]
	s_nop 1
	v_permlane16_swap_b32_e32 v4, v6
	v_permlane16_swap_b32_e32 v5, v7
	v_lshl_add_u64 v[14:15], v[2:3], 0, v[12:13]
	global_store_dwordx4 v[14:15], v[4:7], off
	v_mov_b64_e32 v[8:9], v[24:25]
	v_mov_b64_e32 v[10:11], v[20:21]
	s_nop 1
	v_permlane16_swap_b32_e32 v8, v10
	v_permlane16_swap_b32_e32 v9, v11
	v_lshl_add_u64 v[14:15], v[2:3], 0, v[12:13]
	global_store_dwordx4 v[14:15], v[8:11], off offset:128
	s_cbranch_scc0 .LBB0_943
